# epilogue scale-load hoist plus serpentine MFMA issue order inside each k-group of the GEMM loops (consecutive MFMAs share one operand)
# speedup vs baseline: 1.0028x; 1.0001x over previous
.LBB0_203:
	v_add_u32_e32 v162, s69, v147
	v_add_u32_e32 v178, s70, v147
	ds_read_b128 v[148:151], v162
	ds_read_b128 v[152:155], v162 offset:1024
	ds_read_b128 v[158:161], v162 offset:2048
	ds_read_b128 v[162:165], v162 offset:3072
	ds_read_b128 v[166:169], v178
	ds_read_b128 v[170:173], v178 offset:1024
	ds_read_b128 v[174:177], v178 offset:2048
	ds_read_b128 v[178:181], v178 offset:3072
	s_add_u32 s45, s50, 0xfff80080
	s_addc_u32 s47, s51, -1
	s_and_b64 s[52:53], s[52:53], exec
	s_cselect_b32 s55, s19, s47
	s_cselect_b32 s54, s18, s45
	s_cselect_b32 s53, s17, s74
	s_cselect_b32 s52, s16, s73
	v_lshl_add_u64 v[214:215], s[50:51], 0, v[138:139]
	s_add_i32 m0, s49, 0xc000
	ds_read_b128 v[182:185], v157
	ds_read_b128 v[186:189], v157 offset:1024
	ds_read_b128 v[190:193], v157 offset:2048
	ds_read_b128 v[194:197], v157 offset:3072
	ds_read_b128 v[198:201], v157 offset:4096
	ds_read_b128 v[202:205], v157 offset:5120
	ds_read_b128 v[206:209], v157 offset:6144
	ds_read_b128 v[210:213], v157 offset:7168
	global_load_lds_dwordx4 v[214:215], off
	v_lshl_add_u64 v[214:215], s[50:51], 0, v[140:141]
	s_add_i32 m0, s49, 0xe000
	s_nop 0
	global_load_lds_dwordx4 v[214:215], off
	s_waitcnt vmcnt(8)
	s_waitcnt lgkmcnt(0)
	s_barrier
	s_setprio 3
	s_waitcnt lgkmcnt(0)
	v_mfma_i32_16x16x64_i8 v[126:129], v[148:151], v[182:185], v[126:129]
	v_mfma_i32_16x16x64_i8 v[118:121], v[158:161], v[182:185], v[118:121]
	v_mfma_i32_16x16x64_i8 v[102:105], v[158:161], v[190:193], v[102:105]
	v_mfma_i32_16x16x64_i8 v[110:113], v[148:151], v[190:193], v[110:113]
	v_mfma_i32_16x16x64_i8 v[94:97], v[148:151], v[198:201], v[94:97]
	v_mfma_i32_16x16x64_i8 v[86:89], v[158:161], v[198:201], v[86:89]
	v_mfma_i32_16x16x64_i8 v[70:73], v[158:161], v[206:209], v[70:73]
	v_mfma_i32_16x16x64_i8 v[78:81], v[148:151], v[206:209], v[78:81]
	v_mfma_i32_16x16x64_i8 v[126:129], v[152:155], v[186:189], v[126:129]
	v_mfma_i32_16x16x64_i8 v[118:121], v[162:165], v[186:189], v[118:121]
	v_mfma_i32_16x16x64_i8 v[102:105], v[162:165], v[194:197], v[102:105]
	v_mfma_i32_16x16x64_i8 v[110:113], v[152:155], v[194:197], v[110:113]
	v_mfma_i32_16x16x64_i8 v[94:97], v[152:155], v[202:205], v[94:97]
	v_mfma_i32_16x16x64_i8 v[86:89], v[162:165], v[202:205], v[86:89]
	v_mfma_i32_16x16x64_i8 v[70:73], v[162:165], v[210:213], v[70:73]
	v_mfma_i32_16x16x64_i8 v[78:81], v[152:155], v[210:213], v[78:81]
	s_setprio 0
	s_setprio 3
	v_mfma_i32_16x16x64_i8 v[122:125], v[166:169], v[182:185], v[122:125]
	v_mfma_i32_16x16x64_i8 v[114:117], v[174:177], v[182:185], v[114:117]
	v_mfma_i32_16x16x64_i8 v[98:101], v[174:177], v[190:193], v[98:101]
	v_mfma_i32_16x16x64_i8 v[106:109], v[166:169], v[190:193], v[106:109]
	v_mfma_i32_16x16x64_i8 v[90:93], v[166:169], v[198:201], v[90:93]
	v_mfma_i32_16x16x64_i8 v[82:85], v[174:177], v[198:201], v[82:85]
	v_mfma_i32_16x16x64_i8 v[66:69], v[174:177], v[206:209], v[66:69]
	v_mfma_i32_16x16x64_i8 v[74:77], v[166:169], v[206:209], v[74:77]
	v_mfma_i32_16x16x64_i8 v[122:125], v[170:173], v[186:189], v[122:125]
	v_mfma_i32_16x16x64_i8 v[114:117], v[178:181], v[186:189], v[114:117]
	v_mfma_i32_16x16x64_i8 v[98:101], v[178:181], v[194:197], v[98:101]
	v_mfma_i32_16x16x64_i8 v[106:109], v[170:173], v[194:197], v[106:109]
	v_mfma_i32_16x16x64_i8 v[90:93], v[170:173], v[202:205], v[90:93]
	v_mfma_i32_16x16x64_i8 v[82:85], v[178:181], v[202:205], v[82:85]
	v_mfma_i32_16x16x64_i8 v[66:69], v[178:181], v[210:213], v[66:69]
	v_mfma_i32_16x16x64_i8 v[74:77], v[170:173], v[210:213], v[74:77]
	s_setprio 0
	s_barrier
	s_add_i32 s45, s69, s43
	v_lshl_add_u64 v[214:215], s[52:53], 0, v[130:131]
	s_mov_b32 m0, s45
	ds_read_b128 v[182:185], v157 offset:16384
	ds_read_b128 v[186:189], v157 offset:17408
	ds_read_b128 v[190:193], v157 offset:18432
	ds_read_b128 v[194:197], v157 offset:19456
	ds_read_b128 v[198:201], v157 offset:20480
	ds_read_b128 v[202:205], v157 offset:21504
	ds_read_b128 v[206:209], v157 offset:22528
	ds_read_b128 v[210:213], v157 offset:23552
	global_load_lds_dwordx4 v[214:215], off
	s_add_i32 m0, s45, 0x2000
	s_add_u32 s76, s52, 0x80000
	v_lshl_add_u64 v[214:215], s[52:53], 0, v[132:133]
	s_addc_u32 s77, s53, 0
	s_add_i32 s45, s70, s43
	global_load_lds_dwordx4 v[214:215], off
	v_lshl_add_u64 v[214:215], s[76:77], 0, v[130:131]
	s_mov_b32 m0, s45
	v_lshl_add_u64 v[216:217], s[54:55], 0, v[134:135]
	global_load_lds_dwordx4 v[214:215], off
	v_lshl_add_u64 v[214:215], s[76:77], 0, v[132:133]
	s_add_i32 m0, s45, 0x2000
	s_nop 0
	global_load_lds_dwordx4 v[214:215], off
	v_lshl_add_u64 v[214:215], s[54:55], 0, v[136:137]
	s_mov_b32 m0, s49
	s_nop 0
	global_load_lds_dwordx4 v[214:215], off
	s_mov_b32 m0, s58
	s_nop 0
	global_load_lds_dwordx4 v[216:217], off
	s_waitcnt vmcnt(8)
	s_waitcnt lgkmcnt(0)
	s_barrier
	s_setprio 3
	s_waitcnt lgkmcnt(0)
	v_mfma_i32_16x16x64_i8 v[62:65], v[148:151], v[182:185], v[62:65]
	v_mfma_i32_16x16x64_i8 v[54:57], v[158:161], v[182:185], v[54:57]
	v_mfma_i32_16x16x64_i8 v[38:41], v[158:161], v[190:193], v[38:41]
	v_mfma_i32_16x16x64_i8 v[46:49], v[148:151], v[190:193], v[46:49]
	v_mfma_i32_16x16x64_i8 v[30:33], v[148:151], v[198:201], v[30:33]
	v_mfma_i32_16x16x64_i8 v[22:25], v[158:161], v[198:201], v[22:25]
	v_mfma_i32_16x16x64_i8 v[6:9], v[158:161], v[206:209], v[6:9]
	v_mfma_i32_16x16x64_i8 v[14:17], v[148:151], v[206:209], v[14:17]
	v_mfma_i32_16x16x64_i8 v[62:65], v[152:155], v[186:189], v[62:65]
	v_mfma_i32_16x16x64_i8 v[54:57], v[162:165], v[186:189], v[54:57]
	v_mfma_i32_16x16x64_i8 v[38:41], v[162:165], v[194:197], v[38:41]
	v_mfma_i32_16x16x64_i8 v[46:49], v[152:155], v[194:197], v[46:49]
	v_mfma_i32_16x16x64_i8 v[30:33], v[152:155], v[202:205], v[30:33]
	v_mfma_i32_16x16x64_i8 v[22:25], v[162:165], v[202:205], v[22:25]
	v_mfma_i32_16x16x64_i8 v[6:9], v[162:165], v[210:213], v[6:9]
	v_mfma_i32_16x16x64_i8 v[14:17], v[152:155], v[210:213], v[14:17]
	s_setprio 0
	s_setprio 3
	v_mfma_i32_16x16x64_i8 v[58:61], v[166:169], v[182:185], v[58:61]
	v_mfma_i32_16x16x64_i8 v[50:53], v[174:177], v[182:185], v[50:53]
	v_mfma_i32_16x16x64_i8 v[34:37], v[174:177], v[190:193], v[34:37]
	v_mfma_i32_16x16x64_i8 v[42:45], v[166:169], v[190:193], v[42:45]
	v_mfma_i32_16x16x64_i8 v[26:29], v[166:169], v[198:201], v[26:29]
	v_mfma_i32_16x16x64_i8 v[18:21], v[174:177], v[198:201], v[18:21]
	v_mfma_i32_16x16x64_i8 v[2:5], v[174:177], v[206:209], v[2:5]
	v_mfma_i32_16x16x64_i8 v[10:13], v[166:169], v[206:209], v[10:13]
	v_mfma_i32_16x16x64_i8 v[58:61], v[170:173], v[186:189], v[58:61]
	v_mfma_i32_16x16x64_i8 v[50:53], v[178:181], v[186:189], v[50:53]
	v_mfma_i32_16x16x64_i8 v[34:37], v[178:181], v[194:197], v[34:37]
	v_mfma_i32_16x16x64_i8 v[42:45], v[170:173], v[194:197], v[42:45]
	v_mfma_i32_16x16x64_i8 v[26:29], v[170:173], v[202:205], v[26:29]
	v_mfma_i32_16x16x64_i8 v[18:21], v[178:181], v[202:205], v[18:21]
	v_mfma_i32_16x16x64_i8 v[2:5], v[178:181], v[210:213], v[2:5]
	v_mfma_i32_16x16x64_i8 v[10:13], v[170:173], v[210:213], v[10:13]
	s_setprio 0
	s_barrier
	s_add_i32 s45, 0, 0x18000
	s_add_i32 s47, 0, 0x1c000
	v_add_u32_e32 v162, s45, v147
	v_add_u32_e32 v178, s47, v147
	ds_read_b128 v[148:151], v162
	ds_read_b128 v[152:155], v162 offset:1024
	ds_read_b128 v[158:161], v162 offset:2048
	ds_read_b128 v[162:165], v162 offset:3072
	ds_read_b128 v[166:169], v178
	ds_read_b128 v[170:173], v178 offset:1024
	ds_read_b128 v[174:177], v178 offset:2048
	ds_read_b128 v[178:181], v178 offset:3072
	s_add_u32 s54, s54, 0x80000
	s_addc_u32 s55, s55, 0
	s_mov_b32 m0, s59
	v_lshl_add_u64 v[218:219], s[54:55], 0, v[136:137]
	ds_read_b128 v[182:185], v157 offset:32768
	ds_read_b128 v[186:189], v157 offset:33792
	ds_read_b128 v[190:193], v157 offset:34816
	ds_read_b128 v[194:197], v157 offset:35840
	ds_read_b128 v[198:201], v157 offset:36864
	ds_read_b128 v[202:205], v157 offset:37888
	ds_read_b128 v[206:209], v157 offset:38912
	ds_read_b128 v[210:213], v157 offset:39936
	global_load_lds_dwordx4 v[218:219], off
	v_lshl_add_u64 v[218:219], s[54:55], 0, v[134:135]
	s_mov_b32 m0, s60
	s_nop 0
	global_load_lds_dwordx4 v[218:219], off
	s_waitcnt vmcnt(8)
	s_waitcnt lgkmcnt(0)
	s_barrier
	s_setprio 3
	s_waitcnt lgkmcnt(0)
	v_mfma_i32_16x16x64_i8 v[126:129], v[148:151], v[182:185], v[126:129]
	v_mfma_i32_16x16x64_i8 v[118:121], v[158:161], v[182:185], v[118:121]
	v_mfma_i32_16x16x64_i8 v[102:105], v[158:161], v[190:193], v[102:105]
	v_mfma_i32_16x16x64_i8 v[110:113], v[148:151], v[190:193], v[110:113]
	v_mfma_i32_16x16x64_i8 v[94:97], v[148:151], v[198:201], v[94:97]
	v_mfma_i32_16x16x64_i8 v[86:89], v[158:161], v[198:201], v[86:89]
	v_mfma_i32_16x16x64_i8 v[70:73], v[158:161], v[206:209], v[70:73]
	v_mfma_i32_16x16x64_i8 v[78:81], v[148:151], v[206:209], v[78:81]
	v_mfma_i32_16x16x64_i8 v[126:129], v[152:155], v[186:189], v[126:129]
	v_mfma_i32_16x16x64_i8 v[118:121], v[162:165], v[186:189], v[118:121]
	v_mfma_i32_16x16x64_i8 v[102:105], v[162:165], v[194:197], v[102:105]
	v_mfma_i32_16x16x64_i8 v[110:113], v[152:155], v[194:197], v[110:113]
	v_mfma_i32_16x16x64_i8 v[94:97], v[152:155], v[202:205], v[94:97]
	v_mfma_i32_16x16x64_i8 v[86:89], v[162:165], v[202:205], v[86:89]
	v_mfma_i32_16x16x64_i8 v[70:73], v[162:165], v[210:213], v[70:73]
	v_mfma_i32_16x16x64_i8 v[78:81], v[152:155], v[210:213], v[78:81]
	s_setprio 0
	s_setprio 3
	v_mfma_i32_16x16x64_i8 v[122:125], v[166:169], v[182:185], v[122:125]
	v_mfma_i32_16x16x64_i8 v[114:117], v[174:177], v[182:185], v[114:117]
	v_mfma_i32_16x16x64_i8 v[98:101], v[174:177], v[190:193], v[98:101]
	v_mfma_i32_16x16x64_i8 v[106:109], v[166:169], v[190:193], v[106:109]
	v_mfma_i32_16x16x64_i8 v[90:93], v[166:169], v[198:201], v[90:93]
	v_mfma_i32_16x16x64_i8 v[82:85], v[174:177], v[198:201], v[82:85]
	v_mfma_i32_16x16x64_i8 v[66:69], v[174:177], v[206:209], v[66:69]
	v_mfma_i32_16x16x64_i8 v[74:77], v[166:169], v[206:209], v[74:77]
	v_mfma_i32_16x16x64_i8 v[122:125], v[170:173], v[186:189], v[122:125]
	v_mfma_i32_16x16x64_i8 v[114:117], v[178:181], v[186:189], v[114:117]
	v_mfma_i32_16x16x64_i8 v[98:101], v[178:181], v[194:197], v[98:101]
	v_mfma_i32_16x16x64_i8 v[106:109], v[170:173], v[194:197], v[106:109]
	v_mfma_i32_16x16x64_i8 v[90:93], v[170:173], v[202:205], v[90:93]
	v_mfma_i32_16x16x64_i8 v[82:85], v[178:181], v[202:205], v[82:85]
	v_mfma_i32_16x16x64_i8 v[66:69], v[178:181], v[210:213], v[66:69]
	v_mfma_i32_16x16x64_i8 v[74:77], v[170:173], v[210:213], v[74:77]
	s_setprio 0
	s_barrier
	s_add_u32 s54, s52, 0x4000
	s_addc_u32 s55, s53, 0
	s_add_i32 s45, s45, s43
	v_lshl_add_u64 v[218:219], s[54:55], 0, v[130:131]
	s_mov_b32 m0, s45
	ds_read_b128 v[182:185], v157 offset:49152
	ds_read_b128 v[186:189], v157 offset:50176
	ds_read_b128 v[190:193], v157 offset:51200
	ds_read_b128 v[194:197], v157 offset:52224
	ds_read_b128 v[198:201], v157 offset:53248
	ds_read_b128 v[202:205], v157 offset:54272
	ds_read_b128 v[206:209], v157 offset:55296
	ds_read_b128 v[210:213], v157 offset:56320
	global_load_lds_dwordx4 v[218:219], off
	s_add_i32 m0, s45, 0x2000
	s_add_u32 s52, s52, 0x84000
	v_lshl_add_u64 v[218:219], s[54:55], 0, v[132:133]
	s_addc_u32 s53, s53, 0
	s_add_i32 s45, s47, s43
	global_load_lds_dwordx4 v[218:219], off
	v_lshl_add_u64 v[218:219], s[52:53], 0, v[130:131]
	s_mov_b32 m0, s45
	v_lshl_add_u64 v[214:215], v[214:215], 0, s[38:39]
	global_load_lds_dwordx4 v[218:219], off
	v_lshl_add_u64 v[218:219], s[52:53], 0, v[132:133]
	s_add_i32 m0, s45, 0x2000
	s_nop 0
	global_load_lds_dwordx4 v[218:219], off
	s_mov_b32 m0, s64
	s_nop 0
	global_load_lds_dwordx4 v[214:215], off
	v_lshl_add_u64 v[214:215], v[216:217], 0, s[38:39]
	s_mov_b32 m0, s65
	s_nop 0
	global_load_lds_dwordx4 v[214:215], off
	s_waitcnt vmcnt(8)
	s_waitcnt lgkmcnt(0)
	s_barrier
	s_setprio 3
	s_waitcnt lgkmcnt(0)
	v_mfma_i32_16x16x64_i8 v[62:65], v[148:151], v[182:185], v[62:65]
	v_mfma_i32_16x16x64_i8 v[54:57], v[158:161], v[182:185], v[54:57]
	v_mfma_i32_16x16x64_i8 v[38:41], v[158:161], v[190:193], v[38:41]
	v_mfma_i32_16x16x64_i8 v[46:49], v[148:151], v[190:193], v[46:49]
	v_mfma_i32_16x16x64_i8 v[30:33], v[148:151], v[198:201], v[30:33]
	v_mfma_i32_16x16x64_i8 v[22:25], v[158:161], v[198:201], v[22:25]
	v_mfma_i32_16x16x64_i8 v[6:9], v[158:161], v[206:209], v[6:9]
	v_mfma_i32_16x16x64_i8 v[14:17], v[148:151], v[206:209], v[14:17]
	v_mfma_i32_16x16x64_i8 v[62:65], v[152:155], v[186:189], v[62:65]
	v_mfma_i32_16x16x64_i8 v[54:57], v[162:165], v[186:189], v[54:57]
	v_mfma_i32_16x16x64_i8 v[38:41], v[162:165], v[194:197], v[38:41]
	v_mfma_i32_16x16x64_i8 v[46:49], v[152:155], v[194:197], v[46:49]
	v_mfma_i32_16x16x64_i8 v[30:33], v[152:155], v[202:205], v[30:33]
	v_mfma_i32_16x16x64_i8 v[22:25], v[162:165], v[202:205], v[22:25]
	v_mfma_i32_16x16x64_i8 v[6:9], v[162:165], v[210:213], v[6:9]
	v_mfma_i32_16x16x64_i8 v[14:17], v[152:155], v[210:213], v[14:17]
	s_setprio 0
	s_setprio 3
	v_mfma_i32_16x16x64_i8 v[58:61], v[166:169], v[182:185], v[58:61]
	v_mfma_i32_16x16x64_i8 v[50:53], v[174:177], v[182:185], v[50:53]
	v_mfma_i32_16x16x64_i8 v[34:37], v[174:177], v[190:193], v[34:37]
	v_mfma_i32_16x16x64_i8 v[42:45], v[166:169], v[190:193], v[42:45]
	v_mfma_i32_16x16x64_i8 v[26:29], v[166:169], v[198:201], v[26:29]
	v_mfma_i32_16x16x64_i8 v[18:21], v[174:177], v[198:201], v[18:21]
	v_mfma_i32_16x16x64_i8 v[2:5], v[174:177], v[206:209], v[2:5]
	v_mfma_i32_16x16x64_i8 v[10:13], v[166:169], v[206:209], v[10:13]
	v_mfma_i32_16x16x64_i8 v[58:61], v[170:173], v[186:189], v[58:61]
	v_mfma_i32_16x16x64_i8 v[50:53], v[178:181], v[186:189], v[50:53]
	v_mfma_i32_16x16x64_i8 v[34:37], v[178:181], v[194:197], v[34:37]
	v_mfma_i32_16x16x64_i8 v[42:45], v[170:173], v[194:197], v[42:45]
	v_mfma_i32_16x16x64_i8 v[26:29], v[170:173], v[202:205], v[26:29]
	v_mfma_i32_16x16x64_i8 v[18:21], v[178:181], v[202:205], v[18:21]
	v_mfma_i32_16x16x64_i8 v[2:5], v[178:181], v[210:213], v[2:5]
	v_mfma_i32_16x16x64_i8 v[10:13], v[170:173], v[210:213], v[10:13]
	s_setprio 0
	s_barrier
	s_add_i32 s75, s75, 2
	s_add_u32 s73, s73, 0x8000
	s_addc_u32 s74, s74, 0
	s_add_u32 s50, s50, 0x100
	s_addc_u32 s51, s51, 0
	s_cmp_gt_u32 s75, 29
	s_cbranch_scc1 .LBB0_209

.LBB0_409:
	ds_read_b128 v[148:151], v157
	ds_read_b128 v[152:155], v157 offset:1024
	ds_read_b128 v[160:163], v157 offset:2048
	ds_read_b128 v[164:167], v157 offset:3072
	ds_read_b128 v[168:171], v158
	ds_read_b128 v[172:175], v158 offset:1024
	ds_read_b128 v[176:179], v158 offset:2048
	ds_read_b128 v[180:183], v158 offset:3072
	s_add_u32 s48, s0, 0x100
	s_addc_u32 s49, s1, 0
	s_cmpk_eq_i32 s77, 0x52
	s_cselect_b32 s53, s7, s49
	s_cselect_b32 s52, s6, s48
	s_cselect_b32 s51, s47, s76
	s_cselect_b32 s50, s46, s75
	v_lshl_add_u64 v[216:217], s[0:1], 0, v[138:139]
	s_add_i32 m0, s55, 0xc000
	ds_read_b128 v[184:187], v159
	ds_read_b128 v[188:191], v159 offset:1024
	ds_read_b128 v[192:195], v159 offset:2048
	ds_read_b128 v[196:199], v159 offset:3072
	ds_read_b128 v[200:203], v159 offset:4096
	ds_read_b128 v[204:207], v159 offset:5120
	ds_read_b128 v[208:211], v159 offset:6144
	ds_read_b128 v[212:215], v159 offset:7168
	global_load_lds_dwordx4 v[216:217], off
	v_lshl_add_u64 v[216:217], s[0:1], 0, v[140:141]
	s_add_i32 m0, s55, 0xe000
	s_nop 0
	global_load_lds_dwordx4 v[216:217], off
	s_waitcnt vmcnt(8)
	s_waitcnt lgkmcnt(0)
	s_barrier
	s_setprio 3
	s_waitcnt lgkmcnt(0)
	v_mfma_i32_16x16x64_i8 v[126:129], v[148:151], v[184:187], v[126:129]
	v_mfma_i32_16x16x64_i8 v[122:125], v[160:163], v[184:187], v[122:125]
	v_mfma_i32_16x16x64_i8 v[114:117], v[160:163], v[192:195], v[114:117]
	v_mfma_i32_16x16x64_i8 v[118:121], v[148:151], v[192:195], v[118:121]
	v_mfma_i32_16x16x64_i8 v[110:113], v[148:151], v[200:203], v[110:113]
	v_mfma_i32_16x16x64_i8 v[106:109], v[160:163], v[200:203], v[106:109]
	v_mfma_i32_16x16x64_i8 v[98:101], v[160:163], v[208:211], v[98:101]
	v_mfma_i32_16x16x64_i8 v[102:105], v[148:151], v[208:211], v[102:105]
	v_mfma_i32_16x16x64_i8 v[126:129], v[152:155], v[188:191], v[126:129]
	v_mfma_i32_16x16x64_i8 v[122:125], v[164:167], v[188:191], v[122:125]
	v_mfma_i32_16x16x64_i8 v[114:117], v[164:167], v[196:199], v[114:117]
	v_mfma_i32_16x16x64_i8 v[118:121], v[152:155], v[196:199], v[118:121]
	v_mfma_i32_16x16x64_i8 v[110:113], v[152:155], v[204:207], v[110:113]
	v_mfma_i32_16x16x64_i8 v[106:109], v[164:167], v[204:207], v[106:109]
	v_mfma_i32_16x16x64_i8 v[98:101], v[164:167], v[212:215], v[98:101]
	v_mfma_i32_16x16x64_i8 v[102:105], v[152:155], v[212:215], v[102:105]
	s_setprio 0
	s_setprio 3
	v_mfma_i32_16x16x64_i8 v[62:65], v[168:171], v[184:187], v[62:65]
	v_mfma_i32_16x16x64_i8 v[58:61], v[176:179], v[184:187], v[58:61]
	v_mfma_i32_16x16x64_i8 v[50:53], v[176:179], v[192:195], v[50:53]
	v_mfma_i32_16x16x64_i8 v[54:57], v[168:171], v[192:195], v[54:57]
	v_mfma_i32_16x16x64_i8 v[46:49], v[168:171], v[200:203], v[46:49]
	v_mfma_i32_16x16x64_i8 v[42:45], v[176:179], v[200:203], v[42:45]
	v_mfma_i32_16x16x64_i8 v[34:37], v[176:179], v[208:211], v[34:37]
	v_mfma_i32_16x16x64_i8 v[38:41], v[168:171], v[208:211], v[38:41]
	v_mfma_i32_16x16x64_i8 v[62:65], v[172:175], v[188:191], v[62:65]
	v_mfma_i32_16x16x64_i8 v[58:61], v[180:183], v[188:191], v[58:61]
	v_mfma_i32_16x16x64_i8 v[50:53], v[180:183], v[196:199], v[50:53]
	v_mfma_i32_16x16x64_i8 v[54:57], v[172:175], v[196:199], v[54:57]
	v_mfma_i32_16x16x64_i8 v[46:49], v[172:175], v[204:207], v[46:49]
	v_mfma_i32_16x16x64_i8 v[42:45], v[180:183], v[204:207], v[42:45]
	v_mfma_i32_16x16x64_i8 v[34:37], v[180:183], v[212:215], v[34:37]
	v_mfma_i32_16x16x64_i8 v[38:41], v[172:175], v[212:215], v[38:41]
	s_setprio 0
	s_barrier
	s_add_i32 s0, s63, s54
	v_lshl_add_u64 v[216:217], s[50:51], 0, v[130:131]
	s_mov_b32 m0, s0
	ds_read_b128 v[184:187], v159 offset:16384
	ds_read_b128 v[188:191], v159 offset:17408
	ds_read_b128 v[192:195], v159 offset:18432
	ds_read_b128 v[196:199], v159 offset:19456
	ds_read_b128 v[200:203], v159 offset:20480
	ds_read_b128 v[204:207], v159 offset:21504
	ds_read_b128 v[208:211], v159 offset:22528
	ds_read_b128 v[212:215], v159 offset:23552
	global_load_lds_dwordx4 v[216:217], off
	s_add_i32 m0, s0, 0x2000
	s_add_u32 s0, s50, 0x158000
	v_lshl_add_u64 v[216:217], s[50:51], 0, v[134:135]
	s_addc_u32 s1, s51, 0
	s_add_i32 s78, s64, s54
	global_load_lds_dwordx4 v[216:217], off
	v_lshl_add_u64 v[216:217], s[0:1], 0, v[130:131]
	s_mov_b32 m0, s78
	v_lshl_add_u64 v[218:219], s[52:53], 0, v[136:137]
	global_load_lds_dwordx4 v[216:217], off
	v_lshl_add_u64 v[216:217], s[0:1], 0, v[134:135]
	s_add_i32 m0, s78, 0x2000
	s_nop 0
	global_load_lds_dwordx4 v[216:217], off
	v_lshl_add_u64 v[216:217], s[52:53], 0, v[132:133]
	s_mov_b32 m0, s55
	s_nop 0
	global_load_lds_dwordx4 v[216:217], off
	s_mov_b32 m0, s56
	s_nop 0
	global_load_lds_dwordx4 v[218:219], off
	s_waitcnt vmcnt(8)
	s_waitcnt lgkmcnt(0)
	s_barrier
	s_setprio 3
	s_waitcnt lgkmcnt(0)
	v_mfma_i32_16x16x64_i8 v[94:97], v[148:151], v[184:187], v[94:97]
	v_mfma_i32_16x16x64_i8 v[90:93], v[160:163], v[184:187], v[90:93]
	v_mfma_i32_16x16x64_i8 v[82:85], v[160:163], v[192:195], v[82:85]
	v_mfma_i32_16x16x64_i8 v[86:89], v[148:151], v[192:195], v[86:89]
	v_mfma_i32_16x16x64_i8 v[78:81], v[148:151], v[200:203], v[78:81]
	v_mfma_i32_16x16x64_i8 v[74:77], v[160:163], v[200:203], v[74:77]
	v_mfma_i32_16x16x64_i8 v[66:69], v[160:163], v[208:211], v[66:69]
	v_mfma_i32_16x16x64_i8 v[70:73], v[148:151], v[208:211], v[70:73]
	v_mfma_i32_16x16x64_i8 v[94:97], v[152:155], v[188:191], v[94:97]
	v_mfma_i32_16x16x64_i8 v[90:93], v[164:167], v[188:191], v[90:93]
	v_mfma_i32_16x16x64_i8 v[82:85], v[164:167], v[196:199], v[82:85]
	v_mfma_i32_16x16x64_i8 v[86:89], v[152:155], v[196:199], v[86:89]
	v_mfma_i32_16x16x64_i8 v[78:81], v[152:155], v[204:207], v[78:81]
	v_mfma_i32_16x16x64_i8 v[74:77], v[164:167], v[204:207], v[74:77]
	v_mfma_i32_16x16x64_i8 v[66:69], v[164:167], v[212:215], v[66:69]
	v_mfma_i32_16x16x64_i8 v[70:73], v[152:155], v[212:215], v[70:73]
	s_setprio 0
	s_setprio 3
	v_mfma_i32_16x16x64_i8 v[30:33], v[168:171], v[184:187], v[30:33]
	v_mfma_i32_16x16x64_i8 v[26:29], v[176:179], v[184:187], v[26:29]
	v_mfma_i32_16x16x64_i8 v[18:21], v[176:179], v[192:195], v[18:21]
	v_mfma_i32_16x16x64_i8 v[22:25], v[168:171], v[192:195], v[22:25]
	v_mfma_i32_16x16x64_i8 v[14:17], v[168:171], v[200:203], v[14:17]
	v_mfma_i32_16x16x64_i8 v[10:13], v[176:179], v[200:203], v[10:13]
	v_mfma_i32_16x16x64_i8 v[2:5], v[176:179], v[208:211], v[2:5]
	v_mfma_i32_16x16x64_i8 v[6:9], v[168:171], v[208:211], v[6:9]
	v_mfma_i32_16x16x64_i8 v[30:33], v[172:175], v[188:191], v[30:33]
	v_mfma_i32_16x16x64_i8 v[26:29], v[180:183], v[188:191], v[26:29]
	v_mfma_i32_16x16x64_i8 v[18:21], v[180:183], v[196:199], v[18:21]
	v_mfma_i32_16x16x64_i8 v[22:25], v[172:175], v[196:199], v[22:25]
	v_mfma_i32_16x16x64_i8 v[14:17], v[172:175], v[204:207], v[14:17]
	v_mfma_i32_16x16x64_i8 v[10:13], v[180:183], v[204:207], v[10:13]
	v_mfma_i32_16x16x64_i8 v[2:5], v[180:183], v[212:215], v[2:5]
	v_mfma_i32_16x16x64_i8 v[6:9], v[172:175], v[212:215], v[6:9]
	s_setprio 0
	s_barrier
	s_add_i32 s78, 0, 0x18000
	s_add_i32 s79, 0, 0x1c000
	v_add_u32_e32 v164, s78, v147
	v_add_u32_e32 v180, s79, v147
	ds_read_b128 v[148:151], v164
	ds_read_b128 v[152:155], v164 offset:1024
	ds_read_b128 v[160:163], v164 offset:2048
	ds_read_b128 v[164:167], v164 offset:3072
	ds_read_b128 v[168:171], v180
	ds_read_b128 v[172:175], v180 offset:1024
	ds_read_b128 v[176:179], v180 offset:2048
	ds_read_b128 v[180:183], v180 offset:3072
	s_add_u32 s0, s52, 0x158000
	s_addc_u32 s1, s53, 0
	s_mov_b32 m0, s57
	v_lshl_add_u64 v[220:221], s[0:1], 0, v[132:133]
	ds_read_b128 v[184:187], v159 offset:32768
	ds_read_b128 v[188:191], v159 offset:33792
	ds_read_b128 v[192:195], v159 offset:34816
	ds_read_b128 v[196:199], v159 offset:35840
	ds_read_b128 v[200:203], v159 offset:36864
	ds_read_b128 v[204:207], v159 offset:37888
	ds_read_b128 v[208:211], v159 offset:38912
	ds_read_b128 v[212:215], v159 offset:39936
	global_load_lds_dwordx4 v[220:221], off
	v_lshl_add_u64 v[220:221], s[0:1], 0, v[136:137]
	s_mov_b32 m0, s58
	s_nop 0
	global_load_lds_dwordx4 v[220:221], off
	s_waitcnt vmcnt(8)
	s_waitcnt lgkmcnt(0)
	s_barrier
	s_setprio 3
	s_waitcnt lgkmcnt(0)
	v_mfma_i32_16x16x64_i8 v[126:129], v[148:151], v[184:187], v[126:129]
	v_mfma_i32_16x16x64_i8 v[122:125], v[160:163], v[184:187], v[122:125]
	v_mfma_i32_16x16x64_i8 v[114:117], v[160:163], v[192:195], v[114:117]
	v_mfma_i32_16x16x64_i8 v[118:121], v[148:151], v[192:195], v[118:121]
	v_mfma_i32_16x16x64_i8 v[110:113], v[148:151], v[200:203], v[110:113]
	v_mfma_i32_16x16x64_i8 v[106:109], v[160:163], v[200:203], v[106:109]
	v_mfma_i32_16x16x64_i8 v[98:101], v[160:163], v[208:211], v[98:101]
	v_mfma_i32_16x16x64_i8 v[102:105], v[148:151], v[208:211], v[102:105]
	v_mfma_i32_16x16x64_i8 v[126:129], v[152:155], v[188:191], v[126:129]
	v_mfma_i32_16x16x64_i8 v[122:125], v[164:167], v[188:191], v[122:125]
	v_mfma_i32_16x16x64_i8 v[114:117], v[164:167], v[196:199], v[114:117]
	v_mfma_i32_16x16x64_i8 v[118:121], v[152:155], v[196:199], v[118:121]
	v_mfma_i32_16x16x64_i8 v[110:113], v[152:155], v[204:207], v[110:113]
	v_mfma_i32_16x16x64_i8 v[106:109], v[164:167], v[204:207], v[106:109]
	v_mfma_i32_16x16x64_i8 v[98:101], v[164:167], v[212:215], v[98:101]
	v_mfma_i32_16x16x64_i8 v[102:105], v[152:155], v[212:215], v[102:105]
	s_setprio 0
	s_setprio 3
	v_mfma_i32_16x16x64_i8 v[62:65], v[168:171], v[184:187], v[62:65]
	v_mfma_i32_16x16x64_i8 v[58:61], v[176:179], v[184:187], v[58:61]
	v_mfma_i32_16x16x64_i8 v[50:53], v[176:179], v[192:195], v[50:53]
	v_mfma_i32_16x16x64_i8 v[54:57], v[168:171], v[192:195], v[54:57]
	v_mfma_i32_16x16x64_i8 v[46:49], v[168:171], v[200:203], v[46:49]
	v_mfma_i32_16x16x64_i8 v[42:45], v[176:179], v[200:203], v[42:45]
	v_mfma_i32_16x16x64_i8 v[34:37], v[176:179], v[208:211], v[34:37]
	v_mfma_i32_16x16x64_i8 v[38:41], v[168:171], v[208:211], v[38:41]
	v_mfma_i32_16x16x64_i8 v[62:65], v[172:175], v[188:191], v[62:65]
	v_mfma_i32_16x16x64_i8 v[58:61], v[180:183], v[188:191], v[58:61]
	v_mfma_i32_16x16x64_i8 v[50:53], v[180:183], v[196:199], v[50:53]
	v_mfma_i32_16x16x64_i8 v[54:57], v[172:175], v[196:199], v[54:57]
	v_mfma_i32_16x16x64_i8 v[46:49], v[172:175], v[204:207], v[46:49]
	v_mfma_i32_16x16x64_i8 v[42:45], v[180:183], v[204:207], v[42:45]
	v_mfma_i32_16x16x64_i8 v[34:37], v[180:183], v[212:215], v[34:37]
	v_mfma_i32_16x16x64_i8 v[38:41], v[172:175], v[212:215], v[38:41]
	s_setprio 0
	s_barrier
	s_add_u32 s0, s50, 0x4000
	s_addc_u32 s1, s51, 0
	s_add_i32 s52, s78, s54
	v_lshl_add_u64 v[220:221], s[0:1], 0, v[130:131]
	s_mov_b32 m0, s52
	ds_read_b128 v[184:187], v159 offset:49152
	ds_read_b128 v[188:191], v159 offset:50176
	ds_read_b128 v[192:195], v159 offset:51200
	ds_read_b128 v[196:199], v159 offset:52224
	ds_read_b128 v[200:203], v159 offset:53248
	ds_read_b128 v[204:207], v159 offset:54272
	ds_read_b128 v[208:211], v159 offset:55296
	ds_read_b128 v[212:215], v159 offset:56320
	global_load_lds_dwordx4 v[220:221], off
	s_add_i32 m0, s52, 0x2000
	v_lshl_add_u64 v[220:221], s[0:1], 0, v[134:135]
	s_add_u32 s0, s50, 0x15c000
	s_addc_u32 s1, s51, 0
	s_add_i32 s50, s79, s54
	global_load_lds_dwordx4 v[220:221], off
	v_lshl_add_u64 v[220:221], s[0:1], 0, v[130:131]
	s_mov_b32 m0, s50
	v_lshl_add_u64 v[216:217], v[216:217], 0, s[18:19]
	global_load_lds_dwordx4 v[220:221], off
	v_lshl_add_u64 v[220:221], s[0:1], 0, v[134:135]
	s_add_i32 m0, s50, 0x2000
	s_nop 0
	global_load_lds_dwordx4 v[220:221], off
	s_mov_b32 m0, s60
	s_nop 0
	global_load_lds_dwordx4 v[216:217], off
	v_lshl_add_u64 v[216:217], v[218:219], 0, s[18:19]
	s_mov_b32 m0, s61
	s_nop 0
	global_load_lds_dwordx4 v[216:217], off
	s_waitcnt vmcnt(8)
	s_waitcnt lgkmcnt(0)
	s_barrier
	s_setprio 3
	s_waitcnt lgkmcnt(0)
	v_mfma_i32_16x16x64_i8 v[94:97], v[148:151], v[184:187], v[94:97]
	v_mfma_i32_16x16x64_i8 v[90:93], v[160:163], v[184:187], v[90:93]
	v_mfma_i32_16x16x64_i8 v[82:85], v[160:163], v[192:195], v[82:85]
	v_mfma_i32_16x16x64_i8 v[86:89], v[148:151], v[192:195], v[86:89]
	v_mfma_i32_16x16x64_i8 v[78:81], v[148:151], v[200:203], v[78:81]
	v_mfma_i32_16x16x64_i8 v[74:77], v[160:163], v[200:203], v[74:77]
	v_mfma_i32_16x16x64_i8 v[66:69], v[160:163], v[208:211], v[66:69]
	v_mfma_i32_16x16x64_i8 v[70:73], v[148:151], v[208:211], v[70:73]
	v_mfma_i32_16x16x64_i8 v[94:97], v[152:155], v[188:191], v[94:97]
	v_mfma_i32_16x16x64_i8 v[90:93], v[164:167], v[188:191], v[90:93]
	v_mfma_i32_16x16x64_i8 v[82:85], v[164:167], v[196:199], v[82:85]
	v_mfma_i32_16x16x64_i8 v[86:89], v[152:155], v[196:199], v[86:89]
	v_mfma_i32_16x16x64_i8 v[78:81], v[152:155], v[204:207], v[78:81]
	v_mfma_i32_16x16x64_i8 v[74:77], v[164:167], v[204:207], v[74:77]
	v_mfma_i32_16x16x64_i8 v[66:69], v[164:167], v[212:215], v[66:69]
	v_mfma_i32_16x16x64_i8 v[70:73], v[152:155], v[212:215], v[70:73]
	s_setprio 0
	s_setprio 3
	v_mfma_i32_16x16x64_i8 v[30:33], v[168:171], v[184:187], v[30:33]
	v_mfma_i32_16x16x64_i8 v[26:29], v[176:179], v[184:187], v[26:29]
	v_mfma_i32_16x16x64_i8 v[18:21], v[176:179], v[192:195], v[18:21]
	v_mfma_i32_16x16x64_i8 v[22:25], v[168:171], v[192:195], v[22:25]
	v_mfma_i32_16x16x64_i8 v[14:17], v[168:171], v[200:203], v[14:17]
	v_mfma_i32_16x16x64_i8 v[10:13], v[176:179], v[200:203], v[10:13]
	v_mfma_i32_16x16x64_i8 v[2:5], v[176:179], v[208:211], v[2:5]
	v_mfma_i32_16x16x64_i8 v[6:9], v[168:171], v[208:211], v[6:9]
	v_mfma_i32_16x16x64_i8 v[30:33], v[172:175], v[188:191], v[30:33]
	v_mfma_i32_16x16x64_i8 v[26:29], v[180:183], v[188:191], v[26:29]
	v_mfma_i32_16x16x64_i8 v[18:21], v[180:183], v[196:199], v[18:21]
	v_mfma_i32_16x16x64_i8 v[22:25], v[172:175], v[196:199], v[22:25]
	v_mfma_i32_16x16x64_i8 v[14:17], v[172:175], v[204:207], v[14:17]
	v_mfma_i32_16x16x64_i8 v[10:13], v[180:183], v[204:207], v[10:13]
	v_mfma_i32_16x16x64_i8 v[2:5], v[180:183], v[212:215], v[2:5]
	v_mfma_i32_16x16x64_i8 v[6:9], v[172:175], v[212:215], v[6:9]
	s_setprio 0
	s_barrier
	s_add_i32 s77, s77, 2
	s_add_u32 s75, s75, 0x8000
	s_addc_u32 s76, s76, 0
	s_cmpk_gt_u32 s77, 0x53
	s_mov_b64 s[0:1], s[48:49]
	s_cbranch_scc0 .LBB0_409
	s_and_b64 vcc, exec, s[20:21]
	s_cbranch_vccz .LBB0_412
	s_barrier

.LBB0_558:
	ds_read_b128 v[148:151], v163
	ds_read_b128 v[152:155], v163 offset:1024
	ds_read_b128 v[156:159], v163 offset:2048
	ds_read_b128 v[166:169], v163 offset:3072
	ds_read_b128 v[170:173], v164
	ds_read_b128 v[174:177], v164 offset:1024
	ds_read_b128 v[178:181], v164 offset:2048
	ds_read_b128 v[182:185], v164 offset:3072
	s_add_u32 s48, s0, 0x100
	s_addc_u32 s49, s1, 0
	s_cmp_eq_u32 s67, 28
	s_cselect_b32 s53, s7, s49
	s_cselect_b32 s52, s6, s48
	s_cselect_b32 s51, s45, s43
	s_cselect_b32 s50, s44, s41
	v_lshl_add_u64 v[160:161], s[0:1], 0, v[138:139]
	s_add_i32 m0, s47, 0xc000
	ds_read_b128 v[186:189], v165
	ds_read_b128 v[190:193], v165 offset:1024
	ds_read_b128 v[194:197], v165 offset:2048
	ds_read_b128 v[198:201], v165 offset:3072
	ds_read_b128 v[202:205], v165 offset:4096
	ds_read_b128 v[206:209], v165 offset:5120
	ds_read_b128 v[210:213], v165 offset:6144
	ds_read_b128 v[214:217], v165 offset:7168
	global_load_lds_dwordx4 v[160:161], off
	v_lshl_add_u64 v[160:161], s[0:1], 0, v[140:141]
	s_add_i32 m0, s47, 0xe000
	s_nop 0
	global_load_lds_dwordx4 v[160:161], off
	s_waitcnt vmcnt(8)
	s_waitcnt lgkmcnt(0)
	s_barrier
	s_setprio 3
	s_waitcnt lgkmcnt(0)
	v_mfma_i32_16x16x64_i8 v[126:129], v[148:151], v[186:189], v[126:129]
	v_mfma_i32_16x16x64_i8 v[122:125], v[156:159], v[186:189], v[122:125]
	v_mfma_i32_16x16x64_i8 v[114:117], v[156:159], v[194:197], v[114:117]
	v_mfma_i32_16x16x64_i8 v[118:121], v[148:151], v[194:197], v[118:121]
	v_mfma_i32_16x16x64_i8 v[110:113], v[148:151], v[202:205], v[110:113]
	v_mfma_i32_16x16x64_i8 v[106:109], v[156:159], v[202:205], v[106:109]
	v_mfma_i32_16x16x64_i8 v[98:101], v[156:159], v[210:213], v[98:101]
	v_mfma_i32_16x16x64_i8 v[102:105], v[148:151], v[210:213], v[102:105]
	v_mfma_i32_16x16x64_i8 v[126:129], v[152:155], v[190:193], v[126:129]
	v_mfma_i32_16x16x64_i8 v[122:125], v[166:169], v[190:193], v[122:125]
	v_mfma_i32_16x16x64_i8 v[114:117], v[166:169], v[198:201], v[114:117]
	v_mfma_i32_16x16x64_i8 v[118:121], v[152:155], v[198:201], v[118:121]
	v_mfma_i32_16x16x64_i8 v[110:113], v[152:155], v[206:209], v[110:113]
	v_mfma_i32_16x16x64_i8 v[106:109], v[166:169], v[206:209], v[106:109]
	v_mfma_i32_16x16x64_i8 v[98:101], v[166:169], v[214:217], v[98:101]
	v_mfma_i32_16x16x64_i8 v[102:105], v[152:155], v[214:217], v[102:105]
	s_setprio 0
	s_setprio 3
	v_mfma_i32_16x16x64_i8 v[66:69], v[170:173], v[186:189], v[66:69]
	v_mfma_i32_16x16x64_i8 v[58:61], v[178:181], v[186:189], v[58:61]
	v_mfma_i32_16x16x64_i8 v[50:53], v[178:181], v[194:197], v[50:53]
	v_mfma_i32_16x16x64_i8 v[54:57], v[170:173], v[194:197], v[54:57]
	v_mfma_i32_16x16x64_i8 v[46:49], v[170:173], v[202:205], v[46:49]
	v_mfma_i32_16x16x64_i8 v[42:45], v[178:181], v[202:205], v[42:45]
	v_mfma_i32_16x16x64_i8 v[34:37], v[178:181], v[210:213], v[34:37]
	v_mfma_i32_16x16x64_i8 v[38:41], v[170:173], v[210:213], v[38:41]
	v_mfma_i32_16x16x64_i8 v[66:69], v[174:177], v[190:193], v[66:69]
	v_mfma_i32_16x16x64_i8 v[58:61], v[182:185], v[190:193], v[58:61]
	v_mfma_i32_16x16x64_i8 v[50:53], v[182:185], v[198:201], v[50:53]
	v_mfma_i32_16x16x64_i8 v[54:57], v[174:177], v[198:201], v[54:57]
	v_mfma_i32_16x16x64_i8 v[46:49], v[174:177], v[206:209], v[46:49]
	v_mfma_i32_16x16x64_i8 v[42:45], v[182:185], v[206:209], v[42:45]
	v_mfma_i32_16x16x64_i8 v[34:37], v[182:185], v[214:217], v[34:37]
	v_mfma_i32_16x16x64_i8 v[38:41], v[174:177], v[214:217], v[38:41]
	s_setprio 0
	s_barrier
	s_add_i32 s0, s62, s3
	v_lshl_add_u64 v[160:161], s[50:51], 0, v[130:131]
	s_mov_b32 m0, s0
	ds_read_b128 v[186:189], v165 offset:16384
	ds_read_b128 v[190:193], v165 offset:17408
	ds_read_b128 v[194:197], v165 offset:18432
	ds_read_b128 v[198:201], v165 offset:19456
	ds_read_b128 v[202:205], v165 offset:20480
	ds_read_b128 v[206:209], v165 offset:21504
	ds_read_b128 v[210:213], v165 offset:22528
	ds_read_b128 v[214:217], v165 offset:23552
	global_load_lds_dwordx4 v[160:161], off
	s_add_i32 m0, s0, 0x2000
	s_add_u32 s0, s50, 0x80000
	v_lshl_add_u64 v[160:161], s[50:51], 0, v[132:133]
	s_addc_u32 s1, s51, 0
	s_add_i32 s68, s63, s3
	global_load_lds_dwordx4 v[160:161], off
	v_lshl_add_u64 v[160:161], s[0:1], 0, v[130:131]
	s_mov_b32 m0, s68
	v_lshl_add_u64 v[218:219], s[52:53], 0, v[134:135]
	global_load_lds_dwordx4 v[160:161], off
	v_lshl_add_u64 v[160:161], s[0:1], 0, v[132:133]
	s_add_i32 m0, s68, 0x2000
	s_nop 0
	global_load_lds_dwordx4 v[160:161], off
	v_lshl_add_u64 v[160:161], s[52:53], 0, v[136:137]
	s_mov_b32 m0, s47
	s_nop 0
	global_load_lds_dwordx4 v[160:161], off
	s_mov_b32 m0, s55
	s_nop 0
	global_load_lds_dwordx4 v[218:219], off
	s_waitcnt vmcnt(8)
	s_waitcnt lgkmcnt(0)
	s_barrier
	s_setprio 3
	s_waitcnt lgkmcnt(0)
	v_mfma_i32_16x16x64_i8 v[94:97], v[148:151], v[186:189], v[94:97]
	v_mfma_i32_16x16x64_i8 v[90:93], v[156:159], v[186:189], v[90:93]
	v_mfma_i32_16x16x64_i8 v[82:85], v[156:159], v[194:197], v[82:85]
	v_mfma_i32_16x16x64_i8 v[86:89], v[148:151], v[194:197], v[86:89]
	v_mfma_i32_16x16x64_i8 v[78:81], v[148:151], v[202:205], v[78:81]
	v_mfma_i32_16x16x64_i8 v[74:77], v[156:159], v[202:205], v[74:77]
	v_mfma_i32_16x16x64_i8 v[62:65], v[156:159], v[210:213], v[62:65]
	v_mfma_i32_16x16x64_i8 v[70:73], v[148:151], v[210:213], v[70:73]
	v_mfma_i32_16x16x64_i8 v[94:97], v[152:155], v[190:193], v[94:97]
	v_mfma_i32_16x16x64_i8 v[90:93], v[166:169], v[190:193], v[90:93]
	v_mfma_i32_16x16x64_i8 v[82:85], v[166:169], v[198:201], v[82:85]
	v_mfma_i32_16x16x64_i8 v[86:89], v[152:155], v[198:201], v[86:89]
	v_mfma_i32_16x16x64_i8 v[78:81], v[152:155], v[206:209], v[78:81]
	v_mfma_i32_16x16x64_i8 v[74:77], v[166:169], v[206:209], v[74:77]
	v_mfma_i32_16x16x64_i8 v[62:65], v[166:169], v[214:217], v[62:65]
	v_mfma_i32_16x16x64_i8 v[70:73], v[152:155], v[214:217], v[70:73]
	s_setprio 0
	s_setprio 3
	v_mfma_i32_16x16x64_i8 v[30:33], v[170:173], v[186:189], v[30:33]
	v_mfma_i32_16x16x64_i8 v[26:29], v[178:181], v[186:189], v[26:29]
	v_mfma_i32_16x16x64_i8 v[18:21], v[178:181], v[194:197], v[18:21]
	v_mfma_i32_16x16x64_i8 v[22:25], v[170:173], v[194:197], v[22:25]
	v_mfma_i32_16x16x64_i8 v[14:17], v[170:173], v[202:205], v[14:17]
	v_mfma_i32_16x16x64_i8 v[10:13], v[178:181], v[202:205], v[10:13]
	v_mfma_i32_16x16x64_i8 v[2:5], v[178:181], v[210:213], v[2:5]
	v_mfma_i32_16x16x64_i8 v[6:9], v[170:173], v[210:213], v[6:9]
	v_mfma_i32_16x16x64_i8 v[30:33], v[174:177], v[190:193], v[30:33]
	v_mfma_i32_16x16x64_i8 v[26:29], v[182:185], v[190:193], v[26:29]
	v_mfma_i32_16x16x64_i8 v[18:21], v[182:185], v[198:201], v[18:21]
	v_mfma_i32_16x16x64_i8 v[22:25], v[174:177], v[198:201], v[22:25]
	v_mfma_i32_16x16x64_i8 v[14:17], v[174:177], v[206:209], v[14:17]
	v_mfma_i32_16x16x64_i8 v[10:13], v[182:185], v[206:209], v[10:13]
	v_mfma_i32_16x16x64_i8 v[2:5], v[182:185], v[214:217], v[2:5]
	v_mfma_i32_16x16x64_i8 v[6:9], v[174:177], v[214:217], v[6:9]
	s_setprio 0
	s_barrier
	s_add_i32 s68, 0, 0x18000
	s_add_i32 s69, 0, 0x1c000
	v_add_u32_e32 v166, s68, v147
	v_add_u32_e32 v182, s69, v147
	ds_read_b128 v[148:151], v166
	ds_read_b128 v[152:155], v166 offset:1024
	ds_read_b128 v[156:159], v166 offset:2048
	ds_read_b128 v[166:169], v166 offset:3072
	ds_read_b128 v[170:173], v182
	ds_read_b128 v[174:177], v182 offset:1024
	ds_read_b128 v[178:181], v182 offset:2048
	ds_read_b128 v[182:185], v182 offset:3072
	s_add_u32 s0, s52, 0x80000
	s_addc_u32 s1, s53, 0
	s_mov_b32 m0, s56
	v_lshl_add_u64 v[220:221], s[0:1], 0, v[136:137]
	ds_read_b128 v[186:189], v165 offset:32768
	ds_read_b128 v[190:193], v165 offset:33792
	ds_read_b128 v[194:197], v165 offset:34816
	ds_read_b128 v[198:201], v165 offset:35840
	ds_read_b128 v[202:205], v165 offset:36864
	ds_read_b128 v[206:209], v165 offset:37888
	ds_read_b128 v[210:213], v165 offset:38912
	ds_read_b128 v[214:217], v165 offset:39936
	global_load_lds_dwordx4 v[220:221], off
	v_lshl_add_u64 v[220:221], s[0:1], 0, v[134:135]
	s_mov_b32 m0, s57
	s_nop 0
	global_load_lds_dwordx4 v[220:221], off
	s_waitcnt vmcnt(8)
	s_waitcnt lgkmcnt(0)
	s_barrier
	s_setprio 3
	s_waitcnt lgkmcnt(0)
	v_mfma_i32_16x16x64_i8 v[126:129], v[148:151], v[186:189], v[126:129]
	v_mfma_i32_16x16x64_i8 v[122:125], v[156:159], v[186:189], v[122:125]
	v_mfma_i32_16x16x64_i8 v[114:117], v[156:159], v[194:197], v[114:117]
	v_mfma_i32_16x16x64_i8 v[118:121], v[148:151], v[194:197], v[118:121]
	v_mfma_i32_16x16x64_i8 v[110:113], v[148:151], v[202:205], v[110:113]
	v_mfma_i32_16x16x64_i8 v[106:109], v[156:159], v[202:205], v[106:109]
	v_mfma_i32_16x16x64_i8 v[98:101], v[156:159], v[210:213], v[98:101]
	v_mfma_i32_16x16x64_i8 v[102:105], v[148:151], v[210:213], v[102:105]
	v_mfma_i32_16x16x64_i8 v[126:129], v[152:155], v[190:193], v[126:129]
	v_mfma_i32_16x16x64_i8 v[122:125], v[166:169], v[190:193], v[122:125]
	v_mfma_i32_16x16x64_i8 v[114:117], v[166:169], v[198:201], v[114:117]
	v_mfma_i32_16x16x64_i8 v[118:121], v[152:155], v[198:201], v[118:121]
	v_mfma_i32_16x16x64_i8 v[110:113], v[152:155], v[206:209], v[110:113]
	v_mfma_i32_16x16x64_i8 v[106:109], v[166:169], v[206:209], v[106:109]
	v_mfma_i32_16x16x64_i8 v[98:101], v[166:169], v[214:217], v[98:101]
	v_mfma_i32_16x16x64_i8 v[102:105], v[152:155], v[214:217], v[102:105]
	s_setprio 0
	s_setprio 3
	v_mfma_i32_16x16x64_i8 v[66:69], v[170:173], v[186:189], v[66:69]
	v_mfma_i32_16x16x64_i8 v[58:61], v[178:181], v[186:189], v[58:61]
	v_mfma_i32_16x16x64_i8 v[50:53], v[178:181], v[194:197], v[50:53]
	v_mfma_i32_16x16x64_i8 v[54:57], v[170:173], v[194:197], v[54:57]
	v_mfma_i32_16x16x64_i8 v[46:49], v[170:173], v[202:205], v[46:49]
	v_mfma_i32_16x16x64_i8 v[42:45], v[178:181], v[202:205], v[42:45]
	v_mfma_i32_16x16x64_i8 v[34:37], v[178:181], v[210:213], v[34:37]
	v_mfma_i32_16x16x64_i8 v[38:41], v[170:173], v[210:213], v[38:41]
	v_mfma_i32_16x16x64_i8 v[66:69], v[174:177], v[190:193], v[66:69]
	v_mfma_i32_16x16x64_i8 v[58:61], v[182:185], v[190:193], v[58:61]
	v_mfma_i32_16x16x64_i8 v[50:53], v[182:185], v[198:201], v[50:53]
	v_mfma_i32_16x16x64_i8 v[54:57], v[174:177], v[198:201], v[54:57]
	v_mfma_i32_16x16x64_i8 v[46:49], v[174:177], v[206:209], v[46:49]
	v_mfma_i32_16x16x64_i8 v[42:45], v[182:185], v[206:209], v[42:45]
	v_mfma_i32_16x16x64_i8 v[34:37], v[182:185], v[214:217], v[34:37]
	v_mfma_i32_16x16x64_i8 v[38:41], v[174:177], v[214:217], v[38:41]
	s_setprio 0
	s_barrier
	s_add_u32 s0, s50, 0x4000
	s_addc_u32 s1, s51, 0
	s_add_i32 s52, s68, s3
	v_lshl_add_u64 v[220:221], s[0:1], 0, v[130:131]
	s_mov_b32 m0, s52
	ds_read_b128 v[186:189], v165 offset:49152
	ds_read_b128 v[190:193], v165 offset:50176
	ds_read_b128 v[194:197], v165 offset:51200
	ds_read_b128 v[198:201], v165 offset:52224
	ds_read_b128 v[202:205], v165 offset:53248
	ds_read_b128 v[206:209], v165 offset:54272
	ds_read_b128 v[210:213], v165 offset:55296
	ds_read_b128 v[214:217], v165 offset:56320
	global_load_lds_dwordx4 v[220:221], off
	s_add_i32 m0, s52, 0x2000
	v_lshl_add_u64 v[220:221], s[0:1], 0, v[132:133]
	s_add_u32 s0, s50, 0x84000
	s_addc_u32 s1, s51, 0
	s_add_i32 s50, s69, s3
	global_load_lds_dwordx4 v[220:221], off
	v_lshl_add_u64 v[220:221], s[0:1], 0, v[130:131]
	s_mov_b32 m0, s50
	v_lshl_add_u64 v[160:161], v[160:161], 0, s[20:21]
	global_load_lds_dwordx4 v[220:221], off
	v_lshl_add_u64 v[220:221], s[0:1], 0, v[132:133]
	s_add_i32 m0, s50, 0x2000
	s_nop 0
	global_load_lds_dwordx4 v[220:221], off
	s_mov_b32 m0, s59
	s_nop 0
	global_load_lds_dwordx4 v[160:161], off
	v_lshl_add_u64 v[160:161], v[218:219], 0, s[20:21]
	s_mov_b32 m0, s60
	s_nop 0
	global_load_lds_dwordx4 v[160:161], off
	s_waitcnt vmcnt(8)
	s_waitcnt lgkmcnt(0)
	s_barrier
	s_setprio 3
	s_waitcnt lgkmcnt(0)
	v_mfma_i32_16x16x64_i8 v[94:97], v[148:151], v[186:189], v[94:97]
	v_mfma_i32_16x16x64_i8 v[90:93], v[156:159], v[186:189], v[90:93]
	v_mfma_i32_16x16x64_i8 v[82:85], v[156:159], v[194:197], v[82:85]
	v_mfma_i32_16x16x64_i8 v[86:89], v[148:151], v[194:197], v[86:89]
	v_mfma_i32_16x16x64_i8 v[78:81], v[148:151], v[202:205], v[78:81]
	v_mfma_i32_16x16x64_i8 v[74:77], v[156:159], v[202:205], v[74:77]
	v_mfma_i32_16x16x64_i8 v[62:65], v[156:159], v[210:213], v[62:65]
	v_mfma_i32_16x16x64_i8 v[70:73], v[148:151], v[210:213], v[70:73]
	v_mfma_i32_16x16x64_i8 v[94:97], v[152:155], v[190:193], v[94:97]
	v_mfma_i32_16x16x64_i8 v[90:93], v[166:169], v[190:193], v[90:93]
	v_mfma_i32_16x16x64_i8 v[82:85], v[166:169], v[198:201], v[82:85]
	v_mfma_i32_16x16x64_i8 v[86:89], v[152:155], v[198:201], v[86:89]
	v_mfma_i32_16x16x64_i8 v[78:81], v[152:155], v[206:209], v[78:81]
	v_mfma_i32_16x16x64_i8 v[74:77], v[166:169], v[206:209], v[74:77]
	v_mfma_i32_16x16x64_i8 v[62:65], v[166:169], v[214:217], v[62:65]
	v_mfma_i32_16x16x64_i8 v[70:73], v[152:155], v[214:217], v[70:73]
	s_setprio 0
	s_setprio 3
	v_mfma_i32_16x16x64_i8 v[30:33], v[170:173], v[186:189], v[30:33]
	v_mfma_i32_16x16x64_i8 v[26:29], v[178:181], v[186:189], v[26:29]
	v_mfma_i32_16x16x64_i8 v[18:21], v[178:181], v[194:197], v[18:21]
	v_mfma_i32_16x16x64_i8 v[22:25], v[170:173], v[194:197], v[22:25]
	v_mfma_i32_16x16x64_i8 v[14:17], v[170:173], v[202:205], v[14:17]
	v_mfma_i32_16x16x64_i8 v[10:13], v[178:181], v[202:205], v[10:13]
	v_mfma_i32_16x16x64_i8 v[2:5], v[178:181], v[210:213], v[2:5]
	v_mfma_i32_16x16x64_i8 v[6:9], v[170:173], v[210:213], v[6:9]
	v_mfma_i32_16x16x64_i8 v[30:33], v[174:177], v[190:193], v[30:33]
	v_mfma_i32_16x16x64_i8 v[26:29], v[182:185], v[190:193], v[26:29]
	v_mfma_i32_16x16x64_i8 v[18:21], v[182:185], v[198:201], v[18:21]
	v_mfma_i32_16x16x64_i8 v[22:25], v[174:177], v[198:201], v[22:25]
	v_mfma_i32_16x16x64_i8 v[14:17], v[174:177], v[206:209], v[14:17]
	v_mfma_i32_16x16x64_i8 v[10:13], v[182:185], v[206:209], v[10:13]
	v_mfma_i32_16x16x64_i8 v[2:5], v[182:185], v[214:217], v[2:5]
	v_mfma_i32_16x16x64_i8 v[6:9], v[174:177], v[214:217], v[6:9]
	s_setprio 0
	s_barrier
	s_add_i32 s67, s67, 2
	s_add_u32 s41, s41, 0x8000
	s_addc_u32 s43, s43, 0
	s_cmp_gt_u32 s67, 29
	s_mov_b64 s[0:1], s[48:49]
	s_cbranch_scc0 .LBB0_558
	s_and_b64 vcc, exec, s[24:25]
	s_cbranch_vccz .LBB0_561
	s_barrier

.LBB0_584:
	ds_read_b128 v[148:151], v157
	ds_read_b128 v[152:155], v157 offset:1024
	ds_read_b128 v[160:163], v157 offset:2048
	ds_read_b128 v[164:167], v157 offset:3072
	ds_read_b128 v[168:171], v158
	ds_read_b128 v[172:175], v158 offset:1024
	ds_read_b128 v[176:179], v158 offset:2048
	ds_read_b128 v[180:183], v158 offset:3072
	s_add_u32 s46, s0, 0xfff00080
	s_addc_u32 s47, s1, -1
	s_cmp_eq_u32 s64, 60
	s_cselect_b32 s49, s7, s47
	s_cselect_b32 s48, s6, s46
	s_cselect_b32 s47, s43, s41
	s_cselect_b32 s46, s42, s39
	v_lshl_add_u64 v[216:217], s[0:1], 0, v[138:139]
	s_add_i32 m0, s45, 0xc000
	ds_read_b128 v[184:187], v159
	ds_read_b128 v[188:191], v159 offset:1024
	ds_read_b128 v[192:195], v159 offset:2048
	ds_read_b128 v[196:199], v159 offset:3072
	ds_read_b128 v[200:203], v159 offset:4096
	ds_read_b128 v[204:207], v159 offset:5120
	ds_read_b128 v[208:211], v159 offset:6144
	ds_read_b128 v[212:215], v159 offset:7168
	global_load_lds_dwordx4 v[216:217], off
	v_lshl_add_u64 v[216:217], s[0:1], 0, v[140:141]
	s_add_i32 m0, s45, 0xe000
	s_nop 0
	global_load_lds_dwordx4 v[216:217], off
	s_waitcnt vmcnt(8)
	s_waitcnt lgkmcnt(0)
	s_barrier
	s_setprio 3
	s_waitcnt lgkmcnt(0)
	v_mfma_f32_16x16x32_bf16 v[126:129], v[148:151], v[184:187], v[126:129]
	v_mfma_f32_16x16x32_bf16 v[122:125], v[160:163], v[184:187], v[122:125]
	v_mfma_f32_16x16x32_bf16 v[106:109], v[160:163], v[192:195], v[106:109]
	v_mfma_f32_16x16x32_bf16 v[110:113], v[148:151], v[192:195], v[110:113]
	v_mfma_f32_16x16x32_bf16 v[94:97], v[148:151], v[200:203], v[94:97]
	v_mfma_f32_16x16x32_bf16 v[90:93], v[160:163], v[200:203], v[90:93]
	v_mfma_f32_16x16x32_bf16 v[78:81], v[160:163], v[208:211], v[78:81]
	v_mfma_f32_16x16x32_bf16 v[86:89], v[148:151], v[208:211], v[86:89]
	v_mfma_f32_16x16x32_bf16 v[126:129], v[152:155], v[188:191], v[126:129]
	v_mfma_f32_16x16x32_bf16 v[122:125], v[164:167], v[188:191], v[122:125]
	v_mfma_f32_16x16x32_bf16 v[106:109], v[164:167], v[196:199], v[106:109]
	v_mfma_f32_16x16x32_bf16 v[110:113], v[152:155], v[196:199], v[110:113]
	v_mfma_f32_16x16x32_bf16 v[94:97], v[152:155], v[204:207], v[94:97]
	v_mfma_f32_16x16x32_bf16 v[90:93], v[164:167], v[204:207], v[90:93]
	v_mfma_f32_16x16x32_bf16 v[78:81], v[164:167], v[212:215], v[78:81]
	v_mfma_f32_16x16x32_bf16 v[86:89], v[152:155], v[212:215], v[86:89]
	s_setprio 0
	s_setprio 3
	v_mfma_f32_16x16x32_bf16 v[118:121], v[168:171], v[184:187], v[118:121]
	v_mfma_f32_16x16x32_bf16 v[114:117], v[176:179], v[184:187], v[114:117]
	v_mfma_f32_16x16x32_bf16 v[98:101], v[176:179], v[192:195], v[98:101]
	v_mfma_f32_16x16x32_bf16 v[102:105], v[168:171], v[192:195], v[102:105]
	v_mfma_f32_16x16x32_bf16 v[82:85], v[168:171], v[200:203], v[82:85]
	v_mfma_f32_16x16x32_bf16 v[74:77], v[176:179], v[200:203], v[74:77]
	v_mfma_f32_16x16x32_bf16 v[66:69], v[176:179], v[208:211], v[66:69]
	v_mfma_f32_16x16x32_bf16 v[70:73], v[168:171], v[208:211], v[70:73]
	v_mfma_f32_16x16x32_bf16 v[118:121], v[172:175], v[188:191], v[118:121]
	v_mfma_f32_16x16x32_bf16 v[114:117], v[180:183], v[188:191], v[114:117]
	v_mfma_f32_16x16x32_bf16 v[98:101], v[180:183], v[196:199], v[98:101]
	v_mfma_f32_16x16x32_bf16 v[102:105], v[172:175], v[196:199], v[102:105]
	v_mfma_f32_16x16x32_bf16 v[82:85], v[172:175], v[204:207], v[82:85]
	v_mfma_f32_16x16x32_bf16 v[74:77], v[180:183], v[204:207], v[74:77]
	v_mfma_f32_16x16x32_bf16 v[66:69], v[180:183], v[212:215], v[66:69]
	v_mfma_f32_16x16x32_bf16 v[70:73], v[172:175], v[212:215], v[70:73]
	s_setprio 0
	s_barrier
	s_add_i32 s65, s60, s52
	v_lshl_add_u64 v[216:217], s[46:47], 0, v[130:131]
	s_mov_b32 m0, s65
	ds_read_b128 v[184:187], v159 offset:16384
	ds_read_b128 v[188:191], v159 offset:17408
	ds_read_b128 v[192:195], v159 offset:18432
	ds_read_b128 v[196:199], v159 offset:19456
	ds_read_b128 v[200:203], v159 offset:20480
	ds_read_b128 v[204:207], v159 offset:21504
	ds_read_b128 v[208:211], v159 offset:22528
	ds_read_b128 v[212:215], v159 offset:23552
	global_load_lds_dwordx4 v[216:217], off
	s_add_i32 m0, s65, 0x2000
	s_add_u32 s68, s46, 0x100000
	v_lshl_add_u64 v[216:217], s[46:47], 0, v[134:135]
	s_addc_u32 s69, s47, 0
	s_add_i32 s65, s61, s52
	global_load_lds_dwordx4 v[216:217], off
	v_lshl_add_u64 v[216:217], s[68:69], 0, v[130:131]
	s_mov_b32 m0, s65
	v_lshl_add_u64 v[218:219], s[48:49], 0, v[136:137]
	global_load_lds_dwordx4 v[216:217], off
	v_lshl_add_u64 v[216:217], s[68:69], 0, v[134:135]
	s_add_i32 m0, s65, 0x2000
	s_nop 0
	global_load_lds_dwordx4 v[216:217], off
	v_lshl_add_u64 v[216:217], s[48:49], 0, v[132:133]
	s_mov_b32 m0, s45
	s_nop 0
	global_load_lds_dwordx4 v[216:217], off
	s_mov_b32 m0, s53
	s_nop 0
	global_load_lds_dwordx4 v[218:219], off
	s_waitcnt vmcnt(8)
	s_waitcnt lgkmcnt(0)
	s_barrier
	s_setprio 3
	s_waitcnt lgkmcnt(0)
	v_mfma_f32_16x16x32_bf16 v[62:65], v[148:151], v[184:187], v[62:65]
	v_mfma_f32_16x16x32_bf16 v[58:61], v[160:163], v[184:187], v[58:61]
	v_mfma_f32_16x16x32_bf16 v[42:45], v[160:163], v[192:195], v[42:45]
	v_mfma_f32_16x16x32_bf16 v[46:49], v[148:151], v[192:195], v[46:49]
	v_mfma_f32_16x16x32_bf16 v[30:33], v[148:151], v[200:203], v[30:33]
	v_mfma_f32_16x16x32_bf16 v[26:29], v[160:163], v[200:203], v[26:29]
	v_mfma_f32_16x16x32_bf16 v[10:13], v[160:163], v[208:211], v[10:13]
	v_mfma_f32_16x16x32_bf16 v[14:17], v[148:151], v[208:211], v[14:17]
	v_mfma_f32_16x16x32_bf16 v[62:65], v[152:155], v[188:191], v[62:65]
	v_mfma_f32_16x16x32_bf16 v[58:61], v[164:167], v[188:191], v[58:61]
	v_mfma_f32_16x16x32_bf16 v[42:45], v[164:167], v[196:199], v[42:45]
	v_mfma_f32_16x16x32_bf16 v[46:49], v[152:155], v[196:199], v[46:49]
	v_mfma_f32_16x16x32_bf16 v[30:33], v[152:155], v[204:207], v[30:33]
	v_mfma_f32_16x16x32_bf16 v[26:29], v[164:167], v[204:207], v[26:29]
	v_mfma_f32_16x16x32_bf16 v[10:13], v[164:167], v[212:215], v[10:13]
	v_mfma_f32_16x16x32_bf16 v[14:17], v[152:155], v[212:215], v[14:17]
	s_setprio 0
	s_setprio 3
	v_mfma_f32_16x16x32_bf16 v[54:57], v[168:171], v[184:187], v[54:57]
	v_mfma_f32_16x16x32_bf16 v[50:53], v[176:179], v[184:187], v[50:53]
	v_mfma_f32_16x16x32_bf16 v[34:37], v[176:179], v[192:195], v[34:37]
	v_mfma_f32_16x16x32_bf16 v[38:41], v[168:171], v[192:195], v[38:41]
	v_mfma_f32_16x16x32_bf16 v[22:25], v[168:171], v[200:203], v[22:25]
	v_mfma_f32_16x16x32_bf16 v[18:21], v[176:179], v[200:203], v[18:21]
	v_mfma_f32_16x16x32_bf16 v[2:5], v[176:179], v[208:211], v[2:5]
	v_mfma_f32_16x16x32_bf16 v[6:9], v[168:171], v[208:211], v[6:9]
	v_mfma_f32_16x16x32_bf16 v[54:57], v[172:175], v[188:191], v[54:57]
	v_mfma_f32_16x16x32_bf16 v[50:53], v[180:183], v[188:191], v[50:53]
	v_mfma_f32_16x16x32_bf16 v[34:37], v[180:183], v[196:199], v[34:37]
	v_mfma_f32_16x16x32_bf16 v[38:41], v[172:175], v[196:199], v[38:41]
	v_mfma_f32_16x16x32_bf16 v[22:25], v[172:175], v[204:207], v[22:25]
	v_mfma_f32_16x16x32_bf16 v[18:21], v[180:183], v[204:207], v[18:21]
	v_mfma_f32_16x16x32_bf16 v[2:5], v[180:183], v[212:215], v[2:5]
	v_mfma_f32_16x16x32_bf16 v[6:9], v[172:175], v[212:215], v[6:9]
	s_setprio 0
	s_barrier
	s_add_i32 s65, 0, 0x18000
	s_add_i32 s67, 0, 0x1c000
	v_add_u32_e32 v164, s65, v147
	v_add_u32_e32 v180, s67, v147
	ds_read_b128 v[148:151], v164
	ds_read_b128 v[152:155], v164 offset:1024
	ds_read_b128 v[160:163], v164 offset:2048
	ds_read_b128 v[164:167], v164 offset:3072
	ds_read_b128 v[168:171], v180
	ds_read_b128 v[172:175], v180 offset:1024
	ds_read_b128 v[176:179], v180 offset:2048
	ds_read_b128 v[180:183], v180 offset:3072
	s_add_u32 s48, s48, 0x100000
	s_addc_u32 s49, s49, 0
	s_mov_b32 m0, s54
	v_lshl_add_u64 v[220:221], s[48:49], 0, v[132:133]
	ds_read_b128 v[184:187], v159 offset:32768
	ds_read_b128 v[188:191], v159 offset:33792
	ds_read_b128 v[192:195], v159 offset:34816
	ds_read_b128 v[196:199], v159 offset:35840
	ds_read_b128 v[200:203], v159 offset:36864
	ds_read_b128 v[204:207], v159 offset:37888
	ds_read_b128 v[208:211], v159 offset:38912
	ds_read_b128 v[212:215], v159 offset:39936
	global_load_lds_dwordx4 v[220:221], off
	v_lshl_add_u64 v[220:221], s[48:49], 0, v[136:137]
	s_mov_b32 m0, s55
	s_nop 0
	global_load_lds_dwordx4 v[220:221], off
	s_waitcnt vmcnt(8)
	s_waitcnt lgkmcnt(0)
	s_barrier
	s_setprio 3
	s_waitcnt lgkmcnt(0)
	v_mfma_f32_16x16x32_bf16 v[126:129], v[148:151], v[184:187], v[126:129]
	v_mfma_f32_16x16x32_bf16 v[122:125], v[160:163], v[184:187], v[122:125]
	v_mfma_f32_16x16x32_bf16 v[106:109], v[160:163], v[192:195], v[106:109]
	v_mfma_f32_16x16x32_bf16 v[110:113], v[148:151], v[192:195], v[110:113]
	v_mfma_f32_16x16x32_bf16 v[94:97], v[148:151], v[200:203], v[94:97]
	v_mfma_f32_16x16x32_bf16 v[90:93], v[160:163], v[200:203], v[90:93]
	v_mfma_f32_16x16x32_bf16 v[78:81], v[160:163], v[208:211], v[78:81]
	v_mfma_f32_16x16x32_bf16 v[86:89], v[148:151], v[208:211], v[86:89]
	v_mfma_f32_16x16x32_bf16 v[126:129], v[152:155], v[188:191], v[126:129]
	v_mfma_f32_16x16x32_bf16 v[122:125], v[164:167], v[188:191], v[122:125]
	v_mfma_f32_16x16x32_bf16 v[106:109], v[164:167], v[196:199], v[106:109]
	v_mfma_f32_16x16x32_bf16 v[110:113], v[152:155], v[196:199], v[110:113]
	v_mfma_f32_16x16x32_bf16 v[94:97], v[152:155], v[204:207], v[94:97]
	v_mfma_f32_16x16x32_bf16 v[90:93], v[164:167], v[204:207], v[90:93]
	v_mfma_f32_16x16x32_bf16 v[78:81], v[164:167], v[212:215], v[78:81]
	v_mfma_f32_16x16x32_bf16 v[86:89], v[152:155], v[212:215], v[86:89]
	s_setprio 0
	s_setprio 3
	v_mfma_f32_16x16x32_bf16 v[118:121], v[168:171], v[184:187], v[118:121]
	v_mfma_f32_16x16x32_bf16 v[114:117], v[176:179], v[184:187], v[114:117]
	v_mfma_f32_16x16x32_bf16 v[98:101], v[176:179], v[192:195], v[98:101]
	v_mfma_f32_16x16x32_bf16 v[102:105], v[168:171], v[192:195], v[102:105]
	v_mfma_f32_16x16x32_bf16 v[82:85], v[168:171], v[200:203], v[82:85]
	v_mfma_f32_16x16x32_bf16 v[74:77], v[176:179], v[200:203], v[74:77]
	v_mfma_f32_16x16x32_bf16 v[66:69], v[176:179], v[208:211], v[66:69]
	v_mfma_f32_16x16x32_bf16 v[70:73], v[168:171], v[208:211], v[70:73]
	v_mfma_f32_16x16x32_bf16 v[118:121], v[172:175], v[188:191], v[118:121]
	v_mfma_f32_16x16x32_bf16 v[114:117], v[180:183], v[188:191], v[114:117]
	v_mfma_f32_16x16x32_bf16 v[98:101], v[180:183], v[196:199], v[98:101]
	v_mfma_f32_16x16x32_bf16 v[102:105], v[172:175], v[196:199], v[102:105]
	v_mfma_f32_16x16x32_bf16 v[82:85], v[172:175], v[204:207], v[82:85]
	v_mfma_f32_16x16x32_bf16 v[74:77], v[180:183], v[204:207], v[74:77]
	v_mfma_f32_16x16x32_bf16 v[66:69], v[180:183], v[212:215], v[66:69]
	v_mfma_f32_16x16x32_bf16 v[70:73], v[172:175], v[212:215], v[70:73]
	s_setprio 0
	s_barrier
	s_add_u32 s48, s46, 0x4000
	s_addc_u32 s49, s47, 0
	s_add_i32 s65, s65, s52
	v_lshl_add_u64 v[220:221], s[48:49], 0, v[130:131]
	s_mov_b32 m0, s65
	ds_read_b128 v[184:187], v159 offset:49152
	ds_read_b128 v[188:191], v159 offset:50176
	ds_read_b128 v[192:195], v159 offset:51200
	ds_read_b128 v[196:199], v159 offset:52224
	ds_read_b128 v[200:203], v159 offset:53248
	ds_read_b128 v[204:207], v159 offset:54272
	ds_read_b128 v[208:211], v159 offset:55296
	ds_read_b128 v[212:215], v159 offset:56320
	global_load_lds_dwordx4 v[220:221], off
	s_add_i32 m0, s65, 0x2000
	s_add_u32 s46, s46, 0x104000
	v_lshl_add_u64 v[220:221], s[48:49], 0, v[134:135]
	s_addc_u32 s47, s47, 0
	s_add_i32 s48, s67, s52
	global_load_lds_dwordx4 v[220:221], off
	v_lshl_add_u64 v[220:221], s[46:47], 0, v[130:131]
	s_mov_b32 m0, s48
	v_lshl_add_u64 v[216:217], v[216:217], 0, s[20:21]
	global_load_lds_dwordx4 v[220:221], off
	v_lshl_add_u64 v[220:221], s[46:47], 0, v[134:135]
	s_add_i32 m0, s48, 0x2000
	s_nop 0
	global_load_lds_dwordx4 v[220:221], off
	s_mov_b32 m0, s57
	s_nop 0
	global_load_lds_dwordx4 v[216:217], off
	v_lshl_add_u64 v[216:217], v[218:219], 0, s[20:21]
	s_mov_b32 m0, s58
	s_nop 0
	global_load_lds_dwordx4 v[216:217], off
	s_waitcnt vmcnt(8)
	s_waitcnt lgkmcnt(0)
	s_barrier
	s_setprio 3
	s_waitcnt lgkmcnt(0)
	v_mfma_f32_16x16x32_bf16 v[62:65], v[148:151], v[184:187], v[62:65]
	v_mfma_f32_16x16x32_bf16 v[58:61], v[160:163], v[184:187], v[58:61]
	v_mfma_f32_16x16x32_bf16 v[42:45], v[160:163], v[192:195], v[42:45]
	v_mfma_f32_16x16x32_bf16 v[46:49], v[148:151], v[192:195], v[46:49]
	v_mfma_f32_16x16x32_bf16 v[30:33], v[148:151], v[200:203], v[30:33]
	v_mfma_f32_16x16x32_bf16 v[26:29], v[160:163], v[200:203], v[26:29]
	v_mfma_f32_16x16x32_bf16 v[10:13], v[160:163], v[208:211], v[10:13]
	v_mfma_f32_16x16x32_bf16 v[14:17], v[148:151], v[208:211], v[14:17]
	v_mfma_f32_16x16x32_bf16 v[62:65], v[152:155], v[188:191], v[62:65]
	v_mfma_f32_16x16x32_bf16 v[58:61], v[164:167], v[188:191], v[58:61]
	v_mfma_f32_16x16x32_bf16 v[42:45], v[164:167], v[196:199], v[42:45]
	v_mfma_f32_16x16x32_bf16 v[46:49], v[152:155], v[196:199], v[46:49]
	v_mfma_f32_16x16x32_bf16 v[30:33], v[152:155], v[204:207], v[30:33]
	v_mfma_f32_16x16x32_bf16 v[26:29], v[164:167], v[204:207], v[26:29]
	v_mfma_f32_16x16x32_bf16 v[10:13], v[164:167], v[212:215], v[10:13]
	v_mfma_f32_16x16x32_bf16 v[14:17], v[152:155], v[212:215], v[14:17]
	s_setprio 0
	s_setprio 3
	v_mfma_f32_16x16x32_bf16 v[54:57], v[168:171], v[184:187], v[54:57]
	v_mfma_f32_16x16x32_bf16 v[50:53], v[176:179], v[184:187], v[50:53]
	v_mfma_f32_16x16x32_bf16 v[34:37], v[176:179], v[192:195], v[34:37]
	v_mfma_f32_16x16x32_bf16 v[38:41], v[168:171], v[192:195], v[38:41]
	v_mfma_f32_16x16x32_bf16 v[22:25], v[168:171], v[200:203], v[22:25]
	v_mfma_f32_16x16x32_bf16 v[18:21], v[176:179], v[200:203], v[18:21]
	v_mfma_f32_16x16x32_bf16 v[2:5], v[176:179], v[208:211], v[2:5]
	v_mfma_f32_16x16x32_bf16 v[6:9], v[168:171], v[208:211], v[6:9]
	v_mfma_f32_16x16x32_bf16 v[54:57], v[172:175], v[188:191], v[54:57]
	v_mfma_f32_16x16x32_bf16 v[50:53], v[180:183], v[188:191], v[50:53]
	v_mfma_f32_16x16x32_bf16 v[34:37], v[180:183], v[196:199], v[34:37]
	v_mfma_f32_16x16x32_bf16 v[38:41], v[172:175], v[196:199], v[38:41]
	v_mfma_f32_16x16x32_bf16 v[22:25], v[172:175], v[204:207], v[22:25]
	v_mfma_f32_16x16x32_bf16 v[18:21], v[180:183], v[204:207], v[18:21]
	v_mfma_f32_16x16x32_bf16 v[2:5], v[180:183], v[212:215], v[2:5]
	v_mfma_f32_16x16x32_bf16 v[6:9], v[172:175], v[212:215], v[6:9]
	s_setprio 0
	s_barrier
	s_add_i32 s64, s64, 2
	s_add_u32 s39, s39, 0x8000
	s_addc_u32 s41, s41, 0
	s_add_u32 s0, s0, 0x100
	s_addc_u32 s1, s1, 0
	s_cmp_gt_u32 s64, 61
	s_cbranch_scc0 .LBB0_584
	s_and_b64 vcc, exec, s[24:25]
	s_cbranch_vccz .LBB0_587
	s_barrier

.LBB0_610:
	ds_read_b128 v[148:151], v163
	ds_read_b128 v[152:155], v163 offset:1024
	ds_read_b128 v[156:159], v163 offset:2048
	ds_read_b128 v[166:169], v163 offset:3072
	ds_read_b128 v[170:173], v164
	ds_read_b128 v[174:177], v164 offset:1024
	ds_read_b128 v[178:181], v164 offset:2048
	ds_read_b128 v[182:185], v164 offset:3072
	s_add_u32 s6, s0, 0x100
	s_addc_u32 s7, s1, 0
	s_cmp_eq_u32 s68, 28
	s_cselect_b32 s53, s45, s7
	s_cselect_b32 s52, s44, s6
	s_cselect_b32 s51, s47, s43
	s_cselect_b32 s50, s46, s41
	v_lshl_add_u64 v[160:161], s[0:1], 0, v[138:139]
	s_add_i32 m0, s49, 0xc000
	ds_read_b128 v[186:189], v165
	ds_read_b128 v[190:193], v165 offset:1024
	ds_read_b128 v[194:197], v165 offset:2048
	ds_read_b128 v[198:201], v165 offset:3072
	ds_read_b128 v[202:205], v165 offset:4096
	ds_read_b128 v[206:209], v165 offset:5120
	ds_read_b128 v[210:213], v165 offset:6144
	ds_read_b128 v[214:217], v165 offset:7168
	global_load_lds_dwordx4 v[160:161], off
	v_lshl_add_u64 v[160:161], s[0:1], 0, v[140:141]
	s_add_i32 m0, s49, 0xe000
	s_nop 0
	global_load_lds_dwordx4 v[160:161], off
	s_waitcnt vmcnt(8)
	s_waitcnt lgkmcnt(0)
	s_barrier
	s_setprio 3
	s_waitcnt lgkmcnt(0)
	v_mfma_i32_16x16x64_i8 v[126:129], v[148:151], v[186:189], v[126:129]
	v_mfma_i32_16x16x64_i8 v[122:125], v[156:159], v[186:189], v[122:125]
	v_mfma_i32_16x16x64_i8 v[114:117], v[156:159], v[194:197], v[114:117]
	v_mfma_i32_16x16x64_i8 v[118:121], v[148:151], v[194:197], v[118:121]
	v_mfma_i32_16x16x64_i8 v[110:113], v[148:151], v[202:205], v[110:113]
	v_mfma_i32_16x16x64_i8 v[106:109], v[156:159], v[202:205], v[106:109]
	v_mfma_i32_16x16x64_i8 v[98:101], v[156:159], v[210:213], v[98:101]
	v_mfma_i32_16x16x64_i8 v[102:105], v[148:151], v[210:213], v[102:105]
	v_mfma_i32_16x16x64_i8 v[126:129], v[152:155], v[190:193], v[126:129]
	v_mfma_i32_16x16x64_i8 v[122:125], v[166:169], v[190:193], v[122:125]
	v_mfma_i32_16x16x64_i8 v[114:117], v[166:169], v[198:201], v[114:117]
	v_mfma_i32_16x16x64_i8 v[118:121], v[152:155], v[198:201], v[118:121]
	v_mfma_i32_16x16x64_i8 v[110:113], v[152:155], v[206:209], v[110:113]
	v_mfma_i32_16x16x64_i8 v[106:109], v[166:169], v[206:209], v[106:109]
	v_mfma_i32_16x16x64_i8 v[98:101], v[166:169], v[214:217], v[98:101]
	v_mfma_i32_16x16x64_i8 v[102:105], v[152:155], v[214:217], v[102:105]
	s_setprio 0
	s_setprio 3
	v_mfma_i32_16x16x64_i8 v[62:65], v[170:173], v[186:189], v[62:65]
	v_mfma_i32_16x16x64_i8 v[58:61], v[178:181], v[186:189], v[58:61]
	v_mfma_i32_16x16x64_i8 v[50:53], v[178:181], v[194:197], v[50:53]
	v_mfma_i32_16x16x64_i8 v[54:57], v[170:173], v[194:197], v[54:57]
	v_mfma_i32_16x16x64_i8 v[46:49], v[170:173], v[202:205], v[46:49]
	v_mfma_i32_16x16x64_i8 v[42:45], v[178:181], v[202:205], v[42:45]
	v_mfma_i32_16x16x64_i8 v[34:37], v[178:181], v[210:213], v[34:37]
	v_mfma_i32_16x16x64_i8 v[38:41], v[170:173], v[210:213], v[38:41]
	v_mfma_i32_16x16x64_i8 v[62:65], v[174:177], v[190:193], v[62:65]
	v_mfma_i32_16x16x64_i8 v[58:61], v[182:185], v[190:193], v[58:61]
	v_mfma_i32_16x16x64_i8 v[50:53], v[182:185], v[198:201], v[50:53]
	v_mfma_i32_16x16x64_i8 v[54:57], v[174:177], v[198:201], v[54:57]
	v_mfma_i32_16x16x64_i8 v[46:49], v[174:177], v[206:209], v[46:49]
	v_mfma_i32_16x16x64_i8 v[42:45], v[182:185], v[206:209], v[42:45]
	v_mfma_i32_16x16x64_i8 v[34:37], v[182:185], v[214:217], v[34:37]
	v_mfma_i32_16x16x64_i8 v[38:41], v[174:177], v[214:217], v[38:41]
	s_setprio 0
	s_barrier
	s_add_i32 s0, s63, s55
	v_lshl_add_u64 v[160:161], s[50:51], 0, v[130:131]
	s_mov_b32 m0, s0
	ds_read_b128 v[186:189], v165 offset:16384
	ds_read_b128 v[190:193], v165 offset:17408
	ds_read_b128 v[194:197], v165 offset:18432
	ds_read_b128 v[198:201], v165 offset:19456
	ds_read_b128 v[202:205], v165 offset:20480
	ds_read_b128 v[206:209], v165 offset:21504
	ds_read_b128 v[210:213], v165 offset:22528
	ds_read_b128 v[214:217], v165 offset:23552
	global_load_lds_dwordx4 v[160:161], off
	s_add_i32 m0, s0, 0x2000
	s_add_u32 s0, s50, 0x80000
	v_lshl_add_u64 v[160:161], s[50:51], 0, v[134:135]
	s_addc_u32 s1, s51, 0
	s_add_i32 s69, s64, s55
	global_load_lds_dwordx4 v[160:161], off
	v_lshl_add_u64 v[160:161], s[0:1], 0, v[130:131]
	s_mov_b32 m0, s69
	v_lshl_add_u64 v[218:219], s[52:53], 0, v[136:137]
	global_load_lds_dwordx4 v[160:161], off
	v_lshl_add_u64 v[160:161], s[0:1], 0, v[134:135]
	s_add_i32 m0, s69, 0x2000
	s_nop 0
	global_load_lds_dwordx4 v[160:161], off
	v_lshl_add_u64 v[160:161], s[52:53], 0, v[132:133]
	s_mov_b32 m0, s49
	s_nop 0
	global_load_lds_dwordx4 v[160:161], off
	s_mov_b32 m0, s56
	s_nop 0
	global_load_lds_dwordx4 v[218:219], off
	s_waitcnt vmcnt(8)
	s_waitcnt lgkmcnt(0)
	s_barrier
	s_setprio 3
	s_waitcnt lgkmcnt(0)
	v_mfma_i32_16x16x64_i8 v[94:97], v[148:151], v[186:189], v[94:97]
	v_mfma_i32_16x16x64_i8 v[90:93], v[156:159], v[186:189], v[90:93]
	v_mfma_i32_16x16x64_i8 v[82:85], v[156:159], v[194:197], v[82:85]
	v_mfma_i32_16x16x64_i8 v[86:89], v[148:151], v[194:197], v[86:89]
	v_mfma_i32_16x16x64_i8 v[78:81], v[148:151], v[202:205], v[78:81]
	v_mfma_i32_16x16x64_i8 v[74:77], v[156:159], v[202:205], v[74:77]
	v_mfma_i32_16x16x64_i8 v[66:69], v[156:159], v[210:213], v[66:69]
	v_mfma_i32_16x16x64_i8 v[70:73], v[148:151], v[210:213], v[70:73]
	v_mfma_i32_16x16x64_i8 v[94:97], v[152:155], v[190:193], v[94:97]
	v_mfma_i32_16x16x64_i8 v[90:93], v[166:169], v[190:193], v[90:93]
	v_mfma_i32_16x16x64_i8 v[82:85], v[166:169], v[198:201], v[82:85]
	v_mfma_i32_16x16x64_i8 v[86:89], v[152:155], v[198:201], v[86:89]
	v_mfma_i32_16x16x64_i8 v[78:81], v[152:155], v[206:209], v[78:81]
	v_mfma_i32_16x16x64_i8 v[74:77], v[166:169], v[206:209], v[74:77]
	v_mfma_i32_16x16x64_i8 v[66:69], v[166:169], v[214:217], v[66:69]
	v_mfma_i32_16x16x64_i8 v[70:73], v[152:155], v[214:217], v[70:73]
	s_setprio 0
	s_setprio 3
	v_mfma_i32_16x16x64_i8 v[30:33], v[170:173], v[186:189], v[30:33]
	v_mfma_i32_16x16x64_i8 v[26:29], v[178:181], v[186:189], v[26:29]
	v_mfma_i32_16x16x64_i8 v[18:21], v[178:181], v[194:197], v[18:21]
	v_mfma_i32_16x16x64_i8 v[22:25], v[170:173], v[194:197], v[22:25]
	v_mfma_i32_16x16x64_i8 v[14:17], v[170:173], v[202:205], v[14:17]
	v_mfma_i32_16x16x64_i8 v[10:13], v[178:181], v[202:205], v[10:13]
	v_mfma_i32_16x16x64_i8 v[2:5], v[178:181], v[210:213], v[2:5]
	v_mfma_i32_16x16x64_i8 v[6:9], v[170:173], v[210:213], v[6:9]
	v_mfma_i32_16x16x64_i8 v[30:33], v[174:177], v[190:193], v[30:33]
	v_mfma_i32_16x16x64_i8 v[26:29], v[182:185], v[190:193], v[26:29]
	v_mfma_i32_16x16x64_i8 v[18:21], v[182:185], v[198:201], v[18:21]
	v_mfma_i32_16x16x64_i8 v[22:25], v[174:177], v[198:201], v[22:25]
	v_mfma_i32_16x16x64_i8 v[14:17], v[174:177], v[206:209], v[14:17]
	v_mfma_i32_16x16x64_i8 v[10:13], v[182:185], v[206:209], v[10:13]
	v_mfma_i32_16x16x64_i8 v[2:5], v[182:185], v[214:217], v[2:5]
	v_mfma_i32_16x16x64_i8 v[6:9], v[174:177], v[214:217], v[6:9]
	s_setprio 0
	s_barrier
	s_add_i32 s69, 0, 0x18000
	s_add_i32 s70, 0, 0x1c000
	v_add_u32_e32 v166, s69, v147
	v_add_u32_e32 v182, s70, v147
	ds_read_b128 v[148:151], v166
	ds_read_b128 v[152:155], v166 offset:1024
	ds_read_b128 v[156:159], v166 offset:2048
	ds_read_b128 v[166:169], v166 offset:3072
	ds_read_b128 v[170:173], v182
	ds_read_b128 v[174:177], v182 offset:1024
	ds_read_b128 v[178:181], v182 offset:2048
	ds_read_b128 v[182:185], v182 offset:3072
	s_add_u32 s0, s52, 0x80000
	s_addc_u32 s1, s53, 0
	s_mov_b32 m0, s57
	v_lshl_add_u64 v[220:221], s[0:1], 0, v[132:133]
	ds_read_b128 v[186:189], v165 offset:32768
	ds_read_b128 v[190:193], v165 offset:33792
	ds_read_b128 v[194:197], v165 offset:34816
	ds_read_b128 v[198:201], v165 offset:35840
	ds_read_b128 v[202:205], v165 offset:36864
	ds_read_b128 v[206:209], v165 offset:37888
	ds_read_b128 v[210:213], v165 offset:38912
	ds_read_b128 v[214:217], v165 offset:39936
	global_load_lds_dwordx4 v[220:221], off
	v_lshl_add_u64 v[220:221], s[0:1], 0, v[136:137]
	s_mov_b32 m0, s58
	s_nop 0
	global_load_lds_dwordx4 v[220:221], off
	s_waitcnt vmcnt(8)
	s_waitcnt lgkmcnt(0)
	s_barrier
	s_setprio 3
	s_waitcnt lgkmcnt(0)
	v_mfma_i32_16x16x64_i8 v[126:129], v[148:151], v[186:189], v[126:129]
	v_mfma_i32_16x16x64_i8 v[122:125], v[156:159], v[186:189], v[122:125]
	v_mfma_i32_16x16x64_i8 v[114:117], v[156:159], v[194:197], v[114:117]
	v_mfma_i32_16x16x64_i8 v[118:121], v[148:151], v[194:197], v[118:121]
	v_mfma_i32_16x16x64_i8 v[110:113], v[148:151], v[202:205], v[110:113]
	v_mfma_i32_16x16x64_i8 v[106:109], v[156:159], v[202:205], v[106:109]
	v_mfma_i32_16x16x64_i8 v[98:101], v[156:159], v[210:213], v[98:101]
	v_mfma_i32_16x16x64_i8 v[102:105], v[148:151], v[210:213], v[102:105]
	v_mfma_i32_16x16x64_i8 v[126:129], v[152:155], v[190:193], v[126:129]
	v_mfma_i32_16x16x64_i8 v[122:125], v[166:169], v[190:193], v[122:125]
	v_mfma_i32_16x16x64_i8 v[114:117], v[166:169], v[198:201], v[114:117]
	v_mfma_i32_16x16x64_i8 v[118:121], v[152:155], v[198:201], v[118:121]
	v_mfma_i32_16x16x64_i8 v[110:113], v[152:155], v[206:209], v[110:113]
	v_mfma_i32_16x16x64_i8 v[106:109], v[166:169], v[206:209], v[106:109]
	v_mfma_i32_16x16x64_i8 v[98:101], v[166:169], v[214:217], v[98:101]
	v_mfma_i32_16x16x64_i8 v[102:105], v[152:155], v[214:217], v[102:105]
	s_setprio 0
	s_setprio 3
	v_mfma_i32_16x16x64_i8 v[62:65], v[170:173], v[186:189], v[62:65]
	v_mfma_i32_16x16x64_i8 v[58:61], v[178:181], v[186:189], v[58:61]
	v_mfma_i32_16x16x64_i8 v[50:53], v[178:181], v[194:197], v[50:53]
	v_mfma_i32_16x16x64_i8 v[54:57], v[170:173], v[194:197], v[54:57]
	v_mfma_i32_16x16x64_i8 v[46:49], v[170:173], v[202:205], v[46:49]
	v_mfma_i32_16x16x64_i8 v[42:45], v[178:181], v[202:205], v[42:45]
	v_mfma_i32_16x16x64_i8 v[34:37], v[178:181], v[210:213], v[34:37]
	v_mfma_i32_16x16x64_i8 v[38:41], v[170:173], v[210:213], v[38:41]
	v_mfma_i32_16x16x64_i8 v[62:65], v[174:177], v[190:193], v[62:65]
	v_mfma_i32_16x16x64_i8 v[58:61], v[182:185], v[190:193], v[58:61]
	v_mfma_i32_16x16x64_i8 v[50:53], v[182:185], v[198:201], v[50:53]
	v_mfma_i32_16x16x64_i8 v[54:57], v[174:177], v[198:201], v[54:57]
	v_mfma_i32_16x16x64_i8 v[46:49], v[174:177], v[206:209], v[46:49]
	v_mfma_i32_16x16x64_i8 v[42:45], v[182:185], v[206:209], v[42:45]
	v_mfma_i32_16x16x64_i8 v[34:37], v[182:185], v[214:217], v[34:37]
	v_mfma_i32_16x16x64_i8 v[38:41], v[174:177], v[214:217], v[38:41]
	s_setprio 0
	s_barrier
	s_add_u32 s0, s50, 0x4000
	s_addc_u32 s1, s51, 0
	s_add_i32 s52, s69, s55
	v_lshl_add_u64 v[220:221], s[0:1], 0, v[130:131]
	s_mov_b32 m0, s52
	ds_read_b128 v[186:189], v165 offset:49152
	ds_read_b128 v[190:193], v165 offset:50176
	ds_read_b128 v[194:197], v165 offset:51200
	ds_read_b128 v[198:201], v165 offset:52224
	ds_read_b128 v[202:205], v165 offset:53248
	ds_read_b128 v[206:209], v165 offset:54272
	ds_read_b128 v[210:213], v165 offset:55296
	ds_read_b128 v[214:217], v165 offset:56320
	global_load_lds_dwordx4 v[220:221], off
	s_add_i32 m0, s52, 0x2000
	v_lshl_add_u64 v[220:221], s[0:1], 0, v[134:135]
	s_add_u32 s0, s50, 0x84000
	s_addc_u32 s1, s51, 0
	s_add_i32 s50, s70, s55
	global_load_lds_dwordx4 v[220:221], off
	v_lshl_add_u64 v[220:221], s[0:1], 0, v[130:131]
	s_mov_b32 m0, s50
	v_lshl_add_u64 v[160:161], v[160:161], 0, s[20:21]
	global_load_lds_dwordx4 v[220:221], off
	v_lshl_add_u64 v[220:221], s[0:1], 0, v[134:135]
	s_add_i32 m0, s50, 0x2000
	s_nop 0
	global_load_lds_dwordx4 v[220:221], off
	s_mov_b32 m0, s60
	s_nop 0
	global_load_lds_dwordx4 v[160:161], off
	v_lshl_add_u64 v[160:161], v[218:219], 0, s[20:21]
	s_mov_b32 m0, s61
	s_nop 0
	global_load_lds_dwordx4 v[160:161], off
	s_waitcnt vmcnt(8)
	s_waitcnt lgkmcnt(0)
	s_barrier
	s_setprio 3
	s_waitcnt lgkmcnt(0)
	v_mfma_i32_16x16x64_i8 v[94:97], v[148:151], v[186:189], v[94:97]
	v_mfma_i32_16x16x64_i8 v[90:93], v[156:159], v[186:189], v[90:93]
	v_mfma_i32_16x16x64_i8 v[82:85], v[156:159], v[194:197], v[82:85]
	v_mfma_i32_16x16x64_i8 v[86:89], v[148:151], v[194:197], v[86:89]
	v_mfma_i32_16x16x64_i8 v[78:81], v[148:151], v[202:205], v[78:81]
	v_mfma_i32_16x16x64_i8 v[74:77], v[156:159], v[202:205], v[74:77]
	v_mfma_i32_16x16x64_i8 v[66:69], v[156:159], v[210:213], v[66:69]
	v_mfma_i32_16x16x64_i8 v[70:73], v[148:151], v[210:213], v[70:73]
	v_mfma_i32_16x16x64_i8 v[94:97], v[152:155], v[190:193], v[94:97]
	v_mfma_i32_16x16x64_i8 v[90:93], v[166:169], v[190:193], v[90:93]
	v_mfma_i32_16x16x64_i8 v[82:85], v[166:169], v[198:201], v[82:85]
	v_mfma_i32_16x16x64_i8 v[86:89], v[152:155], v[198:201], v[86:89]
	v_mfma_i32_16x16x64_i8 v[78:81], v[152:155], v[206:209], v[78:81]
	v_mfma_i32_16x16x64_i8 v[74:77], v[166:169], v[206:209], v[74:77]
	v_mfma_i32_16x16x64_i8 v[66:69], v[166:169], v[214:217], v[66:69]
	v_mfma_i32_16x16x64_i8 v[70:73], v[152:155], v[214:217], v[70:73]
	s_setprio 0
	s_setprio 3
	v_mfma_i32_16x16x64_i8 v[30:33], v[170:173], v[186:189], v[30:33]
	v_mfma_i32_16x16x64_i8 v[26:29], v[178:181], v[186:189], v[26:29]
	v_mfma_i32_16x16x64_i8 v[18:21], v[178:181], v[194:197], v[18:21]
	v_mfma_i32_16x16x64_i8 v[22:25], v[170:173], v[194:197], v[22:25]
	v_mfma_i32_16x16x64_i8 v[14:17], v[170:173], v[202:205], v[14:17]
	v_mfma_i32_16x16x64_i8 v[10:13], v[178:181], v[202:205], v[10:13]
	v_mfma_i32_16x16x64_i8 v[2:5], v[178:181], v[210:213], v[2:5]
	v_mfma_i32_16x16x64_i8 v[6:9], v[170:173], v[210:213], v[6:9]
	v_mfma_i32_16x16x64_i8 v[30:33], v[174:177], v[190:193], v[30:33]
	v_mfma_i32_16x16x64_i8 v[26:29], v[182:185], v[190:193], v[26:29]
	v_mfma_i32_16x16x64_i8 v[18:21], v[182:185], v[198:201], v[18:21]
	v_mfma_i32_16x16x64_i8 v[22:25], v[174:177], v[198:201], v[22:25]
	v_mfma_i32_16x16x64_i8 v[14:17], v[174:177], v[206:209], v[14:17]
	v_mfma_i32_16x16x64_i8 v[10:13], v[182:185], v[206:209], v[10:13]
	v_mfma_i32_16x16x64_i8 v[2:5], v[182:185], v[214:217], v[2:5]
	v_mfma_i32_16x16x64_i8 v[6:9], v[174:177], v[214:217], v[6:9]
	s_setprio 0
	s_barrier
	s_add_i32 s68, s68, 2
	s_add_u32 s41, s41, 0x8000
	s_addc_u32 s43, s43, 0
	s_cmp_gt_u32 s68, 29
	s_mov_b64 s[0:1], s[6:7]
	s_cbranch_scc0 .LBB0_610
	s_and_b64 vcc, exec, s[24:25]
	s_cbranch_vccz .LBB0_613
	s_barrier

.LBB0_1103:
	s_lshl_b32 s47, s45, 7
	s_add_u32 s47, s52, s47
	s_addc_u32 s58, s53, 0
	s_add_u32 s59, s47, 0x100
	s_addc_u32 s60, s58, 0
	s_and_b64 s[56:57], s[54:55], exec
	s_cselect_b32 s61, s7, s60
	s_cselect_b32 s60, s6, s59
	s_lshl_b32 s45, s45, 14
	s_add_u32 s45, s50, s45
	s_addc_u32 s56, s51, 0
	s_add_u32 s45, s45, 0x8000
	s_addc_u32 s56, s56, 0
	s_and_b64 s[54:55], s[54:55], exec
	s_cselect_b32 s63, s41, s56
	s_cselect_b32 s62, s40, s45
	s_add_u32 s66, s47, 0x10080
	s_addc_u32 s67, s58, 0
	s_add_i32 s88, s78, s70
	s_add_i32 m0, s49, 0xc000
	s_add_i32 s89, s49, 0xe000
	s_add_i32 s85, s88, 0x2000
	s_add_u32 s64, s62, 0x10000
	ds_read_b128 v[130:133], v147
	ds_read_b128 v[134:137], v147 offset:1024
	ds_read_b128 v[152:155], v147 offset:2048
	ds_read_b128 v[156:159], v147 offset:3072
	ds_read_b128 v[164:167], v162
	ds_read_b128 v[168:171], v162 offset:1024
	ds_read_b128 v[172:175], v162 offset:2048
	ds_read_b128 v[176:179], v162 offset:3072
	s_addc_u32 s65, s63, 0
	s_add_i32 s87, s79, s70
	s_add_i32 s86, s87, 0x2000
	s_add_i32 s84, 0, 0x18000
	s_add_i32 s83, 0, 0x1c000
	s_add_u32 s58, s60, 0x10000
	s_addc_u32 s59, s61, 0
	s_add_u32 s54, s62, 0x4000
	s_addc_u32 s55, s63, 0
	s_add_i32 s82, s84, s70
	s_add_i32 s47, s82, 0x2000
	s_add_u32 s56, s62, 0x14000
	s_addc_u32 s57, s63, 0
	s_add_i32 s81, s83, s70
	s_add_i32 s45, s81, 0x2000
	v_lshl_add_u64 v[160:161], s[66:67], 0, v[140:141]
	ds_read_b128 v[180:183], v163
	ds_read_b128 v[184:187], v163 offset:1024
	ds_read_b128 v[188:191], v163 offset:2048
	ds_read_b128 v[192:195], v163 offset:3072
	ds_read_b128 v[196:199], v163 offset:4096
	ds_read_b128 v[200:203], v163 offset:5120
	ds_read_b128 v[204:207], v163 offset:6144
	ds_read_b128 v[208:211], v163 offset:7168
	global_load_lds_dwordx4 v[160:161], off
	v_lshl_add_u64 v[160:161], s[66:67], 0, v[144:145]
	s_mov_b32 m0, s89
	s_nop 0
	global_load_lds_dwordx4 v[160:161], off
	s_waitcnt vmcnt(8)
	s_waitcnt lgkmcnt(0)
	s_barrier
	s_setprio 3
	s_waitcnt lgkmcnt(0)
	v_mfma_f32_16x16x32_bf16 v[126:129], v[130:133], v[180:183], v[126:129]
	v_mfma_f32_16x16x32_bf16 v[122:125], v[152:155], v[180:183], v[122:125]
	v_mfma_f32_16x16x32_bf16 v[114:117], v[152:155], v[188:191], v[114:117]
	v_mfma_f32_16x16x32_bf16 v[118:121], v[130:133], v[188:191], v[118:121]
	v_mfma_f32_16x16x32_bf16 v[110:113], v[130:133], v[196:199], v[110:113]
	v_mfma_f32_16x16x32_bf16 v[106:109], v[152:155], v[196:199], v[106:109]
	v_mfma_f32_16x16x32_bf16 v[98:101], v[152:155], v[204:207], v[98:101]
	v_mfma_f32_16x16x32_bf16 v[102:105], v[130:133], v[204:207], v[102:105]
	v_mfma_f32_16x16x32_bf16 v[126:129], v[134:137], v[184:187], v[126:129]
	v_mfma_f32_16x16x32_bf16 v[122:125], v[156:159], v[184:187], v[122:125]
	v_mfma_f32_16x16x32_bf16 v[114:117], v[156:159], v[192:195], v[114:117]
	v_mfma_f32_16x16x32_bf16 v[118:121], v[134:137], v[192:195], v[118:121]
	v_mfma_f32_16x16x32_bf16 v[110:113], v[134:137], v[200:203], v[110:113]
	v_mfma_f32_16x16x32_bf16 v[106:109], v[156:159], v[200:203], v[106:109]
	v_mfma_f32_16x16x32_bf16 v[98:101], v[156:159], v[208:211], v[98:101]
	v_mfma_f32_16x16x32_bf16 v[102:105], v[134:137], v[208:211], v[102:105]
	s_setprio 0
	s_setprio 3
	v_mfma_f32_16x16x32_bf16 v[70:73], v[164:167], v[180:183], v[70:73]
	v_mfma_f32_16x16x32_bf16 v[66:69], v[172:175], v[180:183], v[66:69]
	v_mfma_f32_16x16x32_bf16 v[50:53], v[172:175], v[188:191], v[50:53]
	v_mfma_f32_16x16x32_bf16 v[54:57], v[164:167], v[188:191], v[54:57]
	v_mfma_f32_16x16x32_bf16 v[46:49], v[164:167], v[196:199], v[46:49]
	v_mfma_f32_16x16x32_bf16 v[42:45], v[172:175], v[196:199], v[42:45]
	v_mfma_f32_16x16x32_bf16 v[34:37], v[172:175], v[204:207], v[34:37]
	v_mfma_f32_16x16x32_bf16 v[38:41], v[164:167], v[204:207], v[38:41]
	v_mfma_f32_16x16x32_bf16 v[70:73], v[168:171], v[184:187], v[70:73]
	v_mfma_f32_16x16x32_bf16 v[66:69], v[176:179], v[184:187], v[66:69]
	v_mfma_f32_16x16x32_bf16 v[50:53], v[176:179], v[192:195], v[50:53]
	v_mfma_f32_16x16x32_bf16 v[54:57], v[168:171], v[192:195], v[54:57]
	v_mfma_f32_16x16x32_bf16 v[46:49], v[168:171], v[200:203], v[46:49]
	v_mfma_f32_16x16x32_bf16 v[42:45], v[176:179], v[200:203], v[42:45]
	v_mfma_f32_16x16x32_bf16 v[34:37], v[176:179], v[208:211], v[34:37]
	v_mfma_f32_16x16x32_bf16 v[38:41], v[168:171], v[208:211], v[38:41]
	s_setprio 0
	s_barrier
	s_mov_b32 m0, s88
	v_lshl_add_u64 v[160:161], s[62:63], 0, v[138:139]
	ds_read_b128 v[180:183], v163 offset:16384
	ds_read_b128 v[184:187], v163 offset:17408
	ds_read_b128 v[188:191], v163 offset:18432
	ds_read_b128 v[192:195], v163 offset:19456
	ds_read_b128 v[196:199], v163 offset:20480
	ds_read_b128 v[200:203], v163 offset:21504
	ds_read_b128 v[204:207], v163 offset:22528
	ds_read_b128 v[208:211], v163 offset:23552
	global_load_lds_dwordx4 v[160:161], off
	v_lshl_add_u64 v[160:161], s[62:63], 0, v[142:143]
	s_mov_b32 m0, s85
	v_lshl_add_u64 v[212:213], s[60:61], 0, v[144:145]
	global_load_lds_dwordx4 v[160:161], off
	v_lshl_add_u64 v[160:161], s[64:65], 0, v[138:139]
	s_mov_b32 m0, s87
	s_nop 0
	global_load_lds_dwordx4 v[160:161], off
	v_lshl_add_u64 v[160:161], s[64:65], 0, v[142:143]
	s_mov_b32 m0, s86
	s_nop 0
	global_load_lds_dwordx4 v[160:161], off
	v_lshl_add_u64 v[160:161], s[60:61], 0, v[140:141]
	s_mov_b32 m0, s49
	s_nop 0
	global_load_lds_dwordx4 v[160:161], off
	s_mov_b32 m0, s71
	s_nop 0
	global_load_lds_dwordx4 v[212:213], off
	s_waitcnt vmcnt(8)
	s_waitcnt lgkmcnt(0)
	s_barrier
	s_setprio 3
	s_waitcnt lgkmcnt(0)
	v_mfma_f32_16x16x32_bf16 v[94:97], v[130:133], v[180:183], v[94:97]
	v_mfma_f32_16x16x32_bf16 v[90:93], v[152:155], v[180:183], v[90:93]
	v_mfma_f32_16x16x32_bf16 v[82:85], v[152:155], v[188:191], v[82:85]
	v_mfma_f32_16x16x32_bf16 v[86:89], v[130:133], v[188:191], v[86:89]
	v_mfma_f32_16x16x32_bf16 v[78:81], v[130:133], v[196:199], v[78:81]
	v_mfma_f32_16x16x32_bf16 v[74:77], v[152:155], v[196:199], v[74:77]
	v_mfma_f32_16x16x32_bf16 v[58:61], v[152:155], v[204:207], v[58:61]
	v_mfma_f32_16x16x32_bf16 v[62:65], v[130:133], v[204:207], v[62:65]
	v_mfma_f32_16x16x32_bf16 v[94:97], v[134:137], v[184:187], v[94:97]
	v_mfma_f32_16x16x32_bf16 v[90:93], v[156:159], v[184:187], v[90:93]
	v_mfma_f32_16x16x32_bf16 v[82:85], v[156:159], v[192:195], v[82:85]
	v_mfma_f32_16x16x32_bf16 v[86:89], v[134:137], v[192:195], v[86:89]
	v_mfma_f32_16x16x32_bf16 v[78:81], v[134:137], v[200:203], v[78:81]
	v_mfma_f32_16x16x32_bf16 v[74:77], v[156:159], v[200:203], v[74:77]
	v_mfma_f32_16x16x32_bf16 v[58:61], v[156:159], v[208:211], v[58:61]
	v_mfma_f32_16x16x32_bf16 v[62:65], v[134:137], v[208:211], v[62:65]
	s_setprio 0
	s_setprio 3
	v_mfma_f32_16x16x32_bf16 v[30:33], v[164:167], v[180:183], v[30:33]
	v_mfma_f32_16x16x32_bf16 v[26:29], v[172:175], v[180:183], v[26:29]
	v_mfma_f32_16x16x32_bf16 v[18:21], v[172:175], v[188:191], v[18:21]
	v_mfma_f32_16x16x32_bf16 v[22:25], v[164:167], v[188:191], v[22:25]
	v_mfma_f32_16x16x32_bf16 v[14:17], v[164:167], v[196:199], v[14:17]
	v_mfma_f32_16x16x32_bf16 v[10:13], v[172:175], v[196:199], v[10:13]
	v_mfma_f32_16x16x32_bf16 v[2:5], v[172:175], v[204:207], v[2:5]
	v_mfma_f32_16x16x32_bf16 v[6:9], v[164:167], v[204:207], v[6:9]
	v_mfma_f32_16x16x32_bf16 v[30:33], v[168:171], v[184:187], v[30:33]
	v_mfma_f32_16x16x32_bf16 v[26:29], v[176:179], v[184:187], v[26:29]
	v_mfma_f32_16x16x32_bf16 v[18:21], v[176:179], v[192:195], v[18:21]
	v_mfma_f32_16x16x32_bf16 v[22:25], v[168:171], v[192:195], v[22:25]
	v_mfma_f32_16x16x32_bf16 v[14:17], v[168:171], v[200:203], v[14:17]
	v_mfma_f32_16x16x32_bf16 v[10:13], v[176:179], v[200:203], v[10:13]
	v_mfma_f32_16x16x32_bf16 v[2:5], v[176:179], v[208:211], v[2:5]
	v_mfma_f32_16x16x32_bf16 v[6:9], v[168:171], v[208:211], v[6:9]
	s_setprio 0
	s_barrier
	v_add_u32_e32 v156, s84, v1
	v_add_u32_e32 v176, s83, v1
	ds_read_b128 v[130:133], v156
	ds_read_b128 v[134:137], v156 offset:1024
	ds_read_b128 v[152:155], v156 offset:2048
	ds_read_b128 v[156:159], v156 offset:3072
	ds_read_b128 v[164:167], v176
	ds_read_b128 v[168:171], v176 offset:1024
	ds_read_b128 v[172:175], v176 offset:2048
	ds_read_b128 v[176:179], v176 offset:3072
	s_mov_b32 m0, s72
	v_lshl_add_u64 v[214:215], s[58:59], 0, v[140:141]
	ds_read_b128 v[180:183], v163 offset:32768
	ds_read_b128 v[184:187], v163 offset:33792
	ds_read_b128 v[188:191], v163 offset:34816
	ds_read_b128 v[192:195], v163 offset:35840
	ds_read_b128 v[196:199], v163 offset:36864
	ds_read_b128 v[200:203], v163 offset:37888
	ds_read_b128 v[204:207], v163 offset:38912
	ds_read_b128 v[208:211], v163 offset:39936
	global_load_lds_dwordx4 v[214:215], off
	v_lshl_add_u64 v[214:215], s[58:59], 0, v[144:145]
	s_mov_b32 m0, s73
	s_nop 0
	global_load_lds_dwordx4 v[214:215], off
	s_waitcnt vmcnt(8)
	s_waitcnt lgkmcnt(0)
	s_barrier
	s_setprio 3
	s_waitcnt lgkmcnt(0)
	v_mfma_f32_16x16x32_bf16 v[126:129], v[130:133], v[180:183], v[126:129]
	v_mfma_f32_16x16x32_bf16 v[122:125], v[152:155], v[180:183], v[122:125]
	v_mfma_f32_16x16x32_bf16 v[114:117], v[152:155], v[188:191], v[114:117]
	v_mfma_f32_16x16x32_bf16 v[118:121], v[130:133], v[188:191], v[118:121]
	v_mfma_f32_16x16x32_bf16 v[110:113], v[130:133], v[196:199], v[110:113]
	v_mfma_f32_16x16x32_bf16 v[106:109], v[152:155], v[196:199], v[106:109]
	v_mfma_f32_16x16x32_bf16 v[98:101], v[152:155], v[204:207], v[98:101]
	v_mfma_f32_16x16x32_bf16 v[102:105], v[130:133], v[204:207], v[102:105]
	v_mfma_f32_16x16x32_bf16 v[126:129], v[134:137], v[184:187], v[126:129]
	v_mfma_f32_16x16x32_bf16 v[122:125], v[156:159], v[184:187], v[122:125]
	v_mfma_f32_16x16x32_bf16 v[114:117], v[156:159], v[192:195], v[114:117]
	v_mfma_f32_16x16x32_bf16 v[118:121], v[134:137], v[192:195], v[118:121]
	v_mfma_f32_16x16x32_bf16 v[110:113], v[134:137], v[200:203], v[110:113]
	v_mfma_f32_16x16x32_bf16 v[106:109], v[156:159], v[200:203], v[106:109]
	v_mfma_f32_16x16x32_bf16 v[98:101], v[156:159], v[208:211], v[98:101]
	v_mfma_f32_16x16x32_bf16 v[102:105], v[134:137], v[208:211], v[102:105]
	s_setprio 0
	s_setprio 3
	v_mfma_f32_16x16x32_bf16 v[70:73], v[164:167], v[180:183], v[70:73]
	v_mfma_f32_16x16x32_bf16 v[66:69], v[172:175], v[180:183], v[66:69]
	v_mfma_f32_16x16x32_bf16 v[50:53], v[172:175], v[188:191], v[50:53]
	v_mfma_f32_16x16x32_bf16 v[54:57], v[164:167], v[188:191], v[54:57]
	v_mfma_f32_16x16x32_bf16 v[46:49], v[164:167], v[196:199], v[46:49]
	v_mfma_f32_16x16x32_bf16 v[42:45], v[172:175], v[196:199], v[42:45]
	v_mfma_f32_16x16x32_bf16 v[34:37], v[172:175], v[204:207], v[34:37]
	v_mfma_f32_16x16x32_bf16 v[38:41], v[164:167], v[204:207], v[38:41]
	v_mfma_f32_16x16x32_bf16 v[70:73], v[168:171], v[184:187], v[70:73]
	v_mfma_f32_16x16x32_bf16 v[66:69], v[176:179], v[184:187], v[66:69]
	v_mfma_f32_16x16x32_bf16 v[50:53], v[176:179], v[192:195], v[50:53]
	v_mfma_f32_16x16x32_bf16 v[54:57], v[168:171], v[192:195], v[54:57]
	v_mfma_f32_16x16x32_bf16 v[46:49], v[168:171], v[200:203], v[46:49]
	v_mfma_f32_16x16x32_bf16 v[42:45], v[176:179], v[200:203], v[42:45]
	v_mfma_f32_16x16x32_bf16 v[34:37], v[176:179], v[208:211], v[34:37]
	v_mfma_f32_16x16x32_bf16 v[38:41], v[168:171], v[208:211], v[38:41]
	s_setprio 0
	s_barrier
	s_mov_b32 m0, s82
	v_lshl_add_u64 v[214:215], s[54:55], 0, v[138:139]
	ds_read_b128 v[180:183], v163 offset:49152
	ds_read_b128 v[184:187], v163 offset:50176
	ds_read_b128 v[188:191], v163 offset:51200
	ds_read_b128 v[192:195], v163 offset:52224
	ds_read_b128 v[196:199], v163 offset:53248
	ds_read_b128 v[200:203], v163 offset:54272
	ds_read_b128 v[204:207], v163 offset:55296
	ds_read_b128 v[208:211], v163 offset:56320
	global_load_lds_dwordx4 v[214:215], off
	v_lshl_add_u64 v[214:215], s[54:55], 0, v[142:143]
	s_mov_b32 m0, s47
	v_lshl_add_u64 v[160:161], v[160:161], 0, s[24:25]
	global_load_lds_dwordx4 v[214:215], off
	v_lshl_add_u64 v[214:215], s[56:57], 0, v[138:139]
	s_mov_b32 m0, s81
	s_nop 0
	global_load_lds_dwordx4 v[214:215], off
	v_lshl_add_u64 v[214:215], s[56:57], 0, v[142:143]
	s_mov_b32 m0, s45
	s_nop 0
	global_load_lds_dwordx4 v[214:215], off
	s_mov_b32 m0, s75
	s_nop 0
	global_load_lds_dwordx4 v[160:161], off
	v_lshl_add_u64 v[160:161], v[212:213], 0, s[24:25]
	s_mov_b32 m0, s76
	s_nop 0
	global_load_lds_dwordx4 v[160:161], off
	s_waitcnt vmcnt(8)
	s_waitcnt lgkmcnt(0)
	s_barrier
	s_setprio 3
	s_waitcnt lgkmcnt(0)
	v_mfma_f32_16x16x32_bf16 v[94:97], v[130:133], v[180:183], v[94:97]
	v_mfma_f32_16x16x32_bf16 v[90:93], v[152:155], v[180:183], v[90:93]
	v_mfma_f32_16x16x32_bf16 v[82:85], v[152:155], v[188:191], v[82:85]
	v_mfma_f32_16x16x32_bf16 v[86:89], v[130:133], v[188:191], v[86:89]
	v_mfma_f32_16x16x32_bf16 v[78:81], v[130:133], v[196:199], v[78:81]
	v_mfma_f32_16x16x32_bf16 v[74:77], v[152:155], v[196:199], v[74:77]
	v_mfma_f32_16x16x32_bf16 v[58:61], v[152:155], v[204:207], v[58:61]
	v_mfma_f32_16x16x32_bf16 v[62:65], v[130:133], v[204:207], v[62:65]
	v_mfma_f32_16x16x32_bf16 v[94:97], v[134:137], v[184:187], v[94:97]
	v_mfma_f32_16x16x32_bf16 v[90:93], v[156:159], v[184:187], v[90:93]
	v_mfma_f32_16x16x32_bf16 v[82:85], v[156:159], v[192:195], v[82:85]
	v_mfma_f32_16x16x32_bf16 v[86:89], v[134:137], v[192:195], v[86:89]
	v_mfma_f32_16x16x32_bf16 v[78:81], v[134:137], v[200:203], v[78:81]
	v_mfma_f32_16x16x32_bf16 v[74:77], v[156:159], v[200:203], v[74:77]
	v_mfma_f32_16x16x32_bf16 v[58:61], v[156:159], v[208:211], v[58:61]
	v_mfma_f32_16x16x32_bf16 v[62:65], v[134:137], v[208:211], v[62:65]
	s_setprio 0
	s_setprio 3
	v_mfma_f32_16x16x32_bf16 v[30:33], v[164:167], v[180:183], v[30:33]
	v_mfma_f32_16x16x32_bf16 v[26:29], v[172:175], v[180:183], v[26:29]
	v_mfma_f32_16x16x32_bf16 v[18:21], v[172:175], v[188:191], v[18:21]
	v_mfma_f32_16x16x32_bf16 v[22:25], v[164:167], v[188:191], v[22:25]
	v_mfma_f32_16x16x32_bf16 v[14:17], v[164:167], v[196:199], v[14:17]
	v_mfma_f32_16x16x32_bf16 v[10:13], v[172:175], v[196:199], v[10:13]
	v_mfma_f32_16x16x32_bf16 v[2:5], v[172:175], v[204:207], v[2:5]
	v_mfma_f32_16x16x32_bf16 v[6:9], v[164:167], v[204:207], v[6:9]
	v_mfma_f32_16x16x32_bf16 v[30:33], v[168:171], v[184:187], v[30:33]
	v_mfma_f32_16x16x32_bf16 v[26:29], v[176:179], v[184:187], v[26:29]
	v_mfma_f32_16x16x32_bf16 v[18:21], v[176:179], v[192:195], v[18:21]
	v_mfma_f32_16x16x32_bf16 v[22:25], v[168:171], v[192:195], v[22:25]
	v_mfma_f32_16x16x32_bf16 v[14:17], v[168:171], v[200:203], v[14:17]
	v_mfma_f32_16x16x32_bf16 v[10:13], v[176:179], v[200:203], v[10:13]
	v_mfma_f32_16x16x32_bf16 v[2:5], v[176:179], v[208:211], v[2:5]
	v_mfma_f32_16x16x32_bf16 v[6:9], v[168:171], v[208:211], v[6:9]
	s_setprio 0
	s_barrier
	s_mov_b32 s45, 2
	s_andn2_b64 vcc, exec, s[0:1]
	s_mov_b64 s[54:55], -1
	s_mov_b64 s[0:1], 0
	s_cbranch_vccz .LBB0_1103
	s_and_b64 vcc, exec, s[42:43]
	s_cbranch_vccz .LBB0_1106
	s_barrier

.LBB0_1184:
	v_add_u32_e32 v142, s65, v1
	v_add_u32_e32 v176, s66, v1
	ds_read_b128 v[130:133], v142
	ds_read_b128 v[134:137], v142 offset:1024
	ds_read_b128 v[138:141], v142 offset:2048
	ds_read_b128 v[142:145], v142 offset:3072
	ds_read_b128 v[164:167], v176
	ds_read_b128 v[168:171], v176 offset:1024
	ds_read_b128 v[172:175], v176 offset:2048
	ds_read_b128 v[176:179], v176 offset:3072
	s_add_u32 s50, s0, 0xfffc0080
	s_addc_u32 s51, s1, -1
	s_cmp_eq_u32 s73, 12
	s_cselect_b32 s53, s7, s51
	s_cselect_b32 s52, s6, s50
	s_cselect_b32 s51, s47, s45
	s_cselect_b32 s50, s46, s43
	v_lshl_add_u64 v[212:213], s[0:1], 0, v[156:157]
	s_add_i32 m0, s57, 0xc000
	ds_read_b128 v[180:183], v147
	ds_read_b128 v[184:187], v147 offset:1024
	ds_read_b128 v[188:191], v147 offset:2048
	ds_read_b128 v[192:195], v147 offset:3072
	ds_read_b128 v[196:199], v147 offset:4096
	ds_read_b128 v[200:203], v147 offset:5120
	ds_read_b128 v[204:207], v147 offset:6144
	ds_read_b128 v[208:211], v147 offset:7168
	global_load_lds_dwordx4 v[212:213], off
	v_lshl_add_u64 v[212:213], s[0:1], 0, v[158:159]
	s_add_i32 m0, s57, 0xe000
	s_nop 0
	global_load_lds_dwordx4 v[212:213], off
	s_waitcnt vmcnt(8)
	s_waitcnt lgkmcnt(0)
	s_barrier
	s_setprio 3
	s_waitcnt lgkmcnt(0)
	v_mfma_f32_16x16x32_bf16 v[126:129], v[130:133], v[180:183], v[126:129]
	v_mfma_f32_16x16x32_bf16 v[122:125], v[138:141], v[180:183], v[122:125]
	v_mfma_f32_16x16x32_bf16 v[114:117], v[138:141], v[188:191], v[114:117]
	v_mfma_f32_16x16x32_bf16 v[118:121], v[130:133], v[188:191], v[118:121]
	v_mfma_f32_16x16x32_bf16 v[110:113], v[130:133], v[196:199], v[110:113]
	v_mfma_f32_16x16x32_bf16 v[106:109], v[138:141], v[196:199], v[106:109]
	v_mfma_f32_16x16x32_bf16 v[98:101], v[138:141], v[204:207], v[98:101]
	v_mfma_f32_16x16x32_bf16 v[102:105], v[130:133], v[204:207], v[102:105]
	v_mfma_f32_16x16x32_bf16 v[126:129], v[134:137], v[184:187], v[126:129]
	v_mfma_f32_16x16x32_bf16 v[122:125], v[142:145], v[184:187], v[122:125]
	v_mfma_f32_16x16x32_bf16 v[114:117], v[142:145], v[192:195], v[114:117]
	v_mfma_f32_16x16x32_bf16 v[118:121], v[134:137], v[192:195], v[118:121]
	v_mfma_f32_16x16x32_bf16 v[110:113], v[134:137], v[200:203], v[110:113]
	v_mfma_f32_16x16x32_bf16 v[106:109], v[142:145], v[200:203], v[106:109]
	v_mfma_f32_16x16x32_bf16 v[98:101], v[142:145], v[208:211], v[98:101]
	v_mfma_f32_16x16x32_bf16 v[102:105], v[134:137], v[208:211], v[102:105]
	s_setprio 0
	s_setprio 3
	v_mfma_f32_16x16x32_bf16 v[94:97], v[164:167], v[180:183], v[94:97]
	v_mfma_f32_16x16x32_bf16 v[90:93], v[172:175], v[180:183], v[90:93]
	v_mfma_f32_16x16x32_bf16 v[82:85], v[172:175], v[188:191], v[82:85]
	v_mfma_f32_16x16x32_bf16 v[86:89], v[164:167], v[188:191], v[86:89]
	v_mfma_f32_16x16x32_bf16 v[78:81], v[164:167], v[196:199], v[78:81]
	v_mfma_f32_16x16x32_bf16 v[74:77], v[172:175], v[196:199], v[74:77]
	v_mfma_f32_16x16x32_bf16 v[66:69], v[172:175], v[204:207], v[66:69]
	v_mfma_f32_16x16x32_bf16 v[70:73], v[164:167], v[204:207], v[70:73]
	v_mfma_f32_16x16x32_bf16 v[94:97], v[168:171], v[184:187], v[94:97]
	v_mfma_f32_16x16x32_bf16 v[90:93], v[176:179], v[184:187], v[90:93]
	v_mfma_f32_16x16x32_bf16 v[82:85], v[176:179], v[192:195], v[82:85]
	v_mfma_f32_16x16x32_bf16 v[86:89], v[168:171], v[192:195], v[86:89]
	v_mfma_f32_16x16x32_bf16 v[78:81], v[168:171], v[200:203], v[78:81]
	v_mfma_f32_16x16x32_bf16 v[74:77], v[176:179], v[200:203], v[74:77]
	v_mfma_f32_16x16x32_bf16 v[66:69], v[176:179], v[208:211], v[66:69]
	v_mfma_f32_16x16x32_bf16 v[70:73], v[168:171], v[208:211], v[70:73]
	s_setprio 0
	s_barrier
	s_add_i32 s74, s65, s56
	v_lshl_add_u64 v[212:213], s[50:51], 0, v[148:149]
	s_mov_b32 m0, s74
	ds_read_b128 v[180:183], v147 offset:16384
	ds_read_b128 v[184:187], v147 offset:17408
	ds_read_b128 v[188:191], v147 offset:18432
	ds_read_b128 v[192:195], v147 offset:19456
	ds_read_b128 v[196:199], v147 offset:20480
	ds_read_b128 v[200:203], v147 offset:21504
	ds_read_b128 v[204:207], v147 offset:22528
	ds_read_b128 v[208:211], v147 offset:23552
	global_load_lds_dwordx4 v[212:213], off
	s_add_i32 m0, s74, 0x2000
	s_add_u32 s74, s50, 0x40000
	v_lshl_add_u64 v[212:213], s[50:51], 0, v[152:153]
	s_addc_u32 s75, s51, 0
	s_add_i32 s76, s66, s56
	global_load_lds_dwordx4 v[212:213], off
	v_lshl_add_u64 v[212:213], s[74:75], 0, v[148:149]
	s_mov_b32 m0, s76
	v_lshl_add_u64 v[214:215], s[52:53], 0, v[154:155]
	global_load_lds_dwordx4 v[212:213], off
	v_lshl_add_u64 v[212:213], s[74:75], 0, v[152:153]
	s_add_i32 m0, s76, 0x2000
	s_nop 0
	global_load_lds_dwordx4 v[212:213], off
	v_lshl_add_u64 v[212:213], s[52:53], 0, v[150:151]
	s_mov_b32 m0, s57
	s_nop 0
	global_load_lds_dwordx4 v[212:213], off
	s_mov_b32 m0, s58
	s_nop 0
	global_load_lds_dwordx4 v[214:215], off
	s_waitcnt vmcnt(8)
	s_waitcnt lgkmcnt(0)
	s_barrier
	s_setprio 3
	s_waitcnt lgkmcnt(0)
	v_mfma_f32_16x16x32_bf16 v[62:65], v[130:133], v[180:183], v[62:65]
	v_mfma_f32_16x16x32_bf16 v[58:61], v[138:141], v[180:183], v[58:61]
	v_mfma_f32_16x16x32_bf16 v[50:53], v[138:141], v[188:191], v[50:53]
	v_mfma_f32_16x16x32_bf16 v[54:57], v[130:133], v[188:191], v[54:57]
	v_mfma_f32_16x16x32_bf16 v[46:49], v[130:133], v[196:199], v[46:49]
	v_mfma_f32_16x16x32_bf16 v[42:45], v[138:141], v[196:199], v[42:45]
	v_mfma_f32_16x16x32_bf16 v[34:37], v[138:141], v[204:207], v[34:37]
	v_mfma_f32_16x16x32_bf16 v[38:41], v[130:133], v[204:207], v[38:41]
	v_mfma_f32_16x16x32_bf16 v[62:65], v[134:137], v[184:187], v[62:65]
	v_mfma_f32_16x16x32_bf16 v[58:61], v[142:145], v[184:187], v[58:61]
	v_mfma_f32_16x16x32_bf16 v[50:53], v[142:145], v[192:195], v[50:53]
	v_mfma_f32_16x16x32_bf16 v[54:57], v[134:137], v[192:195], v[54:57]
	v_mfma_f32_16x16x32_bf16 v[46:49], v[134:137], v[200:203], v[46:49]
	v_mfma_f32_16x16x32_bf16 v[42:45], v[142:145], v[200:203], v[42:45]
	v_mfma_f32_16x16x32_bf16 v[34:37], v[142:145], v[208:211], v[34:37]
	v_mfma_f32_16x16x32_bf16 v[38:41], v[134:137], v[208:211], v[38:41]
	s_setprio 0
	s_setprio 3
	v_mfma_f32_16x16x32_bf16 v[30:33], v[164:167], v[180:183], v[30:33]
	v_mfma_f32_16x16x32_bf16 v[26:29], v[172:175], v[180:183], v[26:29]
	v_mfma_f32_16x16x32_bf16 v[18:21], v[172:175], v[188:191], v[18:21]
	v_mfma_f32_16x16x32_bf16 v[22:25], v[164:167], v[188:191], v[22:25]
	v_mfma_f32_16x16x32_bf16 v[14:17], v[164:167], v[196:199], v[14:17]
	v_mfma_f32_16x16x32_bf16 v[10:13], v[172:175], v[196:199], v[10:13]
	v_mfma_f32_16x16x32_bf16 v[2:5], v[172:175], v[204:207], v[2:5]
	v_mfma_f32_16x16x32_bf16 v[6:9], v[164:167], v[204:207], v[6:9]
	v_mfma_f32_16x16x32_bf16 v[30:33], v[168:171], v[184:187], v[30:33]
	v_mfma_f32_16x16x32_bf16 v[26:29], v[176:179], v[184:187], v[26:29]
	v_mfma_f32_16x16x32_bf16 v[18:21], v[176:179], v[192:195], v[18:21]
	v_mfma_f32_16x16x32_bf16 v[22:25], v[168:171], v[192:195], v[22:25]
	v_mfma_f32_16x16x32_bf16 v[14:17], v[168:171], v[200:203], v[14:17]
	v_mfma_f32_16x16x32_bf16 v[10:13], v[176:179], v[200:203], v[10:13]
	v_mfma_f32_16x16x32_bf16 v[2:5], v[176:179], v[208:211], v[2:5]
	v_mfma_f32_16x16x32_bf16 v[6:9], v[168:171], v[208:211], v[6:9]
	s_setprio 0
	s_barrier
	s_add_i32 s74, 0, 0x18000
	s_add_i32 s75, 0, 0x1c000
	v_add_u32_e32 v142, s74, v1
	v_add_u32_e32 v176, s75, v1
	ds_read_b128 v[130:133], v142
	ds_read_b128 v[134:137], v142 offset:1024
	ds_read_b128 v[138:141], v142 offset:2048
	ds_read_b128 v[142:145], v142 offset:3072
	ds_read_b128 v[164:167], v176
	ds_read_b128 v[168:171], v176 offset:1024
	ds_read_b128 v[172:175], v176 offset:2048
	ds_read_b128 v[176:179], v176 offset:3072
	s_add_u32 s52, s52, 0x40000
	s_addc_u32 s53, s53, 0
	s_mov_b32 m0, s59
	v_lshl_add_u64 v[216:217], s[52:53], 0, v[150:151]
	ds_read_b128 v[180:183], v147 offset:32768
	ds_read_b128 v[184:187], v147 offset:33792
	ds_read_b128 v[188:191], v147 offset:34816
	ds_read_b128 v[192:195], v147 offset:35840
	ds_read_b128 v[196:199], v147 offset:36864
	ds_read_b128 v[200:203], v147 offset:37888
	ds_read_b128 v[204:207], v147 offset:38912
	ds_read_b128 v[208:211], v147 offset:39936
	global_load_lds_dwordx4 v[216:217], off
	v_lshl_add_u64 v[216:217], s[52:53], 0, v[154:155]
	s_mov_b32 m0, s60
	s_nop 0
	global_load_lds_dwordx4 v[216:217], off
	s_waitcnt vmcnt(8)
	s_waitcnt lgkmcnt(0)
	s_barrier
	s_setprio 3
	s_waitcnt lgkmcnt(0)
	v_mfma_f32_16x16x32_bf16 v[126:129], v[130:133], v[180:183], v[126:129]
	v_mfma_f32_16x16x32_bf16 v[122:125], v[138:141], v[180:183], v[122:125]
	v_mfma_f32_16x16x32_bf16 v[114:117], v[138:141], v[188:191], v[114:117]
	v_mfma_f32_16x16x32_bf16 v[118:121], v[130:133], v[188:191], v[118:121]
	v_mfma_f32_16x16x32_bf16 v[110:113], v[130:133], v[196:199], v[110:113]
	v_mfma_f32_16x16x32_bf16 v[106:109], v[138:141], v[196:199], v[106:109]
	v_mfma_f32_16x16x32_bf16 v[98:101], v[138:141], v[204:207], v[98:101]
	v_mfma_f32_16x16x32_bf16 v[102:105], v[130:133], v[204:207], v[102:105]
	v_mfma_f32_16x16x32_bf16 v[126:129], v[134:137], v[184:187], v[126:129]
	v_mfma_f32_16x16x32_bf16 v[122:125], v[142:145], v[184:187], v[122:125]
	v_mfma_f32_16x16x32_bf16 v[114:117], v[142:145], v[192:195], v[114:117]
	v_mfma_f32_16x16x32_bf16 v[118:121], v[134:137], v[192:195], v[118:121]
	v_mfma_f32_16x16x32_bf16 v[110:113], v[134:137], v[200:203], v[110:113]
	v_mfma_f32_16x16x32_bf16 v[106:109], v[142:145], v[200:203], v[106:109]
	v_mfma_f32_16x16x32_bf16 v[98:101], v[142:145], v[208:211], v[98:101]
	v_mfma_f32_16x16x32_bf16 v[102:105], v[134:137], v[208:211], v[102:105]
	s_setprio 0
	s_setprio 3
	v_mfma_f32_16x16x32_bf16 v[94:97], v[164:167], v[180:183], v[94:97]
	v_mfma_f32_16x16x32_bf16 v[90:93], v[172:175], v[180:183], v[90:93]
	v_mfma_f32_16x16x32_bf16 v[82:85], v[172:175], v[188:191], v[82:85]
	v_mfma_f32_16x16x32_bf16 v[86:89], v[164:167], v[188:191], v[86:89]
	v_mfma_f32_16x16x32_bf16 v[78:81], v[164:167], v[196:199], v[78:81]
	v_mfma_f32_16x16x32_bf16 v[74:77], v[172:175], v[196:199], v[74:77]
	v_mfma_f32_16x16x32_bf16 v[66:69], v[172:175], v[204:207], v[66:69]
	v_mfma_f32_16x16x32_bf16 v[70:73], v[164:167], v[204:207], v[70:73]
	v_mfma_f32_16x16x32_bf16 v[94:97], v[168:171], v[184:187], v[94:97]
	v_mfma_f32_16x16x32_bf16 v[90:93], v[176:179], v[184:187], v[90:93]
	v_mfma_f32_16x16x32_bf16 v[82:85], v[176:179], v[192:195], v[82:85]
	v_mfma_f32_16x16x32_bf16 v[86:89], v[168:171], v[192:195], v[86:89]
	v_mfma_f32_16x16x32_bf16 v[78:81], v[168:171], v[200:203], v[78:81]
	v_mfma_f32_16x16x32_bf16 v[74:77], v[176:179], v[200:203], v[74:77]
	v_mfma_f32_16x16x32_bf16 v[66:69], v[176:179], v[208:211], v[66:69]
	v_mfma_f32_16x16x32_bf16 v[70:73], v[168:171], v[208:211], v[70:73]
	s_setprio 0
	s_barrier
	s_add_u32 s52, s50, 0x4000
	s_addc_u32 s53, s51, 0
	s_add_i32 s74, s74, s56
	v_lshl_add_u64 v[216:217], s[52:53], 0, v[148:149]
	s_mov_b32 m0, s74
	ds_read_b128 v[180:183], v147 offset:49152
	ds_read_b128 v[184:187], v147 offset:50176
	ds_read_b128 v[188:191], v147 offset:51200
	ds_read_b128 v[192:195], v147 offset:52224
	ds_read_b128 v[196:199], v147 offset:53248
	ds_read_b128 v[200:203], v147 offset:54272
	ds_read_b128 v[204:207], v147 offset:55296
	ds_read_b128 v[208:211], v147 offset:56320
	global_load_lds_dwordx4 v[216:217], off
	s_add_i32 m0, s74, 0x2000
	s_add_u32 s50, s50, 0x44000
	v_lshl_add_u64 v[216:217], s[52:53], 0, v[152:153]
	s_addc_u32 s51, s51, 0
	s_add_i32 s52, s75, s56
	global_load_lds_dwordx4 v[216:217], off
	v_lshl_add_u64 v[216:217], s[50:51], 0, v[148:149]
	s_mov_b32 m0, s52
	v_lshl_add_u64 v[212:213], v[212:213], 0, s[20:21]
	global_load_lds_dwordx4 v[216:217], off
	v_lshl_add_u64 v[216:217], s[50:51], 0, v[152:153]
	s_add_i32 m0, s52, 0x2000
	s_nop 0
	global_load_lds_dwordx4 v[216:217], off
	s_mov_b32 m0, s63
	s_nop 0
	global_load_lds_dwordx4 v[212:213], off
	v_lshl_add_u64 v[212:213], v[214:215], 0, s[20:21]
	s_mov_b32 m0, s64
	s_nop 0
	global_load_lds_dwordx4 v[212:213], off
	s_waitcnt vmcnt(8)
	s_waitcnt lgkmcnt(0)
	s_barrier
	s_setprio 3
	s_waitcnt lgkmcnt(0)
	v_mfma_f32_16x16x32_bf16 v[62:65], v[130:133], v[180:183], v[62:65]
	v_mfma_f32_16x16x32_bf16 v[58:61], v[138:141], v[180:183], v[58:61]
	v_mfma_f32_16x16x32_bf16 v[50:53], v[138:141], v[188:191], v[50:53]
	v_mfma_f32_16x16x32_bf16 v[54:57], v[130:133], v[188:191], v[54:57]
	v_mfma_f32_16x16x32_bf16 v[46:49], v[130:133], v[196:199], v[46:49]
	v_mfma_f32_16x16x32_bf16 v[42:45], v[138:141], v[196:199], v[42:45]
	v_mfma_f32_16x16x32_bf16 v[34:37], v[138:141], v[204:207], v[34:37]
	v_mfma_f32_16x16x32_bf16 v[38:41], v[130:133], v[204:207], v[38:41]
	v_mfma_f32_16x16x32_bf16 v[62:65], v[134:137], v[184:187], v[62:65]
	v_mfma_f32_16x16x32_bf16 v[58:61], v[142:145], v[184:187], v[58:61]
	v_mfma_f32_16x16x32_bf16 v[50:53], v[142:145], v[192:195], v[50:53]
	v_mfma_f32_16x16x32_bf16 v[54:57], v[134:137], v[192:195], v[54:57]
	v_mfma_f32_16x16x32_bf16 v[46:49], v[134:137], v[200:203], v[46:49]
	v_mfma_f32_16x16x32_bf16 v[42:45], v[142:145], v[200:203], v[42:45]
	v_mfma_f32_16x16x32_bf16 v[34:37], v[142:145], v[208:211], v[34:37]
	v_mfma_f32_16x16x32_bf16 v[38:41], v[134:137], v[208:211], v[38:41]
	s_setprio 0
	s_setprio 3
	v_mfma_f32_16x16x32_bf16 v[30:33], v[164:167], v[180:183], v[30:33]
	v_mfma_f32_16x16x32_bf16 v[26:29], v[172:175], v[180:183], v[26:29]
	v_mfma_f32_16x16x32_bf16 v[18:21], v[172:175], v[188:191], v[18:21]
	v_mfma_f32_16x16x32_bf16 v[22:25], v[164:167], v[188:191], v[22:25]
	v_mfma_f32_16x16x32_bf16 v[14:17], v[164:167], v[196:199], v[14:17]
	v_mfma_f32_16x16x32_bf16 v[10:13], v[172:175], v[196:199], v[10:13]
	v_mfma_f32_16x16x32_bf16 v[2:5], v[172:175], v[204:207], v[2:5]
	v_mfma_f32_16x16x32_bf16 v[6:9], v[164:167], v[204:207], v[6:9]
	v_mfma_f32_16x16x32_bf16 v[30:33], v[168:171], v[184:187], v[30:33]
	v_mfma_f32_16x16x32_bf16 v[26:29], v[176:179], v[184:187], v[26:29]
	v_mfma_f32_16x16x32_bf16 v[18:21], v[176:179], v[192:195], v[18:21]
	v_mfma_f32_16x16x32_bf16 v[22:25], v[168:171], v[192:195], v[22:25]
	v_mfma_f32_16x16x32_bf16 v[14:17], v[168:171], v[200:203], v[14:17]
	v_mfma_f32_16x16x32_bf16 v[10:13], v[176:179], v[200:203], v[10:13]
	v_mfma_f32_16x16x32_bf16 v[2:5], v[176:179], v[208:211], v[2:5]
	v_mfma_f32_16x16x32_bf16 v[6:9], v[168:171], v[208:211], v[6:9]
	s_setprio 0
	s_barrier
	s_add_i32 s73, s73, 2
	s_add_u32 s43, s43, 0x8000
	s_addc_u32 s45, s45, 0
	s_add_u32 s0, s0, 0x100
	s_addc_u32 s1, s1, 0
	s_cmp_gt_u32 s73, 13
	s_cbranch_scc0 .LBB0_1184
	s_and_b64 vcc, exec, s[24:25]
	s_cbranch_vccz .LBB0_1187
	s_barrier

.LBB0_1271:
	ds_read_b128 v[154:157], v151
	ds_read_b128 v[158:161], v151 offset:1024
	ds_read_b128 v[162:165], v151 offset:2048
	ds_read_b128 v[166:169], v151 offset:3072
	ds_read_b128 v[170:173], v152
	ds_read_b128 v[174:177], v152 offset:1024
	ds_read_b128 v[178:181], v152 offset:2048
	ds_read_b128 v[182:185], v152 offset:3072
	s_add_u32 s52, s0, 0xfff00080
	s_addc_u32 s53, s1, -1
	s_cmp_eq_u32 s73, 60
	s_cselect_b32 s55, s7, s53
	s_cselect_b32 s54, s6, s52
	s_cselect_b32 s53, s49, s47
	s_cselect_b32 s52, s48, s45
	v_lshl_add_u64 v[148:149], s[0:1], 0, v[138:139]
	s_add_i32 m0, s51, 0xc000
	ds_read_b128 v[186:189], v153
	ds_read_b128 v[190:193], v153 offset:1024
	ds_read_b128 v[194:197], v153 offset:2048
	ds_read_b128 v[198:201], v153 offset:3072
	ds_read_b128 v[202:205], v153 offset:4096
	ds_read_b128 v[206:209], v153 offset:5120
	ds_read_b128 v[210:213], v153 offset:6144
	ds_read_b128 v[214:217], v153 offset:7168
	global_load_lds_dwordx4 v[148:149], off
	v_lshl_add_u64 v[148:149], s[0:1], 0, v[140:141]
	s_add_i32 m0, s51, 0xe000
	s_nop 0
	global_load_lds_dwordx4 v[148:149], off
	s_waitcnt vmcnt(8)
	s_waitcnt lgkmcnt(0)
	s_barrier
	s_setprio 3
	s_waitcnt lgkmcnt(0)
	v_mfma_f32_16x16x32_bf16 v[126:129], v[154:157], v[186:189], v[126:129]
	v_mfma_f32_16x16x32_bf16 v[122:125], v[162:165], v[186:189], v[122:125]
	v_mfma_f32_16x16x32_bf16 v[110:113], v[162:165], v[194:197], v[110:113]
	v_mfma_f32_16x16x32_bf16 v[118:121], v[154:157], v[194:197], v[118:121]
	v_mfma_f32_16x16x32_bf16 v[102:105], v[154:157], v[202:205], v[102:105]
	v_mfma_f32_16x16x32_bf16 v[94:97], v[162:165], v[202:205], v[94:97]
	v_mfma_f32_16x16x32_bf16 v[78:81], v[162:165], v[210:213], v[78:81]
	v_mfma_f32_16x16x32_bf16 v[86:89], v[154:157], v[210:213], v[86:89]
	v_mfma_f32_16x16x32_bf16 v[126:129], v[158:161], v[190:193], v[126:129]
	v_mfma_f32_16x16x32_bf16 v[122:125], v[166:169], v[190:193], v[122:125]
	v_mfma_f32_16x16x32_bf16 v[110:113], v[166:169], v[198:201], v[110:113]
	v_mfma_f32_16x16x32_bf16 v[118:121], v[158:161], v[198:201], v[118:121]
	v_mfma_f32_16x16x32_bf16 v[102:105], v[158:161], v[206:209], v[102:105]
	v_mfma_f32_16x16x32_bf16 v[94:97], v[166:169], v[206:209], v[94:97]
	v_mfma_f32_16x16x32_bf16 v[78:81], v[166:169], v[214:217], v[78:81]
	v_mfma_f32_16x16x32_bf16 v[86:89], v[158:161], v[214:217], v[86:89]
	s_setprio 0
	s_setprio 3
	v_mfma_f32_16x16x32_bf16 v[114:117], v[170:173], v[186:189], v[114:117]
	v_mfma_f32_16x16x32_bf16 v[106:109], v[178:181], v[186:189], v[106:109]
	v_mfma_f32_16x16x32_bf16 v[90:93], v[178:181], v[194:197], v[90:93]
	v_mfma_f32_16x16x32_bf16 v[98:101], v[170:173], v[194:197], v[98:101]
	v_mfma_f32_16x16x32_bf16 v[82:85], v[170:173], v[202:205], v[82:85]
	v_mfma_f32_16x16x32_bf16 v[74:77], v[178:181], v[202:205], v[74:77]
	v_mfma_f32_16x16x32_bf16 v[66:69], v[178:181], v[210:213], v[66:69]
	v_mfma_f32_16x16x32_bf16 v[70:73], v[170:173], v[210:213], v[70:73]
	v_mfma_f32_16x16x32_bf16 v[114:117], v[174:177], v[190:193], v[114:117]
	v_mfma_f32_16x16x32_bf16 v[106:109], v[182:185], v[190:193], v[106:109]
	v_mfma_f32_16x16x32_bf16 v[90:93], v[182:185], v[198:201], v[90:93]
	v_mfma_f32_16x16x32_bf16 v[98:101], v[174:177], v[198:201], v[98:101]
	v_mfma_f32_16x16x32_bf16 v[82:85], v[174:177], v[206:209], v[82:85]
	v_mfma_f32_16x16x32_bf16 v[74:77], v[182:185], v[206:209], v[74:77]
	v_mfma_f32_16x16x32_bf16 v[66:69], v[182:185], v[214:217], v[66:69]
	v_mfma_f32_16x16x32_bf16 v[70:73], v[174:177], v[214:217], v[70:73]
	s_setprio 0
	s_barrier
	s_add_i32 s74, s66, s58
	v_lshl_add_u64 v[148:149], s[52:53], 0, v[130:131]
	s_mov_b32 m0, s74
	ds_read_b128 v[186:189], v153 offset:16384
	ds_read_b128 v[190:193], v153 offset:17408
	ds_read_b128 v[194:197], v153 offset:18432
	ds_read_b128 v[198:201], v153 offset:19456
	ds_read_b128 v[202:205], v153 offset:20480
	ds_read_b128 v[206:209], v153 offset:21504
	ds_read_b128 v[210:213], v153 offset:22528
	ds_read_b128 v[214:217], v153 offset:23552
	global_load_lds_dwordx4 v[148:149], off
	s_add_i32 m0, s74, 0x2000
	s_add_u32 s74, s52, 0x100000
	v_lshl_add_u64 v[148:149], s[52:53], 0, v[134:135]
	s_addc_u32 s75, s53, 0
	s_add_i32 s76, s67, s58
	global_load_lds_dwordx4 v[148:149], off
	v_lshl_add_u64 v[148:149], s[74:75], 0, v[130:131]
	s_mov_b32 m0, s76
	v_lshl_add_u64 v[218:219], s[54:55], 0, v[136:137]
	global_load_lds_dwordx4 v[148:149], off
	v_lshl_add_u64 v[148:149], s[74:75], 0, v[134:135]
	s_add_i32 m0, s76, 0x2000
	s_nop 0
	global_load_lds_dwordx4 v[148:149], off
	v_lshl_add_u64 v[148:149], s[54:55], 0, v[132:133]
	s_mov_b32 m0, s51
	s_nop 0
	global_load_lds_dwordx4 v[148:149], off
	s_mov_b32 m0, s59
	s_nop 0
	global_load_lds_dwordx4 v[218:219], off
	s_waitcnt vmcnt(8)
	s_waitcnt lgkmcnt(0)
	s_barrier
	s_setprio 3
	s_waitcnt lgkmcnt(0)
	v_mfma_f32_16x16x32_bf16 v[62:65], v[154:157], v[186:189], v[62:65]
	v_mfma_f32_16x16x32_bf16 v[58:61], v[162:165], v[186:189], v[58:61]
	v_mfma_f32_16x16x32_bf16 v[46:49], v[162:165], v[194:197], v[46:49]
	v_mfma_f32_16x16x32_bf16 v[54:57], v[154:157], v[194:197], v[54:57]
	v_mfma_f32_16x16x32_bf16 v[38:41], v[154:157], v[202:205], v[38:41]
	v_mfma_f32_16x16x32_bf16 v[30:33], v[162:165], v[202:205], v[30:33]
	v_mfma_f32_16x16x32_bf16 v[14:17], v[162:165], v[210:213], v[14:17]
	v_mfma_f32_16x16x32_bf16 v[22:25], v[154:157], v[210:213], v[22:25]
	v_mfma_f32_16x16x32_bf16 v[62:65], v[158:161], v[190:193], v[62:65]
	v_mfma_f32_16x16x32_bf16 v[58:61], v[166:169], v[190:193], v[58:61]
	v_mfma_f32_16x16x32_bf16 v[46:49], v[166:169], v[198:201], v[46:49]
	v_mfma_f32_16x16x32_bf16 v[54:57], v[158:161], v[198:201], v[54:57]
	v_mfma_f32_16x16x32_bf16 v[38:41], v[158:161], v[206:209], v[38:41]
	v_mfma_f32_16x16x32_bf16 v[30:33], v[166:169], v[206:209], v[30:33]
	v_mfma_f32_16x16x32_bf16 v[14:17], v[166:169], v[214:217], v[14:17]
	v_mfma_f32_16x16x32_bf16 v[22:25], v[158:161], v[214:217], v[22:25]
	s_setprio 0
	s_setprio 3
	v_mfma_f32_16x16x32_bf16 v[50:53], v[170:173], v[186:189], v[50:53]
	v_mfma_f32_16x16x32_bf16 v[42:45], v[178:181], v[186:189], v[42:45]
	v_mfma_f32_16x16x32_bf16 v[26:29], v[178:181], v[194:197], v[26:29]
	v_mfma_f32_16x16x32_bf16 v[34:37], v[170:173], v[194:197], v[34:37]
	v_mfma_f32_16x16x32_bf16 v[18:21], v[170:173], v[202:205], v[18:21]
	v_mfma_f32_16x16x32_bf16 v[10:13], v[178:181], v[202:205], v[10:13]
	v_mfma_f32_16x16x32_bf16 v[2:5], v[178:181], v[210:213], v[2:5]
	v_mfma_f32_16x16x32_bf16 v[6:9], v[170:173], v[210:213], v[6:9]
	v_mfma_f32_16x16x32_bf16 v[50:53], v[174:177], v[190:193], v[50:53]
	v_mfma_f32_16x16x32_bf16 v[42:45], v[182:185], v[190:193], v[42:45]
	v_mfma_f32_16x16x32_bf16 v[26:29], v[182:185], v[198:201], v[26:29]
	v_mfma_f32_16x16x32_bf16 v[34:37], v[174:177], v[198:201], v[34:37]
	v_mfma_f32_16x16x32_bf16 v[18:21], v[174:177], v[206:209], v[18:21]
	v_mfma_f32_16x16x32_bf16 v[10:13], v[182:185], v[206:209], v[10:13]
	v_mfma_f32_16x16x32_bf16 v[2:5], v[182:185], v[214:217], v[2:5]
	v_mfma_f32_16x16x32_bf16 v[6:9], v[174:177], v[214:217], v[6:9]
	s_setprio 0
	s_barrier
	s_add_i32 s74, 0, 0x18000
	s_add_i32 s75, 0, 0x1c000
	v_add_u32_e32 v166, s74, v147
	v_add_u32_e32 v182, s75, v147
	ds_read_b128 v[154:157], v166
	ds_read_b128 v[158:161], v166 offset:1024
	ds_read_b128 v[162:165], v166 offset:2048
	ds_read_b128 v[166:169], v166 offset:3072
	ds_read_b128 v[170:173], v182
	ds_read_b128 v[174:177], v182 offset:1024
	ds_read_b128 v[178:181], v182 offset:2048
	ds_read_b128 v[182:185], v182 offset:3072
	s_add_u32 s54, s54, 0x100000
	s_addc_u32 s55, s55, 0
	s_mov_b32 m0, s60
	v_lshl_add_u64 v[220:221], s[54:55], 0, v[132:133]
	ds_read_b128 v[186:189], v153 offset:32768
	ds_read_b128 v[190:193], v153 offset:33792
	ds_read_b128 v[194:197], v153 offset:34816
	ds_read_b128 v[198:201], v153 offset:35840
	ds_read_b128 v[202:205], v153 offset:36864
	ds_read_b128 v[206:209], v153 offset:37888
	ds_read_b128 v[210:213], v153 offset:38912
	ds_read_b128 v[214:217], v153 offset:39936
	global_load_lds_dwordx4 v[220:221], off
	v_lshl_add_u64 v[220:221], s[54:55], 0, v[136:137]
	s_mov_b32 m0, s61
	s_nop 0
	global_load_lds_dwordx4 v[220:221], off
	s_waitcnt vmcnt(8)
	s_waitcnt lgkmcnt(0)
	s_barrier
	s_setprio 3
	s_waitcnt lgkmcnt(0)
	v_mfma_f32_16x16x32_bf16 v[126:129], v[154:157], v[186:189], v[126:129]
	v_mfma_f32_16x16x32_bf16 v[122:125], v[162:165], v[186:189], v[122:125]
	v_mfma_f32_16x16x32_bf16 v[110:113], v[162:165], v[194:197], v[110:113]
	v_mfma_f32_16x16x32_bf16 v[118:121], v[154:157], v[194:197], v[118:121]
	v_mfma_f32_16x16x32_bf16 v[102:105], v[154:157], v[202:205], v[102:105]
	v_mfma_f32_16x16x32_bf16 v[94:97], v[162:165], v[202:205], v[94:97]
	v_mfma_f32_16x16x32_bf16 v[78:81], v[162:165], v[210:213], v[78:81]
	v_mfma_f32_16x16x32_bf16 v[86:89], v[154:157], v[210:213], v[86:89]
	v_mfma_f32_16x16x32_bf16 v[126:129], v[158:161], v[190:193], v[126:129]
	v_mfma_f32_16x16x32_bf16 v[122:125], v[166:169], v[190:193], v[122:125]
	v_mfma_f32_16x16x32_bf16 v[110:113], v[166:169], v[198:201], v[110:113]
	v_mfma_f32_16x16x32_bf16 v[118:121], v[158:161], v[198:201], v[118:121]
	v_mfma_f32_16x16x32_bf16 v[102:105], v[158:161], v[206:209], v[102:105]
	v_mfma_f32_16x16x32_bf16 v[94:97], v[166:169], v[206:209], v[94:97]
	v_mfma_f32_16x16x32_bf16 v[78:81], v[166:169], v[214:217], v[78:81]
	v_mfma_f32_16x16x32_bf16 v[86:89], v[158:161], v[214:217], v[86:89]
	s_setprio 0
	s_setprio 3
	v_mfma_f32_16x16x32_bf16 v[114:117], v[170:173], v[186:189], v[114:117]
	v_mfma_f32_16x16x32_bf16 v[106:109], v[178:181], v[186:189], v[106:109]
	v_mfma_f32_16x16x32_bf16 v[90:93], v[178:181], v[194:197], v[90:93]
	v_mfma_f32_16x16x32_bf16 v[98:101], v[170:173], v[194:197], v[98:101]
	v_mfma_f32_16x16x32_bf16 v[82:85], v[170:173], v[202:205], v[82:85]
	v_mfma_f32_16x16x32_bf16 v[74:77], v[178:181], v[202:205], v[74:77]
	v_mfma_f32_16x16x32_bf16 v[66:69], v[178:181], v[210:213], v[66:69]
	v_mfma_f32_16x16x32_bf16 v[70:73], v[170:173], v[210:213], v[70:73]
	v_mfma_f32_16x16x32_bf16 v[114:117], v[174:177], v[190:193], v[114:117]
	v_mfma_f32_16x16x32_bf16 v[106:109], v[182:185], v[190:193], v[106:109]
	v_mfma_f32_16x16x32_bf16 v[90:93], v[182:185], v[198:201], v[90:93]
	v_mfma_f32_16x16x32_bf16 v[98:101], v[174:177], v[198:201], v[98:101]
	v_mfma_f32_16x16x32_bf16 v[82:85], v[174:177], v[206:209], v[82:85]
	v_mfma_f32_16x16x32_bf16 v[74:77], v[182:185], v[206:209], v[74:77]
	v_mfma_f32_16x16x32_bf16 v[66:69], v[182:185], v[214:217], v[66:69]
	v_mfma_f32_16x16x32_bf16 v[70:73], v[174:177], v[214:217], v[70:73]
	s_setprio 0
	s_barrier
	s_add_u32 s54, s52, 0x4000
	s_addc_u32 s55, s53, 0
	s_add_i32 s74, s74, s58
	v_lshl_add_u64 v[220:221], s[54:55], 0, v[130:131]
	s_mov_b32 m0, s74
	ds_read_b128 v[186:189], v153 offset:49152
	ds_read_b128 v[190:193], v153 offset:50176
	ds_read_b128 v[194:197], v153 offset:51200
	ds_read_b128 v[198:201], v153 offset:52224
	ds_read_b128 v[202:205], v153 offset:53248
	ds_read_b128 v[206:209], v153 offset:54272
	ds_read_b128 v[210:213], v153 offset:55296
	ds_read_b128 v[214:217], v153 offset:56320
	global_load_lds_dwordx4 v[220:221], off
	s_add_i32 m0, s74, 0x2000
	s_add_u32 s52, s52, 0x104000
	v_lshl_add_u64 v[220:221], s[54:55], 0, v[134:135]
	s_addc_u32 s53, s53, 0
	s_add_i32 s54, s75, s58
	global_load_lds_dwordx4 v[220:221], off
	v_lshl_add_u64 v[220:221], s[52:53], 0, v[130:131]
	s_mov_b32 m0, s54
	v_lshl_add_u64 v[148:149], v[148:149], 0, s[18:19]
	global_load_lds_dwordx4 v[220:221], off
	v_lshl_add_u64 v[220:221], s[52:53], 0, v[134:135]
	s_add_i32 m0, s54, 0x2000
	s_nop 0
	global_load_lds_dwordx4 v[220:221], off
	s_mov_b32 m0, s63
	s_nop 0
	global_load_lds_dwordx4 v[148:149], off
	v_lshl_add_u64 v[148:149], v[218:219], 0, s[18:19]
	s_mov_b32 m0, s64
	s_nop 0
	global_load_lds_dwordx4 v[148:149], off
	s_waitcnt vmcnt(8)
	s_waitcnt lgkmcnt(0)
	s_barrier
	s_setprio 3
	s_waitcnt lgkmcnt(0)
	v_mfma_f32_16x16x32_bf16 v[62:65], v[154:157], v[186:189], v[62:65]
	v_mfma_f32_16x16x32_bf16 v[58:61], v[162:165], v[186:189], v[58:61]
	v_mfma_f32_16x16x32_bf16 v[46:49], v[162:165], v[194:197], v[46:49]
	v_mfma_f32_16x16x32_bf16 v[54:57], v[154:157], v[194:197], v[54:57]
	v_mfma_f32_16x16x32_bf16 v[38:41], v[154:157], v[202:205], v[38:41]
	v_mfma_f32_16x16x32_bf16 v[30:33], v[162:165], v[202:205], v[30:33]
	v_mfma_f32_16x16x32_bf16 v[14:17], v[162:165], v[210:213], v[14:17]
	v_mfma_f32_16x16x32_bf16 v[22:25], v[154:157], v[210:213], v[22:25]
	v_mfma_f32_16x16x32_bf16 v[62:65], v[158:161], v[190:193], v[62:65]
	v_mfma_f32_16x16x32_bf16 v[58:61], v[166:169], v[190:193], v[58:61]
	v_mfma_f32_16x16x32_bf16 v[46:49], v[166:169], v[198:201], v[46:49]
	v_mfma_f32_16x16x32_bf16 v[54:57], v[158:161], v[198:201], v[54:57]
	v_mfma_f32_16x16x32_bf16 v[38:41], v[158:161], v[206:209], v[38:41]
	v_mfma_f32_16x16x32_bf16 v[30:33], v[166:169], v[206:209], v[30:33]
	v_mfma_f32_16x16x32_bf16 v[14:17], v[166:169], v[214:217], v[14:17]
	v_mfma_f32_16x16x32_bf16 v[22:25], v[158:161], v[214:217], v[22:25]
	s_setprio 0
	s_setprio 3
	v_mfma_f32_16x16x32_bf16 v[50:53], v[170:173], v[186:189], v[50:53]
	v_mfma_f32_16x16x32_bf16 v[42:45], v[178:181], v[186:189], v[42:45]
	v_mfma_f32_16x16x32_bf16 v[26:29], v[178:181], v[194:197], v[26:29]
	v_mfma_f32_16x16x32_bf16 v[34:37], v[170:173], v[194:197], v[34:37]
	v_mfma_f32_16x16x32_bf16 v[18:21], v[170:173], v[202:205], v[18:21]
	v_mfma_f32_16x16x32_bf16 v[10:13], v[178:181], v[202:205], v[10:13]
	v_mfma_f32_16x16x32_bf16 v[2:5], v[178:181], v[210:213], v[2:5]
	v_mfma_f32_16x16x32_bf16 v[6:9], v[170:173], v[210:213], v[6:9]
	v_mfma_f32_16x16x32_bf16 v[50:53], v[174:177], v[190:193], v[50:53]
	v_mfma_f32_16x16x32_bf16 v[42:45], v[182:185], v[190:193], v[42:45]
	v_mfma_f32_16x16x32_bf16 v[26:29], v[182:185], v[198:201], v[26:29]
	v_mfma_f32_16x16x32_bf16 v[34:37], v[174:177], v[198:201], v[34:37]
	v_mfma_f32_16x16x32_bf16 v[18:21], v[174:177], v[206:209], v[18:21]
	v_mfma_f32_16x16x32_bf16 v[10:13], v[182:185], v[206:209], v[10:13]
	v_mfma_f32_16x16x32_bf16 v[2:5], v[182:185], v[214:217], v[2:5]
	v_mfma_f32_16x16x32_bf16 v[6:9], v[174:177], v[214:217], v[6:9]
	s_setprio 0
	s_barrier
	s_add_i32 s73, s73, 2
	s_add_u32 s45, s45, 0x8000
	s_addc_u32 s47, s47, 0
	s_add_u32 s0, s0, 0x100
	s_addc_u32 s1, s1, 0
	s_cmp_gt_u32 s73, 61
	s_cbranch_scc0 .LBB0_1271
	s_and_b64 vcc, exec, s[20:21]
	s_cbranch_vccz .LBB0_1274
	s_barrier

.LBB0_1427:
	v_add_u32_e32 v162, s74, v147
	v_add_u32_e32 v178, s75, v147
	ds_read_b128 v[148:151], v162
	ds_read_b128 v[152:155], v162 offset:1024
	ds_read_b128 v[158:161], v162 offset:2048
	ds_read_b128 v[162:165], v162 offset:3072
	ds_read_b128 v[166:169], v178
	ds_read_b128 v[170:173], v178 offset:1024
	ds_read_b128 v[174:177], v178 offset:2048
	ds_read_b128 v[178:181], v178 offset:3072
	s_add_u32 s49, s54, 0xfff80080
	s_addc_u32 s51, s55, -1
	s_and_b64 s[56:57], s[56:57], exec
	s_cselect_b32 s59, s17, s51
	s_cselect_b32 s58, s16, s49
	s_cselect_b32 s57, s11, s79
	s_cselect_b32 s56, s10, s78
	v_lshl_add_u64 v[214:215], s[54:55], 0, v[138:139]
	s_add_i32 m0, s53, 0xc000
	ds_read_b128 v[182:185], v157
	ds_read_b128 v[186:189], v157 offset:1024
	ds_read_b128 v[190:193], v157 offset:2048
	ds_read_b128 v[194:197], v157 offset:3072
	ds_read_b128 v[198:201], v157 offset:4096
	ds_read_b128 v[202:205], v157 offset:5120
	ds_read_b128 v[206:209], v157 offset:6144
	ds_read_b128 v[210:213], v157 offset:7168
	global_load_lds_dwordx4 v[214:215], off
	v_lshl_add_u64 v[214:215], s[54:55], 0, v[140:141]
	s_add_i32 m0, s53, 0xe000
	s_nop 0
	global_load_lds_dwordx4 v[214:215], off
	s_waitcnt vmcnt(8)
	s_waitcnt lgkmcnt(0)
	s_barrier
	s_setprio 3
	s_waitcnt lgkmcnt(0)
	v_mfma_i32_16x16x64_i8 v[126:129], v[148:151], v[182:185], v[126:129]
	v_mfma_i32_16x16x64_i8 v[118:121], v[158:161], v[182:185], v[118:121]
	v_mfma_i32_16x16x64_i8 v[102:105], v[158:161], v[190:193], v[102:105]
	v_mfma_i32_16x16x64_i8 v[110:113], v[148:151], v[190:193], v[110:113]
	v_mfma_i32_16x16x64_i8 v[94:97], v[148:151], v[198:201], v[94:97]
	v_mfma_i32_16x16x64_i8 v[86:89], v[158:161], v[198:201], v[86:89]
	v_mfma_i32_16x16x64_i8 v[70:73], v[158:161], v[206:209], v[70:73]
	v_mfma_i32_16x16x64_i8 v[78:81], v[148:151], v[206:209], v[78:81]
	v_mfma_i32_16x16x64_i8 v[126:129], v[152:155], v[186:189], v[126:129]
	v_mfma_i32_16x16x64_i8 v[118:121], v[162:165], v[186:189], v[118:121]
	v_mfma_i32_16x16x64_i8 v[102:105], v[162:165], v[194:197], v[102:105]
	v_mfma_i32_16x16x64_i8 v[110:113], v[152:155], v[194:197], v[110:113]
	v_mfma_i32_16x16x64_i8 v[94:97], v[152:155], v[202:205], v[94:97]
	v_mfma_i32_16x16x64_i8 v[86:89], v[162:165], v[202:205], v[86:89]
	v_mfma_i32_16x16x64_i8 v[70:73], v[162:165], v[210:213], v[70:73]
	v_mfma_i32_16x16x64_i8 v[78:81], v[152:155], v[210:213], v[78:81]
	s_setprio 0
	s_setprio 3
	v_mfma_i32_16x16x64_i8 v[122:125], v[166:169], v[182:185], v[122:125]
	v_mfma_i32_16x16x64_i8 v[114:117], v[174:177], v[182:185], v[114:117]
	v_mfma_i32_16x16x64_i8 v[98:101], v[174:177], v[190:193], v[98:101]
	v_mfma_i32_16x16x64_i8 v[106:109], v[166:169], v[190:193], v[106:109]
	v_mfma_i32_16x16x64_i8 v[90:93], v[166:169], v[198:201], v[90:93]
	v_mfma_i32_16x16x64_i8 v[82:85], v[174:177], v[198:201], v[82:85]
	v_mfma_i32_16x16x64_i8 v[66:69], v[174:177], v[206:209], v[66:69]
	v_mfma_i32_16x16x64_i8 v[74:77], v[166:169], v[206:209], v[74:77]
	v_mfma_i32_16x16x64_i8 v[122:125], v[170:173], v[186:189], v[122:125]
	v_mfma_i32_16x16x64_i8 v[114:117], v[178:181], v[186:189], v[114:117]
	v_mfma_i32_16x16x64_i8 v[98:101], v[178:181], v[194:197], v[98:101]
	v_mfma_i32_16x16x64_i8 v[106:109], v[170:173], v[194:197], v[106:109]
	v_mfma_i32_16x16x64_i8 v[90:93], v[170:173], v[202:205], v[90:93]
	v_mfma_i32_16x16x64_i8 v[82:85], v[178:181], v[202:205], v[82:85]
	v_mfma_i32_16x16x64_i8 v[66:69], v[178:181], v[210:213], v[66:69]
	v_mfma_i32_16x16x64_i8 v[74:77], v[170:173], v[210:213], v[74:77]
	s_setprio 0
	s_barrier
	s_add_i32 s49, s74, s61
	v_lshl_add_u64 v[214:215], s[56:57], 0, v[130:131]
	s_mov_b32 m0, s49
	ds_read_b128 v[182:185], v157 offset:16384
	ds_read_b128 v[186:189], v157 offset:17408
	ds_read_b128 v[190:193], v157 offset:18432
	ds_read_b128 v[194:197], v157 offset:19456
	ds_read_b128 v[198:201], v157 offset:20480
	ds_read_b128 v[202:205], v157 offset:21504
	ds_read_b128 v[206:209], v157 offset:22528
	ds_read_b128 v[210:213], v157 offset:23552
	global_load_lds_dwordx4 v[214:215], off
	s_add_i32 m0, s49, 0x2000
	s_add_u32 s82, s56, 0x80000
	v_lshl_add_u64 v[214:215], s[56:57], 0, v[132:133]
	s_addc_u32 s83, s57, 0
	s_add_i32 s49, s75, s61
	global_load_lds_dwordx4 v[214:215], off
	v_lshl_add_u64 v[214:215], s[82:83], 0, v[130:131]
	s_mov_b32 m0, s49
	v_lshl_add_u64 v[216:217], s[58:59], 0, v[134:135]
	global_load_lds_dwordx4 v[214:215], off
	v_lshl_add_u64 v[214:215], s[82:83], 0, v[132:133]
	s_add_i32 m0, s49, 0x2000
	s_nop 0
	global_load_lds_dwordx4 v[214:215], off
	v_lshl_add_u64 v[214:215], s[58:59], 0, v[136:137]
	s_mov_b32 m0, s53
	s_nop 0
	global_load_lds_dwordx4 v[214:215], off
	s_mov_b32 m0, s64
	s_nop 0
	global_load_lds_dwordx4 v[216:217], off
	s_waitcnt vmcnt(8)
	s_waitcnt lgkmcnt(0)
	s_barrier
	s_setprio 3
	s_waitcnt lgkmcnt(0)
	v_mfma_i32_16x16x64_i8 v[62:65], v[148:151], v[182:185], v[62:65]
	v_mfma_i32_16x16x64_i8 v[54:57], v[158:161], v[182:185], v[54:57]
	v_mfma_i32_16x16x64_i8 v[38:41], v[158:161], v[190:193], v[38:41]
	v_mfma_i32_16x16x64_i8 v[46:49], v[148:151], v[190:193], v[46:49]
	v_mfma_i32_16x16x64_i8 v[30:33], v[148:151], v[198:201], v[30:33]
	v_mfma_i32_16x16x64_i8 v[22:25], v[158:161], v[198:201], v[22:25]
	v_mfma_i32_16x16x64_i8 v[6:9], v[158:161], v[206:209], v[6:9]
	v_mfma_i32_16x16x64_i8 v[14:17], v[148:151], v[206:209], v[14:17]
	v_mfma_i32_16x16x64_i8 v[62:65], v[152:155], v[186:189], v[62:65]
	v_mfma_i32_16x16x64_i8 v[54:57], v[162:165], v[186:189], v[54:57]
	v_mfma_i32_16x16x64_i8 v[38:41], v[162:165], v[194:197], v[38:41]
	v_mfma_i32_16x16x64_i8 v[46:49], v[152:155], v[194:197], v[46:49]
	v_mfma_i32_16x16x64_i8 v[30:33], v[152:155], v[202:205], v[30:33]
	v_mfma_i32_16x16x64_i8 v[22:25], v[162:165], v[202:205], v[22:25]
	v_mfma_i32_16x16x64_i8 v[6:9], v[162:165], v[210:213], v[6:9]
	v_mfma_i32_16x16x64_i8 v[14:17], v[152:155], v[210:213], v[14:17]
	s_setprio 0
	s_setprio 3
	v_mfma_i32_16x16x64_i8 v[58:61], v[166:169], v[182:185], v[58:61]
	v_mfma_i32_16x16x64_i8 v[50:53], v[174:177], v[182:185], v[50:53]
	v_mfma_i32_16x16x64_i8 v[34:37], v[174:177], v[190:193], v[34:37]
	v_mfma_i32_16x16x64_i8 v[42:45], v[166:169], v[190:193], v[42:45]
	v_mfma_i32_16x16x64_i8 v[26:29], v[166:169], v[198:201], v[26:29]
	v_mfma_i32_16x16x64_i8 v[18:21], v[174:177], v[198:201], v[18:21]
	v_mfma_i32_16x16x64_i8 v[2:5], v[174:177], v[206:209], v[2:5]
	v_mfma_i32_16x16x64_i8 v[10:13], v[166:169], v[206:209], v[10:13]
	v_mfma_i32_16x16x64_i8 v[58:61], v[170:173], v[186:189], v[58:61]
	v_mfma_i32_16x16x64_i8 v[50:53], v[178:181], v[186:189], v[50:53]
	v_mfma_i32_16x16x64_i8 v[34:37], v[178:181], v[194:197], v[34:37]
	v_mfma_i32_16x16x64_i8 v[42:45], v[170:173], v[194:197], v[42:45]
	v_mfma_i32_16x16x64_i8 v[26:29], v[170:173], v[202:205], v[26:29]
	v_mfma_i32_16x16x64_i8 v[18:21], v[178:181], v[202:205], v[18:21]
	v_mfma_i32_16x16x64_i8 v[2:5], v[178:181], v[210:213], v[2:5]
	v_mfma_i32_16x16x64_i8 v[10:13], v[170:173], v[210:213], v[10:13]
	s_setprio 0
	s_barrier
	s_add_i32 s49, 0, 0x18000
	s_add_i32 s51, 0, 0x1c000
	v_add_u32_e32 v162, s49, v147
	v_add_u32_e32 v178, s51, v147
	ds_read_b128 v[148:151], v162
	ds_read_b128 v[152:155], v162 offset:1024
	ds_read_b128 v[158:161], v162 offset:2048
	ds_read_b128 v[162:165], v162 offset:3072
	ds_read_b128 v[166:169], v178
	ds_read_b128 v[170:173], v178 offset:1024
	ds_read_b128 v[174:177], v178 offset:2048
	ds_read_b128 v[178:181], v178 offset:3072
	s_add_u32 s58, s58, 0x80000
	s_addc_u32 s59, s59, 0
	s_mov_b32 m0, s65
	v_lshl_add_u64 v[218:219], s[58:59], 0, v[136:137]
	ds_read_b128 v[182:185], v157 offset:32768
	ds_read_b128 v[186:189], v157 offset:33792
	ds_read_b128 v[190:193], v157 offset:34816
	ds_read_b128 v[194:197], v157 offset:35840
	ds_read_b128 v[198:201], v157 offset:36864
	ds_read_b128 v[202:205], v157 offset:37888
	ds_read_b128 v[206:209], v157 offset:38912
	ds_read_b128 v[210:213], v157 offset:39936
	global_load_lds_dwordx4 v[218:219], off
	v_lshl_add_u64 v[218:219], s[58:59], 0, v[134:135]
	s_mov_b32 m0, s66
	s_nop 0
	global_load_lds_dwordx4 v[218:219], off
	s_waitcnt vmcnt(8)
	s_waitcnt lgkmcnt(0)
	s_barrier
	s_setprio 3
	s_waitcnt lgkmcnt(0)
	v_mfma_i32_16x16x64_i8 v[126:129], v[148:151], v[182:185], v[126:129]
	v_mfma_i32_16x16x64_i8 v[118:121], v[158:161], v[182:185], v[118:121]
	v_mfma_i32_16x16x64_i8 v[102:105], v[158:161], v[190:193], v[102:105]
	v_mfma_i32_16x16x64_i8 v[110:113], v[148:151], v[190:193], v[110:113]
	v_mfma_i32_16x16x64_i8 v[94:97], v[148:151], v[198:201], v[94:97]
	v_mfma_i32_16x16x64_i8 v[86:89], v[158:161], v[198:201], v[86:89]
	v_mfma_i32_16x16x64_i8 v[70:73], v[158:161], v[206:209], v[70:73]
	v_mfma_i32_16x16x64_i8 v[78:81], v[148:151], v[206:209], v[78:81]
	v_mfma_i32_16x16x64_i8 v[126:129], v[152:155], v[186:189], v[126:129]
	v_mfma_i32_16x16x64_i8 v[118:121], v[162:165], v[186:189], v[118:121]
	v_mfma_i32_16x16x64_i8 v[102:105], v[162:165], v[194:197], v[102:105]
	v_mfma_i32_16x16x64_i8 v[110:113], v[152:155], v[194:197], v[110:113]
	v_mfma_i32_16x16x64_i8 v[94:97], v[152:155], v[202:205], v[94:97]
	v_mfma_i32_16x16x64_i8 v[86:89], v[162:165], v[202:205], v[86:89]
	v_mfma_i32_16x16x64_i8 v[70:73], v[162:165], v[210:213], v[70:73]
	v_mfma_i32_16x16x64_i8 v[78:81], v[152:155], v[210:213], v[78:81]
	s_setprio 0
	s_setprio 3
	v_mfma_i32_16x16x64_i8 v[122:125], v[166:169], v[182:185], v[122:125]
	v_mfma_i32_16x16x64_i8 v[114:117], v[174:177], v[182:185], v[114:117]
	v_mfma_i32_16x16x64_i8 v[98:101], v[174:177], v[190:193], v[98:101]
	v_mfma_i32_16x16x64_i8 v[106:109], v[166:169], v[190:193], v[106:109]
	v_mfma_i32_16x16x64_i8 v[90:93], v[166:169], v[198:201], v[90:93]
	v_mfma_i32_16x16x64_i8 v[82:85], v[174:177], v[198:201], v[82:85]
	v_mfma_i32_16x16x64_i8 v[66:69], v[174:177], v[206:209], v[66:69]
	v_mfma_i32_16x16x64_i8 v[74:77], v[166:169], v[206:209], v[74:77]
	v_mfma_i32_16x16x64_i8 v[122:125], v[170:173], v[186:189], v[122:125]
	v_mfma_i32_16x16x64_i8 v[114:117], v[178:181], v[186:189], v[114:117]
	v_mfma_i32_16x16x64_i8 v[98:101], v[178:181], v[194:197], v[98:101]
	v_mfma_i32_16x16x64_i8 v[106:109], v[170:173], v[194:197], v[106:109]
	v_mfma_i32_16x16x64_i8 v[90:93], v[170:173], v[202:205], v[90:93]
	v_mfma_i32_16x16x64_i8 v[82:85], v[178:181], v[202:205], v[82:85]
	v_mfma_i32_16x16x64_i8 v[66:69], v[178:181], v[210:213], v[66:69]
	v_mfma_i32_16x16x64_i8 v[74:77], v[170:173], v[210:213], v[74:77]
	s_setprio 0
	s_barrier
	s_add_u32 s58, s56, 0x4000
	s_addc_u32 s59, s57, 0
	s_add_i32 s49, s49, s61
	v_lshl_add_u64 v[218:219], s[58:59], 0, v[130:131]
	s_mov_b32 m0, s49
	ds_read_b128 v[182:185], v157 offset:49152
	ds_read_b128 v[186:189], v157 offset:50176
	ds_read_b128 v[190:193], v157 offset:51200
	ds_read_b128 v[194:197], v157 offset:52224
	ds_read_b128 v[198:201], v157 offset:53248
	ds_read_b128 v[202:205], v157 offset:54272
	ds_read_b128 v[206:209], v157 offset:55296
	ds_read_b128 v[210:213], v157 offset:56320
	global_load_lds_dwordx4 v[218:219], off
	s_add_i32 m0, s49, 0x2000
	s_add_u32 s56, s56, 0x84000
	v_lshl_add_u64 v[218:219], s[58:59], 0, v[132:133]
	s_addc_u32 s57, s57, 0
	s_add_i32 s49, s51, s61
	global_load_lds_dwordx4 v[218:219], off
	v_lshl_add_u64 v[218:219], s[56:57], 0, v[130:131]
	s_mov_b32 m0, s49
	v_lshl_add_u64 v[214:215], v[214:215], 0, s[42:43]
	global_load_lds_dwordx4 v[218:219], off
	v_lshl_add_u64 v[218:219], s[56:57], 0, v[132:133]
	s_add_i32 m0, s49, 0x2000
	s_nop 0
	global_load_lds_dwordx4 v[218:219], off
	s_mov_b32 m0, s70
	s_nop 0
	global_load_lds_dwordx4 v[214:215], off
	v_lshl_add_u64 v[214:215], v[216:217], 0, s[42:43]
	s_mov_b32 m0, s71
	s_nop 0
	global_load_lds_dwordx4 v[214:215], off
	s_waitcnt vmcnt(8)
	s_waitcnt lgkmcnt(0)
	s_barrier
	s_setprio 3
	s_waitcnt lgkmcnt(0)
	v_mfma_i32_16x16x64_i8 v[62:65], v[148:151], v[182:185], v[62:65]
	v_mfma_i32_16x16x64_i8 v[54:57], v[158:161], v[182:185], v[54:57]
	v_mfma_i32_16x16x64_i8 v[38:41], v[158:161], v[190:193], v[38:41]
	v_mfma_i32_16x16x64_i8 v[46:49], v[148:151], v[190:193], v[46:49]
	v_mfma_i32_16x16x64_i8 v[30:33], v[148:151], v[198:201], v[30:33]
	v_mfma_i32_16x16x64_i8 v[22:25], v[158:161], v[198:201], v[22:25]
	v_mfma_i32_16x16x64_i8 v[6:9], v[158:161], v[206:209], v[6:9]
	v_mfma_i32_16x16x64_i8 v[14:17], v[148:151], v[206:209], v[14:17]
	v_mfma_i32_16x16x64_i8 v[62:65], v[152:155], v[186:189], v[62:65]
	v_mfma_i32_16x16x64_i8 v[54:57], v[162:165], v[186:189], v[54:57]
	v_mfma_i32_16x16x64_i8 v[38:41], v[162:165], v[194:197], v[38:41]
	v_mfma_i32_16x16x64_i8 v[46:49], v[152:155], v[194:197], v[46:49]
	v_mfma_i32_16x16x64_i8 v[30:33], v[152:155], v[202:205], v[30:33]
	v_mfma_i32_16x16x64_i8 v[22:25], v[162:165], v[202:205], v[22:25]
	v_mfma_i32_16x16x64_i8 v[6:9], v[162:165], v[210:213], v[6:9]
	v_mfma_i32_16x16x64_i8 v[14:17], v[152:155], v[210:213], v[14:17]
	s_setprio 0
	s_setprio 3
	v_mfma_i32_16x16x64_i8 v[58:61], v[166:169], v[182:185], v[58:61]
	v_mfma_i32_16x16x64_i8 v[50:53], v[174:177], v[182:185], v[50:53]
	v_mfma_i32_16x16x64_i8 v[34:37], v[174:177], v[190:193], v[34:37]
	v_mfma_i32_16x16x64_i8 v[42:45], v[166:169], v[190:193], v[42:45]
	v_mfma_i32_16x16x64_i8 v[26:29], v[166:169], v[198:201], v[26:29]
	v_mfma_i32_16x16x64_i8 v[18:21], v[174:177], v[198:201], v[18:21]
	v_mfma_i32_16x16x64_i8 v[2:5], v[174:177], v[206:209], v[2:5]
	v_mfma_i32_16x16x64_i8 v[10:13], v[166:169], v[206:209], v[10:13]
	v_mfma_i32_16x16x64_i8 v[58:61], v[170:173], v[186:189], v[58:61]
	v_mfma_i32_16x16x64_i8 v[50:53], v[178:181], v[186:189], v[50:53]
	v_mfma_i32_16x16x64_i8 v[34:37], v[178:181], v[194:197], v[34:37]
	v_mfma_i32_16x16x64_i8 v[42:45], v[170:173], v[194:197], v[42:45]
	v_mfma_i32_16x16x64_i8 v[26:29], v[170:173], v[202:205], v[26:29]
	v_mfma_i32_16x16x64_i8 v[18:21], v[178:181], v[202:205], v[18:21]
	v_mfma_i32_16x16x64_i8 v[2:5], v[178:181], v[210:213], v[2:5]
	v_mfma_i32_16x16x64_i8 v[10:13], v[170:173], v[210:213], v[10:13]
	s_setprio 0
	s_barrier
	s_add_i32 s80, s80, 2
	s_add_u32 s78, s78, 0x8000
	s_addc_u32 s79, s79, 0
	s_add_u32 s54, s54, 0x100
	s_addc_u32 s55, s55, 0
	s_cmp_gt_u32 s80, 29
	s_cbranch_scc1 .LBB0_1433

.LBB0_1600:
	ds_read_b128 v[146:149], v156
	ds_read_b128 v[150:153], v156 offset:1024
	ds_read_b128 v[160:163], v156 offset:2048
	ds_read_b128 v[164:167], v156 offset:3072
	ds_read_b128 v[168:171], v157
	ds_read_b128 v[172:175], v157 offset:1024
	ds_read_b128 v[176:179], v157 offset:2048
	ds_read_b128 v[180:183], v157 offset:3072
	s_add_u32 s42, s0, 0x100
	s_addc_u32 s43, s1, 0
	s_cmpk_eq_i32 s70, 0x52
	s_cselect_b32 s47, s7, s43
	s_cselect_b32 s46, s6, s42
	s_cselect_b32 s45, s41, s69
	s_cselect_b32 s44, s40, s68
	v_lshl_add_u64 v[216:217], s[0:1], 0, v[138:139]
	s_add_i32 m0, s49, 0xc000
	ds_read_b128 v[184:187], v158
	ds_read_b128 v[188:191], v158 offset:1024
	ds_read_b128 v[192:195], v158 offset:2048
	ds_read_b128 v[196:199], v158 offset:3072
	ds_read_b128 v[200:203], v158 offset:4096
	ds_read_b128 v[204:207], v158 offset:5120
	ds_read_b128 v[208:211], v158 offset:6144
	ds_read_b128 v[212:215], v158 offset:7168
	global_load_lds_dwordx4 v[216:217], off
	v_lshl_add_u64 v[216:217], s[0:1], 0, v[140:141]
	s_add_i32 m0, s49, 0xe000
	s_nop 0
	global_load_lds_dwordx4 v[216:217], off
	s_waitcnt vmcnt(8)
	s_waitcnt lgkmcnt(0)
	s_barrier
	s_setprio 3
	s_waitcnt lgkmcnt(0)
	v_mfma_i32_16x16x64_i8 v[126:129], v[146:149], v[184:187], v[126:129]
	v_mfma_i32_16x16x64_i8 v[122:125], v[160:163], v[184:187], v[122:125]
	v_mfma_i32_16x16x64_i8 v[114:117], v[160:163], v[192:195], v[114:117]
	v_mfma_i32_16x16x64_i8 v[118:121], v[146:149], v[192:195], v[118:121]
	v_mfma_i32_16x16x64_i8 v[110:113], v[146:149], v[200:203], v[110:113]
	v_mfma_i32_16x16x64_i8 v[106:109], v[160:163], v[200:203], v[106:109]
	v_mfma_i32_16x16x64_i8 v[98:101], v[160:163], v[208:211], v[98:101]
	v_mfma_i32_16x16x64_i8 v[102:105], v[146:149], v[208:211], v[102:105]
	v_mfma_i32_16x16x64_i8 v[126:129], v[150:153], v[188:191], v[126:129]
	v_mfma_i32_16x16x64_i8 v[122:125], v[164:167], v[188:191], v[122:125]
	v_mfma_i32_16x16x64_i8 v[114:117], v[164:167], v[196:199], v[114:117]
	v_mfma_i32_16x16x64_i8 v[118:121], v[150:153], v[196:199], v[118:121]
	v_mfma_i32_16x16x64_i8 v[110:113], v[150:153], v[204:207], v[110:113]
	v_mfma_i32_16x16x64_i8 v[106:109], v[164:167], v[204:207], v[106:109]
	v_mfma_i32_16x16x64_i8 v[98:101], v[164:167], v[212:215], v[98:101]
	v_mfma_i32_16x16x64_i8 v[102:105], v[150:153], v[212:215], v[102:105]
	s_setprio 0
	s_setprio 3
	v_mfma_i32_16x16x64_i8 v[62:65], v[168:171], v[184:187], v[62:65]
	v_mfma_i32_16x16x64_i8 v[58:61], v[176:179], v[184:187], v[58:61]
	v_mfma_i32_16x16x64_i8 v[50:53], v[176:179], v[192:195], v[50:53]
	v_mfma_i32_16x16x64_i8 v[54:57], v[168:171], v[192:195], v[54:57]
	v_mfma_i32_16x16x64_i8 v[46:49], v[168:171], v[200:203], v[46:49]
	v_mfma_i32_16x16x64_i8 v[42:45], v[176:179], v[200:203], v[42:45]
	v_mfma_i32_16x16x64_i8 v[34:37], v[176:179], v[208:211], v[34:37]
	v_mfma_i32_16x16x64_i8 v[38:41], v[168:171], v[208:211], v[38:41]
	v_mfma_i32_16x16x64_i8 v[62:65], v[172:175], v[188:191], v[62:65]
	v_mfma_i32_16x16x64_i8 v[58:61], v[180:183], v[188:191], v[58:61]
	v_mfma_i32_16x16x64_i8 v[50:53], v[180:183], v[196:199], v[50:53]
	v_mfma_i32_16x16x64_i8 v[54:57], v[172:175], v[196:199], v[54:57]
	v_mfma_i32_16x16x64_i8 v[46:49], v[172:175], v[204:207], v[46:49]
	v_mfma_i32_16x16x64_i8 v[42:45], v[180:183], v[204:207], v[42:45]
	v_mfma_i32_16x16x64_i8 v[34:37], v[180:183], v[212:215], v[34:37]
	v_mfma_i32_16x16x64_i8 v[38:41], v[172:175], v[212:215], v[38:41]
	s_setprio 0
	s_barrier
	s_add_i32 s0, s57, s48
	v_lshl_add_u64 v[216:217], s[44:45], 0, v[130:131]
	s_mov_b32 m0, s0
	ds_read_b128 v[184:187], v158 offset:16384
	ds_read_b128 v[188:191], v158 offset:17408
	ds_read_b128 v[192:195], v158 offset:18432
	ds_read_b128 v[196:199], v158 offset:19456
	ds_read_b128 v[200:203], v158 offset:20480
	ds_read_b128 v[204:207], v158 offset:21504
	ds_read_b128 v[208:211], v158 offset:22528
	ds_read_b128 v[212:215], v158 offset:23552
	global_load_lds_dwordx4 v[216:217], off
	s_add_i32 m0, s0, 0x2000
	s_add_u32 s0, s44, 0x158000
	v_lshl_add_u64 v[216:217], s[44:45], 0, v[134:135]
	s_addc_u32 s1, s45, 0
	s_add_i32 s71, s58, s48
	global_load_lds_dwordx4 v[216:217], off
	v_lshl_add_u64 v[216:217], s[0:1], 0, v[130:131]
	s_mov_b32 m0, s71
	v_lshl_add_u64 v[218:219], s[46:47], 0, v[136:137]
	global_load_lds_dwordx4 v[216:217], off
	v_lshl_add_u64 v[216:217], s[0:1], 0, v[134:135]
	s_add_i32 m0, s71, 0x2000
	s_nop 0
	global_load_lds_dwordx4 v[216:217], off
	v_lshl_add_u64 v[216:217], s[46:47], 0, v[132:133]
	s_mov_b32 m0, s49
	s_nop 0
	global_load_lds_dwordx4 v[216:217], off
	s_mov_b32 m0, s50
	s_nop 0
	global_load_lds_dwordx4 v[218:219], off
	s_waitcnt vmcnt(8)
	s_waitcnt lgkmcnt(0)
	s_barrier
	s_setprio 3
	s_waitcnt lgkmcnt(0)
	v_mfma_i32_16x16x64_i8 v[94:97], v[146:149], v[184:187], v[94:97]
	v_mfma_i32_16x16x64_i8 v[90:93], v[160:163], v[184:187], v[90:93]
	v_mfma_i32_16x16x64_i8 v[82:85], v[160:163], v[192:195], v[82:85]
	v_mfma_i32_16x16x64_i8 v[86:89], v[146:149], v[192:195], v[86:89]
	v_mfma_i32_16x16x64_i8 v[78:81], v[146:149], v[200:203], v[78:81]
	v_mfma_i32_16x16x64_i8 v[74:77], v[160:163], v[200:203], v[74:77]
	v_mfma_i32_16x16x64_i8 v[66:69], v[160:163], v[208:211], v[66:69]
	v_mfma_i32_16x16x64_i8 v[70:73], v[146:149], v[208:211], v[70:73]
	v_mfma_i32_16x16x64_i8 v[94:97], v[150:153], v[188:191], v[94:97]
	v_mfma_i32_16x16x64_i8 v[90:93], v[164:167], v[188:191], v[90:93]
	v_mfma_i32_16x16x64_i8 v[82:85], v[164:167], v[196:199], v[82:85]
	v_mfma_i32_16x16x64_i8 v[86:89], v[150:153], v[196:199], v[86:89]
	v_mfma_i32_16x16x64_i8 v[78:81], v[150:153], v[204:207], v[78:81]
	v_mfma_i32_16x16x64_i8 v[74:77], v[164:167], v[204:207], v[74:77]
	v_mfma_i32_16x16x64_i8 v[66:69], v[164:167], v[212:215], v[66:69]
	v_mfma_i32_16x16x64_i8 v[70:73], v[150:153], v[212:215], v[70:73]
	s_setprio 0
	s_setprio 3
	v_mfma_i32_16x16x64_i8 v[30:33], v[168:171], v[184:187], v[30:33]
	v_mfma_i32_16x16x64_i8 v[26:29], v[176:179], v[184:187], v[26:29]
	v_mfma_i32_16x16x64_i8 v[18:21], v[176:179], v[192:195], v[18:21]
	v_mfma_i32_16x16x64_i8 v[22:25], v[168:171], v[192:195], v[22:25]
	v_mfma_i32_16x16x64_i8 v[14:17], v[168:171], v[200:203], v[14:17]
	v_mfma_i32_16x16x64_i8 v[10:13], v[176:179], v[200:203], v[10:13]
	v_mfma_i32_16x16x64_i8 v[2:5], v[176:179], v[208:211], v[2:5]
	v_mfma_i32_16x16x64_i8 v[6:9], v[168:171], v[208:211], v[6:9]
	v_mfma_i32_16x16x64_i8 v[30:33], v[172:175], v[188:191], v[30:33]
	v_mfma_i32_16x16x64_i8 v[26:29], v[180:183], v[188:191], v[26:29]
	v_mfma_i32_16x16x64_i8 v[18:21], v[180:183], v[196:199], v[18:21]
	v_mfma_i32_16x16x64_i8 v[22:25], v[172:175], v[196:199], v[22:25]
	v_mfma_i32_16x16x64_i8 v[14:17], v[172:175], v[204:207], v[14:17]
	v_mfma_i32_16x16x64_i8 v[10:13], v[180:183], v[204:207], v[10:13]
	v_mfma_i32_16x16x64_i8 v[2:5], v[180:183], v[212:215], v[2:5]
	v_mfma_i32_16x16x64_i8 v[6:9], v[172:175], v[212:215], v[6:9]
	s_setprio 0
	s_barrier
	s_add_i32 s71, 0, 0x18000
	v_add_u32_e32 v159, s71, v154
	s_add_i32 s72, 0, 0x1c000
	ds_read_b128 v[146:149], v159
	ds_read_b128 v[150:153], v159 offset:1024
	ds_read_b128 v[160:163], v159 offset:2048
	ds_read_b128 v[164:167], v159 offset:3072
	v_add_u32_e32 v159, s72, v154
	ds_read_b128 v[168:171], v159
	ds_read_b128 v[172:175], v159 offset:1024
	ds_read_b128 v[176:179], v159 offset:2048
	ds_read_b128 v[180:183], v159 offset:3072
	s_add_u32 s0, s46, 0x158000
	s_addc_u32 s1, s47, 0
	s_mov_b32 m0, s51
	v_lshl_add_u64 v[220:221], s[0:1], 0, v[132:133]
	ds_read_b128 v[184:187], v158 offset:32768
	ds_read_b128 v[188:191], v158 offset:33792
	ds_read_b128 v[192:195], v158 offset:34816
	ds_read_b128 v[196:199], v158 offset:35840
	ds_read_b128 v[200:203], v158 offset:36864
	ds_read_b128 v[204:207], v158 offset:37888
	ds_read_b128 v[208:211], v158 offset:38912
	ds_read_b128 v[212:215], v158 offset:39936
	global_load_lds_dwordx4 v[220:221], off
	v_lshl_add_u64 v[220:221], s[0:1], 0, v[136:137]
	s_mov_b32 m0, s52
	s_nop 0
	global_load_lds_dwordx4 v[220:221], off
	s_waitcnt vmcnt(8)
	s_waitcnt lgkmcnt(0)
	s_barrier
	s_setprio 3
	s_waitcnt lgkmcnt(0)
	v_mfma_i32_16x16x64_i8 v[126:129], v[146:149], v[184:187], v[126:129]
	v_mfma_i32_16x16x64_i8 v[122:125], v[160:163], v[184:187], v[122:125]
	v_mfma_i32_16x16x64_i8 v[114:117], v[160:163], v[192:195], v[114:117]
	v_mfma_i32_16x16x64_i8 v[118:121], v[146:149], v[192:195], v[118:121]
	v_mfma_i32_16x16x64_i8 v[110:113], v[146:149], v[200:203], v[110:113]
	v_mfma_i32_16x16x64_i8 v[106:109], v[160:163], v[200:203], v[106:109]
	v_mfma_i32_16x16x64_i8 v[98:101], v[160:163], v[208:211], v[98:101]
	v_mfma_i32_16x16x64_i8 v[102:105], v[146:149], v[208:211], v[102:105]
	v_mfma_i32_16x16x64_i8 v[126:129], v[150:153], v[188:191], v[126:129]
	v_mfma_i32_16x16x64_i8 v[122:125], v[164:167], v[188:191], v[122:125]
	v_mfma_i32_16x16x64_i8 v[114:117], v[164:167], v[196:199], v[114:117]
	v_mfma_i32_16x16x64_i8 v[118:121], v[150:153], v[196:199], v[118:121]
	v_mfma_i32_16x16x64_i8 v[110:113], v[150:153], v[204:207], v[110:113]
	v_mfma_i32_16x16x64_i8 v[106:109], v[164:167], v[204:207], v[106:109]
	v_mfma_i32_16x16x64_i8 v[98:101], v[164:167], v[212:215], v[98:101]
	v_mfma_i32_16x16x64_i8 v[102:105], v[150:153], v[212:215], v[102:105]
	s_setprio 0
	s_setprio 3
	v_mfma_i32_16x16x64_i8 v[62:65], v[168:171], v[184:187], v[62:65]
	v_mfma_i32_16x16x64_i8 v[58:61], v[176:179], v[184:187], v[58:61]
	v_mfma_i32_16x16x64_i8 v[50:53], v[176:179], v[192:195], v[50:53]
	v_mfma_i32_16x16x64_i8 v[54:57], v[168:171], v[192:195], v[54:57]
	v_mfma_i32_16x16x64_i8 v[46:49], v[168:171], v[200:203], v[46:49]
	v_mfma_i32_16x16x64_i8 v[42:45], v[176:179], v[200:203], v[42:45]
	v_mfma_i32_16x16x64_i8 v[34:37], v[176:179], v[208:211], v[34:37]
	v_mfma_i32_16x16x64_i8 v[38:41], v[168:171], v[208:211], v[38:41]
	v_mfma_i32_16x16x64_i8 v[62:65], v[172:175], v[188:191], v[62:65]
	v_mfma_i32_16x16x64_i8 v[58:61], v[180:183], v[188:191], v[58:61]
	v_mfma_i32_16x16x64_i8 v[50:53], v[180:183], v[196:199], v[50:53]
	v_mfma_i32_16x16x64_i8 v[54:57], v[172:175], v[196:199], v[54:57]
	v_mfma_i32_16x16x64_i8 v[46:49], v[172:175], v[204:207], v[46:49]
	v_mfma_i32_16x16x64_i8 v[42:45], v[180:183], v[204:207], v[42:45]
	v_mfma_i32_16x16x64_i8 v[34:37], v[180:183], v[212:215], v[34:37]
	v_mfma_i32_16x16x64_i8 v[38:41], v[172:175], v[212:215], v[38:41]
	s_setprio 0
	s_barrier
	s_add_u32 s0, s44, 0x4000
	s_addc_u32 s1, s45, 0
	s_add_i32 s46, s71, s48
	v_lshl_add_u64 v[220:221], s[0:1], 0, v[130:131]
	s_mov_b32 m0, s46
	ds_read_b128 v[184:187], v158 offset:49152
	ds_read_b128 v[188:191], v158 offset:50176
	ds_read_b128 v[192:195], v158 offset:51200
	ds_read_b128 v[196:199], v158 offset:52224
	ds_read_b128 v[200:203], v158 offset:53248
	ds_read_b128 v[204:207], v158 offset:54272
	ds_read_b128 v[208:211], v158 offset:55296
	ds_read_b128 v[212:215], v158 offset:56320
	global_load_lds_dwordx4 v[220:221], off
	s_add_i32 m0, s46, 0x2000
	v_lshl_add_u64 v[220:221], s[0:1], 0, v[134:135]
	s_add_u32 s0, s44, 0x15c000
	s_addc_u32 s1, s45, 0
	s_add_i32 s44, s72, s48
	global_load_lds_dwordx4 v[220:221], off
	v_lshl_add_u64 v[220:221], s[0:1], 0, v[130:131]
	s_mov_b32 m0, s44
	v_lshl_add_u64 v[216:217], v[216:217], 0, s[18:19]
	global_load_lds_dwordx4 v[220:221], off
	v_lshl_add_u64 v[220:221], s[0:1], 0, v[134:135]
	s_add_i32 m0, s44, 0x2000
	s_nop 0
	global_load_lds_dwordx4 v[220:221], off
	s_mov_b32 m0, s54
	s_nop 0
	global_load_lds_dwordx4 v[216:217], off
	v_lshl_add_u64 v[216:217], v[218:219], 0, s[18:19]
	s_mov_b32 m0, s55
	s_nop 0
	global_load_lds_dwordx4 v[216:217], off
	s_waitcnt vmcnt(8)
	s_waitcnt lgkmcnt(0)
	s_barrier
	s_setprio 3
	s_waitcnt lgkmcnt(0)
	v_mfma_i32_16x16x64_i8 v[94:97], v[146:149], v[184:187], v[94:97]
	v_mfma_i32_16x16x64_i8 v[90:93], v[160:163], v[184:187], v[90:93]
	v_mfma_i32_16x16x64_i8 v[82:85], v[160:163], v[192:195], v[82:85]
	v_mfma_i32_16x16x64_i8 v[86:89], v[146:149], v[192:195], v[86:89]
	v_mfma_i32_16x16x64_i8 v[78:81], v[146:149], v[200:203], v[78:81]
	v_mfma_i32_16x16x64_i8 v[74:77], v[160:163], v[200:203], v[74:77]
	v_mfma_i32_16x16x64_i8 v[66:69], v[160:163], v[208:211], v[66:69]
	v_mfma_i32_16x16x64_i8 v[70:73], v[146:149], v[208:211], v[70:73]
	v_mfma_i32_16x16x64_i8 v[94:97], v[150:153], v[188:191], v[94:97]
	v_mfma_i32_16x16x64_i8 v[90:93], v[164:167], v[188:191], v[90:93]
	v_mfma_i32_16x16x64_i8 v[82:85], v[164:167], v[196:199], v[82:85]
	v_mfma_i32_16x16x64_i8 v[86:89], v[150:153], v[196:199], v[86:89]
	v_mfma_i32_16x16x64_i8 v[78:81], v[150:153], v[204:207], v[78:81]
	v_mfma_i32_16x16x64_i8 v[74:77], v[164:167], v[204:207], v[74:77]
	v_mfma_i32_16x16x64_i8 v[66:69], v[164:167], v[212:215], v[66:69]
	v_mfma_i32_16x16x64_i8 v[70:73], v[150:153], v[212:215], v[70:73]
	s_setprio 0
	s_setprio 3
	v_mfma_i32_16x16x64_i8 v[30:33], v[168:171], v[184:187], v[30:33]
	v_mfma_i32_16x16x64_i8 v[26:29], v[176:179], v[184:187], v[26:29]
	v_mfma_i32_16x16x64_i8 v[18:21], v[176:179], v[192:195], v[18:21]
	v_mfma_i32_16x16x64_i8 v[22:25], v[168:171], v[192:195], v[22:25]
	v_mfma_i32_16x16x64_i8 v[14:17], v[168:171], v[200:203], v[14:17]
	v_mfma_i32_16x16x64_i8 v[10:13], v[176:179], v[200:203], v[10:13]
	v_mfma_i32_16x16x64_i8 v[2:5], v[176:179], v[208:211], v[2:5]
	v_mfma_i32_16x16x64_i8 v[6:9], v[168:171], v[208:211], v[6:9]
	v_mfma_i32_16x16x64_i8 v[30:33], v[172:175], v[188:191], v[30:33]
	v_mfma_i32_16x16x64_i8 v[26:29], v[180:183], v[188:191], v[26:29]
	v_mfma_i32_16x16x64_i8 v[18:21], v[180:183], v[196:199], v[18:21]
	v_mfma_i32_16x16x64_i8 v[22:25], v[172:175], v[196:199], v[22:25]
	v_mfma_i32_16x16x64_i8 v[14:17], v[172:175], v[204:207], v[14:17]
	v_mfma_i32_16x16x64_i8 v[10:13], v[180:183], v[204:207], v[10:13]
	v_mfma_i32_16x16x64_i8 v[2:5], v[180:183], v[212:215], v[2:5]
	v_mfma_i32_16x16x64_i8 v[6:9], v[172:175], v[212:215], v[6:9]
	s_setprio 0
	s_barrier
	s_add_i32 s70, s70, 2
	s_add_u32 s68, s68, 0x8000
	s_addc_u32 s69, s69, 0
	s_cmpk_gt_u32 s70, 0x53
	s_mov_b64 s[0:1], s[42:43]
	s_cbranch_scc0 .LBB0_1600
	s_and_b64 vcc, exec, s[20:21]
	s_cbranch_vccz .LBB0_1603
	s_barrier
